# GEMM k-loops: ds_reads then LDS-DMA issue under s_setprio 2 after each barrier, prio 0 for MFMA ladder; plus attention VALU trims
# speedup vs baseline: 1.0516x; 1.0161x over previous
.LBB0_30:
	s_mul_i32 s44, s43, 0x6000
	s_add_i32 s45, s44, 0xffffa000
	s_cmp_gt_i32 s43, 0
	s_waitcnt vmcnt(6)
	s_cselect_b32 s45, s45, 0xc000
	s_waitcnt lgkmcnt(0)
	s_barrier
	s_setprio 2
	v_add3_u32 v0, s44, v177, v176
	v_add_u32_e32 v0, s55, v0
	ds_read_b128 v[180:183], v0
	ds_read_b128 v[184:187], v0 offset:1024
	ds_read_b128 v[188:191], v0 offset:2048
	ds_read_b128 v[192:195], v0 offset:3072
	v_add3_u32 v0, s44, v178, v176
	ds_read_b128 v[196:199], v0 offset:8192
	ds_read_b128 v[200:203], v0 offset:9216
	ds_read_b128 v[204:207], v0 offset:10240
	ds_read_b128 v[208:211], v0 offset:11264
	ds_read_b128 v[216:219], v0 offset:12288
	ds_read_b128 v[226:229], v0 offset:13312
	ds_read_b128 v[230:233], v0 offset:14336
	ds_read_b128 v[234:237], v0 offset:15360
	v_lshl_add_u64 v[212:213], v[174:175], 0, s[12:13]
	v_lshl_add_u64 v[212:213], v[162:163], 1, v[212:213]
	s_add_i32 s68, s45, s42
	s_mov_b32 m0, s68
	s_nop 0
	global_load_lds_dwordx4 v[212:213], off
	v_lshl_add_u64 v[212:213], v[174:175], 0, s[12:13]
	v_lshl_add_u64 v[212:213], v[164:165], 1, v[212:213]
	s_add_i32 s68, s45, s40
	s_mov_b32 m0, s68
	s_nop 0
	global_load_lds_dwordx4 v[212:213], off
	s_add_i32 s45, s41, s45
	v_lshl_add_u64 v[212:213], v[172:173], 0, s[12:13]
	s_mov_b32 m0, s45
	s_nop 0
	global_load_lds_dwordx4 v[212:213], off
	v_lshl_add_u64 v[212:213], v[170:171], 0, s[12:13]
	s_add_i32 s68, s45, 0x400
	s_mov_b32 m0, s68
	s_nop 0
	global_load_lds_dwordx4 v[212:213], off
	v_lshl_add_u64 v[212:213], v[168:169], 0, s[12:13]
	s_add_i32 s68, s45, 0x800
	s_mov_b32 m0, s68
	s_nop 0
	global_load_lds_dwordx4 v[212:213], off
	s_addk_i32 s45, 0xc00
	v_lshl_add_u64 v[212:213], v[166:167], 0, s[12:13]
	s_mov_b32 m0, s45
	s_nop 0
	global_load_lds_dwordx4 v[212:213], off
	s_setprio 0
	s_waitcnt lgkmcnt(7)
	v_mfma_f32_16x16x32_bf16 v[34:37], v[196:199], v[180:183], v[34:37]
	v_mfma_f32_16x16x32_bf16 v[38:41], v[196:199], v[184:187], v[38:41]
	v_mfma_f32_16x16x32_bf16 v[42:45], v[196:199], v[188:191], v[42:45]
	v_mfma_f32_16x16x32_bf16 v[46:49], v[196:199], v[192:195], v[46:49]
	s_waitcnt lgkmcnt(6)
	v_mfma_f32_16x16x32_bf16 v[50:53], v[200:203], v[180:183], v[50:53]
	v_mfma_f32_16x16x32_bf16 v[54:57], v[200:203], v[184:187], v[54:57]
	v_mfma_f32_16x16x32_bf16 v[58:61], v[200:203], v[188:191], v[58:61]
	v_mfma_f32_16x16x32_bf16 v[62:65], v[200:203], v[192:195], v[62:65]
	s_waitcnt lgkmcnt(5)
	v_mfma_f32_16x16x32_bf16 v[66:69], v[204:207], v[180:183], v[66:69]
	v_mfma_f32_16x16x32_bf16 v[70:73], v[204:207], v[184:187], v[70:73]
	v_mfma_f32_16x16x32_bf16 v[74:77], v[204:207], v[188:191], v[74:77]
	v_mfma_f32_16x16x32_bf16 v[78:81], v[204:207], v[192:195], v[78:81]
	s_waitcnt lgkmcnt(4)
	v_mfma_f32_16x16x32_bf16 v[82:85], v[208:211], v[180:183], v[82:85]
	v_mfma_f32_16x16x32_bf16 v[86:89], v[208:211], v[184:187], v[86:89]
	v_mfma_f32_16x16x32_bf16 v[90:93], v[208:211], v[188:191], v[90:93]
	v_mfma_f32_16x16x32_bf16 v[94:97], v[208:211], v[192:195], v[94:97]
	s_waitcnt lgkmcnt(3)
	v_mfma_f32_16x16x32_bf16 v[98:101], v[216:219], v[180:183], v[98:101]
	v_mfma_f32_16x16x32_bf16 v[102:105], v[216:219], v[184:187], v[102:105]
	v_mfma_f32_16x16x32_bf16 v[106:109], v[216:219], v[188:191], v[106:109]
	v_mfma_f32_16x16x32_bf16 v[110:113], v[216:219], v[192:195], v[110:113]
	s_waitcnt lgkmcnt(2)
	v_mfma_f32_16x16x32_bf16 v[114:117], v[226:229], v[180:183], v[114:117]
	v_mfma_f32_16x16x32_bf16 v[118:121], v[226:229], v[184:187], v[118:121]
	v_mfma_f32_16x16x32_bf16 v[122:125], v[226:229], v[188:191], v[122:125]
	v_mfma_f32_16x16x32_bf16 v[126:129], v[226:229], v[192:195], v[126:129]
	s_waitcnt lgkmcnt(1)
	v_mfma_f32_16x16x32_bf16 v[130:133], v[230:233], v[180:183], v[130:133]
	v_mfma_f32_16x16x32_bf16 v[134:137], v[230:233], v[184:187], v[134:137]
	v_mfma_f32_16x16x32_bf16 v[138:141], v[230:233], v[188:191], v[138:141]
	v_mfma_f32_16x16x32_bf16 v[142:145], v[230:233], v[192:195], v[142:145]
	s_waitcnt lgkmcnt(0)
	v_mfma_f32_16x16x32_bf16 v[146:149], v[234:237], v[180:183], v[146:149]
	v_mfma_f32_16x16x32_bf16 v[150:153], v[234:237], v[184:187], v[150:153]
	v_mfma_f32_16x16x32_bf16 v[154:157], v[234:237], v[188:191], v[154:157]
	v_mfma_f32_16x16x32_bf16 v[158:161], v[234:237], v[192:195], v[158:161]
	s_add_i32 s44, s43, 1
	s_cmp_lg_u32 s43, 2
	s_cselect_b32 s43, s44, 0
	s_add_u32 s12, s12, 64
	s_addc_u32 s13, s13, 0
	s_cmpk_eq_i32 s12, 0x780
	s_cbranch_scc0 .LBB0_30
	s_waitcnt vmcnt(6)
	v_mov_b32_e32 v162, v23
	v_mov_b32_e32 v163, v24
	v_mov_b32_e32 v23, v25
	v_mov_b32_e32 v164, v7
	v_mov_b32_e32 v165, v8
	v_pk_add_f32 v[22:23], v[162:163], v[22:23]
	v_mov_b32_e32 v7, v9
	v_pk_add_f32 v[6:7], v[164:165], v[6:7]
	v_add_f32_e32 v0, v22, v23
	v_add_f32_e32 v0, v0, v6
	v_add_f32_e32 v0, v0, v7
	v_fmamk_f32 v0, v0, 0x3a800000, v250
	s_mov_b32 s12, 0x800000
	s_waitcnt vmcnt(4)
	v_mov_b32_e32 v166, v19
	v_mov_b32_e32 v167, v20
	v_mov_b32_e32 v168, v3
	v_mul_f32_e32 v3, 0x4b800000, v0
	v_cmp_gt_f32_e32 vcc, s12, v0
	v_mov_b32_e32 v19, v21
	v_mov_b32_e32 v169, v4
	v_cndmask_b32_e32 v0, v0, v3, vcc
	v_pk_add_f32 v[6:7], v[166:167], v[18:19]
	v_mov_b32_e32 v3, v5
	v_pk_add_f32 v[2:3], v[168:169], v[2:3]
	v_add_f32_e32 v4, v6, v7
	v_add_f32_e32 v2, v4, v2
	v_add_f32_e32 v2, v2, v3
	v_fmamk_f32 v2, v2, 0x3a800000, v250
	v_mul_f32_e32 v3, 0x4b800000, v2
	v_cmp_gt_f32_e64 s[40:41], s12, v2
	s_waitcnt vmcnt(2)
	v_mov_b32_e32 v170, v27
	v_mov_b32_e32 v171, v28
	v_cndmask_b32_e64 v2, v2, v3, s[40:41]
	v_mov_b32_e32 v27, v29
	v_mov_b32_e32 v172, v11
	v_mov_b32_e32 v173, v12
	v_rsq_f32_e32 v179, v2
	v_pk_add_f32 v[2:3], v[170:171], v[26:27]
	v_mov_b32_e32 v11, v13
	v_pk_add_f32 v[4:5], v[172:173], v[10:11]
	v_add_f32_e32 v2, v2, v3
	v_add_f32_e32 v2, v2, v4
	v_add_f32_e32 v2, v2, v5
	v_fmamk_f32 v2, v2, 0x3a800000, v250
	v_mul_f32_e32 v3, 0x4b800000, v2
	v_cmp_gt_f32_e64 s[42:43], s12, v2
	s_waitcnt vmcnt(0)
	v_mov_b32_e32 v174, v31
	v_mov_b32_e32 v175, v32
	v_cndmask_b32_e64 v2, v2, v3, s[42:43]
	v_mov_b32_e32 v31, v33
	v_mov_b32_e32 v180, v15
	v_mov_b32_e32 v181, v16
	v_rsq_f32_e32 v182, v2
	v_pk_add_f32 v[2:3], v[174:175], v[30:31]
	v_mov_b32_e32 v15, v17
	v_pk_add_f32 v[4:5], v[180:181], v[14:15]
	v_add_f32_e32 v2, v2, v3
	v_add_f32_e32 v2, v2, v4
	v_add_f32_e32 v2, v2, v5
	v_fmamk_f32 v2, v2, 0x3a800000, v250
	v_mul_f32_e32 v3, 0x4b800000, v2
	v_cmp_gt_f32_e64 s[44:45], s12, v2
	s_waitcnt vmcnt(6)
	v_add_u32_e32 v183, v178, v176
	s_waitcnt lgkmcnt(0)
	s_barrier
	v_cndmask_b32_e64 v2, v2, v3, s[44:45]
	v_rsq_f32_e32 v180, v2
	ds_read_b128 v[2:5], v183 offset:15360
	ds_read_b128 v[6:9], v183 offset:14336
	ds_read_b128 v[10:13], v183 offset:13312
	ds_read_b128 v[14:17], v183 offset:12288
	ds_read_b128 v[18:21], v183 offset:11264
	ds_read_b128 v[22:25], v183 offset:10240
	ds_read_b128 v[26:29], v183 offset:9216
	ds_read_b128 v[30:33], v183 offset:8192
	v_add3_u32 v178, s55, v177, v176
	ds_read_b128 v[162:165], v178 offset:3072
	ds_read_b128 v[166:169], v178 offset:2048
	ds_read_b128 v[170:173], v178 offset:1024
	ds_read_b128 v[174:177], v178
	v_rsq_f32_e32 v0, v0
	v_mul_f32_e32 v184, 0x45800000, v179
	v_mul_f32_e32 v185, 0x45800000, v182
	v_mul_f32_e32 v186, 0x45800000, v180
	v_mul_f32_e32 v181, 0x45800000, v0
	s_waitcnt lgkmcnt(0)
	v_mfma_f32_16x16x32_bf16 v[34:37], v[30:33], v[174:177], v[34:37]
	v_mfma_f32_16x16x32_bf16 v[38:41], v[30:33], v[170:173], v[38:41]
	v_mfma_f32_16x16x32_bf16 v[42:45], v[30:33], v[166:169], v[42:45]
	v_mfma_f32_16x16x32_bf16 v[30:33], v[30:33], v[162:165], v[46:49]
	v_mfma_f32_16x16x32_bf16 v[46:49], v[26:29], v[174:177], v[50:53]
	v_mfma_f32_16x16x32_bf16 v[50:53], v[26:29], v[170:173], v[54:57]
	v_mfma_f32_16x16x32_bf16 v[54:57], v[26:29], v[166:169], v[58:61]
	v_mfma_f32_16x16x32_bf16 v[58:61], v[26:29], v[162:165], v[62:65]
	v_mfma_f32_16x16x32_bf16 v[62:65], v[22:25], v[174:177], v[66:69]
	v_mfma_f32_16x16x32_bf16 v[66:69], v[22:25], v[170:173], v[70:73]
	v_mfma_f32_16x16x32_bf16 v[70:73], v[22:25], v[166:169], v[74:77]
	v_mfma_f32_16x16x32_bf16 v[74:77], v[22:25], v[162:165], v[78:81]
	v_mfma_f32_16x16x32_bf16 v[78:81], v[18:21], v[174:177], v[82:85]
	v_mfma_f32_16x16x32_bf16 v[82:85], v[18:21], v[170:173], v[86:89]
	v_mfma_f32_16x16x32_bf16 v[86:89], v[18:21], v[166:169], v[90:93]
	v_mfma_f32_16x16x32_bf16 v[18:21], v[18:21], v[162:165], v[94:97]
	v_mfma_f32_16x16x32_bf16 v[90:93], v[14:17], v[174:177], v[98:101]
	v_mfma_f32_16x16x32_bf16 v[94:97], v[14:17], v[170:173], v[102:105]
	v_mfma_f32_16x16x32_bf16 v[98:101], v[14:17], v[166:169], v[106:109]
	v_mfma_f32_16x16x32_bf16 v[14:17], v[14:17], v[162:165], v[110:113]
	v_mfma_f32_16x16x32_bf16 v[102:105], v[10:13], v[174:177], v[114:117]
	v_mfma_f32_16x16x32_bf16 v[106:109], v[10:13], v[170:173], v[118:121]
	v_mfma_f32_16x16x32_bf16 v[110:113], v[10:13], v[166:169], v[122:125]
	v_mfma_f32_16x16x32_bf16 v[10:13], v[10:13], v[162:165], v[126:129]
	v_mfma_f32_16x16x32_bf16 v[114:117], v[6:9], v[174:177], v[130:133]
	v_mfma_f32_16x16x32_bf16 v[118:121], v[6:9], v[170:173], v[134:137]
	v_mfma_f32_16x16x32_bf16 v[122:125], v[6:9], v[166:169], v[138:141]
	v_mfma_f32_16x16x32_bf16 v[6:9], v[6:9], v[162:165], v[142:145]
	v_mfma_f32_16x16x32_bf16 v[126:129], v[2:5], v[174:177], v[146:149]
	v_mfma_f32_16x16x32_bf16 v[130:133], v[2:5], v[170:173], v[150:153]
	v_mfma_f32_16x16x32_bf16 v[134:137], v[2:5], v[166:169], v[154:157]
	v_mfma_f32_16x16x32_bf16 v[2:5], v[2:5], v[162:165], v[158:161]
	s_waitcnt vmcnt(0)
	v_cndmask_b32_e32 v26, v0, v181, vcc
	v_cndmask_b32_e64 v24, v179, v184, s[40:41]
	v_cndmask_b32_e64 v22, v182, v185, s[42:43]
	v_cndmask_b32_e64 v0, v180, v186, s[44:45]
	s_waitcnt lgkmcnt(0)
	s_barrier
	ds_read_b128 v[138:141], v178 offset:24576
	ds_read_b128 v[142:145], v178 offset:25600
	ds_read_b128 v[146:149], v178 offset:26624
	ds_read_b128 v[150:153], v178 offset:27648
	ds_read_b128 v[154:157], v183 offset:32768
	ds_read_b128 v[158:161], v183 offset:33792
	ds_read_b128 v[162:165], v183 offset:34816
	ds_read_b128 v[166:169], v183 offset:35840
	ds_read_b128 v[170:173], v183 offset:36864
	ds_read_b128 v[174:177], v183 offset:37888
	ds_read_b128 v[178:181], v183 offset:38912
	ds_read_b128 v[182:185], v183 offset:39936
	s_waitcnt lgkmcnt(7)
	v_mfma_f32_16x16x32_bf16 v[34:37], v[154:157], v[138:141], v[34:37]
	v_mfma_f32_16x16x32_bf16 v[38:41], v[154:157], v[142:145], v[38:41]
	v_mfma_f32_16x16x32_bf16 v[42:45], v[154:157], v[146:149], v[42:45]
	v_mfma_f32_16x16x32_bf16 v[28:31], v[154:157], v[150:153], v[30:33]
	s_waitcnt lgkmcnt(6)
	v_mfma_f32_16x16x32_bf16 v[46:49], v[158:161], v[138:141], v[46:49]
	v_mfma_f32_16x16x32_bf16 v[50:53], v[158:161], v[142:145], v[50:53]
	v_mfma_f32_16x16x32_bf16 v[54:57], v[158:161], v[146:149], v[54:57]
	v_mfma_f32_16x16x32_bf16 v[58:61], v[158:161], v[150:153], v[58:61]
	s_waitcnt lgkmcnt(5)
	v_mfma_f32_16x16x32_bf16 v[62:65], v[162:165], v[138:141], v[62:65]
	v_mfma_f32_16x16x32_bf16 v[66:69], v[162:165], v[142:145], v[66:69]
	v_mfma_f32_16x16x32_bf16 v[70:73], v[162:165], v[146:149], v[70:73]
	v_mfma_f32_16x16x32_bf16 v[74:77], v[162:165], v[150:153], v[74:77]
	s_waitcnt lgkmcnt(4)
	v_mfma_f32_16x16x32_bf16 v[78:81], v[166:169], v[138:141], v[78:81]
	v_mfma_f32_16x16x32_bf16 v[82:85], v[166:169], v[142:145], v[82:85]
	v_mfma_f32_16x16x32_bf16 v[86:89], v[166:169], v[146:149], v[86:89]
	v_mfma_f32_16x16x32_bf16 v[154:157], v[166:169], v[150:153], v[18:21]
	s_waitcnt lgkmcnt(3)
	v_mfma_f32_16x16x32_bf16 v[90:93], v[170:173], v[138:141], v[90:93]
	v_mfma_f32_16x16x32_bf16 v[94:97], v[170:173], v[142:145], v[94:97]
	v_mfma_f32_16x16x32_bf16 v[98:101], v[170:173], v[146:149], v[98:101]
	v_mfma_f32_16x16x32_bf16 v[158:161], v[170:173], v[150:153], v[14:17]
	s_waitcnt lgkmcnt(2)
	v_mfma_f32_16x16x32_bf16 v[102:105], v[174:177], v[138:141], v[102:105]
	v_mfma_f32_16x16x32_bf16 v[106:109], v[174:177], v[142:145], v[106:109]
	v_mfma_f32_16x16x32_bf16 v[110:113], v[174:177], v[146:149], v[110:113]
	v_mfma_f32_16x16x32_bf16 v[162:165], v[174:177], v[150:153], v[10:13]
	s_waitcnt lgkmcnt(1)
	v_mfma_f32_16x16x32_bf16 v[114:117], v[178:181], v[138:141], v[114:117]
	v_mfma_f32_16x16x32_bf16 v[118:121], v[178:181], v[142:145], v[118:121]
	v_mfma_f32_16x16x32_bf16 v[122:125], v[178:181], v[146:149], v[122:125]
	v_mfma_f32_16x16x32_bf16 v[18:21], v[178:181], v[150:153], v[6:9]
	s_waitcnt lgkmcnt(0)
	v_mfma_f32_16x16x32_bf16 v[14:17], v[182:185], v[138:141], v[126:129]
	v_mfma_f32_16x16x32_bf16 v[10:13], v[182:185], v[142:145], v[130:133]
	v_mfma_f32_16x16x32_bf16 v[6:9], v[182:185], v[146:149], v[134:137]
	v_mfma_f32_16x16x32_bf16 v[2:5], v[182:185], v[150:153], v[2:5]
	v_mov_b32_e32 v23, v224
	s_movk_i32 s12, 0x210
	v_lshrrev_b32_e32 v32, 1, v23
	v_and_b32_e32 v27, 0x7fffff80, v23
	v_and_b32_e32 v32, 24, v32
	v_and_b32_e32 v25, 0x4f, v23
	v_lshl_or_b32 v27, v27, 1, v32
	v_pk_mul_f32 v[32:33], v[26:27], v[34:35] op_sel_hi:[0,1]
	v_pk_mul_f32 v[34:35], v[26:27], v[36:37] op_sel_hi:[0,1]
	v_mad_u32_u24 v25, v25, s12, v27
	v_cvt_pk_bf16_f32 v32, v32, v33
	v_cvt_pk_bf16_f32 v33, v34, v35
	v_pk_mul_f32 v[34:35], v[24:25], v[38:39] op_sel_hi:[0,1]
	v_pk_mul_f32 v[36:37], v[24:25], v[40:41] op_sel_hi:[0,1]
	v_cvt_pk_bf16_f32 v34, v34, v35
	v_cvt_pk_bf16_f32 v35, v36, v37
	v_pk_mul_f32 v[36:37], v[22:23], v[42:43] op_sel_hi:[0,1]
	v_pk_mul_f32 v[38:39], v[22:23], v[44:45] op_sel_hi:[0,1]
	v_pk_mul_f32 v[28:29], v[0:1], v[28:29] op_sel_hi:[0,1]
	v_pk_mul_f32 v[30:31], v[0:1], v[30:31] op_sel_hi:[0,1]
	v_cvt_pk_bf16_f32 v36, v36, v37
	v_cvt_pk_bf16_f32 v37, v38, v39
	v_cvt_pk_bf16_f32 v28, v28, v29
	v_cvt_pk_bf16_f32 v29, v30, v31
	v_pk_mul_f32 v[30:31], v[26:27], v[46:47] op_sel_hi:[0,1]
	v_pk_mul_f32 v[38:39], v[26:27], v[48:49] op_sel_hi:[0,1]
	v_cvt_pk_bf16_f32 v30, v30, v31
	v_cvt_pk_bf16_f32 v31, v38, v39
	s_barrier
	ds_write2_b64 v25, v[32:33], v[30:31] offset1:4
	v_pk_mul_f32 v[30:31], v[24:25], v[50:51] op_sel_hi:[0,1]
	v_pk_mul_f32 v[32:33], v[24:25], v[52:53] op_sel_hi:[0,1]
	v_cvt_pk_bf16_f32 v30, v30, v31
	v_cvt_pk_bf16_f32 v31, v32, v33
	v_add_u32_e32 v27, 0x2000, v25
	ds_write2_b64 v27, v[34:35], v[30:31] offset0:32 offset1:36
	v_pk_mul_f32 v[30:31], v[22:23], v[54:55] op_sel_hi:[0,1]
	v_pk_mul_f32 v[32:33], v[22:23], v[56:57] op_sel_hi:[0,1]
	v_cvt_pk_bf16_f32 v30, v30, v31
	v_cvt_pk_bf16_f32 v31, v32, v33
	v_add_u32_e32 v40, 0x4000, v25
	ds_write2_b64 v40, v[36:37], v[30:31] offset0:64 offset1:68
	v_pk_mul_f32 v[30:31], v[0:1], v[58:59] op_sel_hi:[0,1]
	v_pk_mul_f32 v[32:33], v[0:1], v[60:61] op_sel_hi:[0,1]
	v_cvt_pk_bf16_f32 v30, v30, v31
	v_cvt_pk_bf16_f32 v31, v32, v33
	v_add_u32_e32 v41, 0x6000, v25
	ds_write2_b64 v41, v[28:29], v[30:31] offset0:96 offset1:100
	v_pk_mul_f32 v[28:29], v[26:27], v[62:63] op_sel_hi:[0,1]
	v_pk_mul_f32 v[30:31], v[26:27], v[64:65] op_sel_hi:[0,1]
	v_cvt_pk_bf16_f32 v28, v28, v29
	v_cvt_pk_bf16_f32 v29, v30, v31
	v_pk_mul_f32 v[30:31], v[24:25], v[66:67] op_sel_hi:[0,1]
	v_pk_mul_f32 v[32:33], v[24:25], v[68:69] op_sel_hi:[0,1]
	v_cvt_pk_bf16_f32 v30, v30, v31
	v_cvt_pk_bf16_f32 v31, v32, v33
	v_pk_mul_f32 v[32:33], v[22:23], v[70:71] op_sel_hi:[0,1]
	v_pk_mul_f32 v[34:35], v[22:23], v[72:73] op_sel_hi:[0,1]
	v_cvt_pk_bf16_f32 v32, v32, v33
	v_cvt_pk_bf16_f32 v33, v34, v35
	v_pk_mul_f32 v[34:35], v[0:1], v[74:75] op_sel_hi:[0,1]
	v_pk_mul_f32 v[36:37], v[0:1], v[76:77] op_sel_hi:[0,1]
	v_cvt_pk_bf16_f32 v34, v34, v35
	v_cvt_pk_bf16_f32 v35, v36, v37
	v_pk_mul_f32 v[36:37], v[26:27], v[78:79] op_sel_hi:[0,1]
	v_pk_mul_f32 v[38:39], v[26:27], v[80:81] op_sel_hi:[0,1]
	v_cvt_pk_bf16_f32 v36, v36, v37
	v_cvt_pk_bf16_f32 v37, v38, v39
	ds_write2_b64 v25, v[28:29], v[36:37] offset0:8 offset1:12
	v_pk_mul_f32 v[28:29], v[24:25], v[82:83] op_sel_hi:[0,1]
	v_pk_mul_f32 v[36:37], v[24:25], v[84:85] op_sel_hi:[0,1]
	v_cvt_pk_bf16_f32 v28, v28, v29
	v_cvt_pk_bf16_f32 v29, v36, v37
	ds_write2_b64 v27, v[30:31], v[28:29] offset0:40 offset1:44
	v_pk_mul_f32 v[28:29], v[22:23], v[86:87] op_sel_hi:[0,1]
	v_pk_mul_f32 v[30:31], v[22:23], v[88:89] op_sel_hi:[0,1]
	v_cvt_pk_bf16_f32 v28, v28, v29
	v_cvt_pk_bf16_f32 v29, v30, v31
	ds_write2_b64 v40, v[32:33], v[28:29] offset0:72 offset1:76
	v_pk_mul_f32 v[28:29], v[0:1], v[154:155] op_sel_hi:[0,1]
	v_pk_mul_f32 v[30:31], v[0:1], v[156:157] op_sel_hi:[0,1]
	v_cvt_pk_bf16_f32 v28, v28, v29
	v_cvt_pk_bf16_f32 v29, v30, v31
	ds_write2_b64 v41, v[34:35], v[28:29] offset0:104 offset1:108
	v_pk_mul_f32 v[28:29], v[26:27], v[90:91] op_sel_hi:[0,1]
	v_pk_mul_f32 v[30:31], v[26:27], v[92:93] op_sel_hi:[0,1]
	v_cvt_pk_bf16_f32 v28, v28, v29
	v_cvt_pk_bf16_f32 v29, v30, v31
	v_pk_mul_f32 v[30:31], v[24:25], v[94:95] op_sel_hi:[0,1]
	v_pk_mul_f32 v[32:33], v[24:25], v[96:97] op_sel_hi:[0,1]
	v_cvt_pk_bf16_f32 v30, v30, v31
	v_cvt_pk_bf16_f32 v31, v32, v33
	v_pk_mul_f32 v[32:33], v[22:23], v[98:99] op_sel_hi:[0,1]
	v_pk_mul_f32 v[34:35], v[22:23], v[100:101] op_sel_hi:[0,1]
	v_cvt_pk_bf16_f32 v32, v32, v33
	v_cvt_pk_bf16_f32 v33, v34, v35
	v_pk_mul_f32 v[34:35], v[0:1], v[158:159] op_sel_hi:[0,1]
	v_pk_mul_f32 v[36:37], v[0:1], v[160:161] op_sel_hi:[0,1]
	v_cvt_pk_bf16_f32 v34, v34, v35
	v_cvt_pk_bf16_f32 v35, v36, v37
	v_pk_mul_f32 v[36:37], v[26:27], v[102:103] op_sel_hi:[0,1]
	v_pk_mul_f32 v[38:39], v[26:27], v[104:105] op_sel_hi:[0,1]
	v_cvt_pk_bf16_f32 v36, v36, v37
	v_cvt_pk_bf16_f32 v37, v38, v39
	ds_write2_b64 v25, v[28:29], v[36:37] offset0:16 offset1:20
	v_pk_mul_f32 v[28:29], v[24:25], v[106:107] op_sel_hi:[0,1]
	v_pk_mul_f32 v[36:37], v[24:25], v[108:109] op_sel_hi:[0,1]
	v_cvt_pk_bf16_f32 v28, v28, v29
	v_cvt_pk_bf16_f32 v29, v36, v37
	ds_write2_b64 v27, v[30:31], v[28:29] offset0:48 offset1:52
	v_pk_mul_f32 v[28:29], v[22:23], v[110:111] op_sel_hi:[0,1]
	v_pk_mul_f32 v[30:31], v[22:23], v[112:113] op_sel_hi:[0,1]
	v_cvt_pk_bf16_f32 v28, v28, v29
	v_cvt_pk_bf16_f32 v29, v30, v31
	ds_write2_b64 v40, v[32:33], v[28:29] offset0:80 offset1:84
	v_pk_mul_f32 v[28:29], v[0:1], v[162:163] op_sel_hi:[0,1]
	v_pk_mul_f32 v[30:31], v[0:1], v[164:165] op_sel_hi:[0,1]
	v_cvt_pk_bf16_f32 v28, v28, v29
	v_cvt_pk_bf16_f32 v29, v30, v31
	ds_write2_b64 v41, v[34:35], v[28:29] offset0:112 offset1:116
	v_pk_mul_f32 v[28:29], v[26:27], v[114:115] op_sel_hi:[0,1]
	v_pk_mul_f32 v[30:31], v[26:27], v[116:117] op_sel_hi:[0,1]
	v_pk_mul_f32 v[18:19], v[0:1], v[18:19] op_sel_hi:[0,1]
	v_pk_mul_f32 v[20:21], v[0:1], v[20:21] op_sel_hi:[0,1]
	v_pk_mul_f32 v[2:3], v[0:1], v[2:3] op_sel_hi:[0,1]
	v_pk_mul_f32 v[4:5], v[0:1], v[4:5] op_sel_hi:[0,1]
	v_lshlrev_b32_e32 v0, 3, v23
	v_cvt_pk_bf16_f32 v28, v28, v29
	v_cvt_pk_bf16_f32 v29, v30, v31
	v_pk_mul_f32 v[30:31], v[24:25], v[118:119] op_sel_hi:[0,1]
	v_pk_mul_f32 v[32:33], v[24:25], v[120:121] op_sel_hi:[0,1]
	v_cvt_pk_bf16_f32 v18, v18, v19
	v_cvt_pk_bf16_f32 v19, v20, v21
	v_cvt_pk_bf16_f32 v2, v2, v3
	v_cvt_pk_bf16_f32 v3, v4, v5
	v_and_b32_e32 v0, 0xf8, v0
	v_cvt_pk_bf16_f32 v30, v30, v31
	v_cvt_pk_bf16_f32 v31, v32, v33
	v_pk_mul_f32 v[32:33], v[22:23], v[122:123] op_sel_hi:[0,1]
	v_pk_mul_f32 v[34:35], v[22:23], v[124:125] op_sel_hi:[0,1]
	v_pk_mul_f32 v[14:15], v[26:27], v[14:15] op_sel_hi:[0,1]
	v_pk_mul_f32 v[16:17], v[26:27], v[16:17] op_sel_hi:[0,1]
	v_pk_mul_f32 v[10:11], v[24:25], v[10:11] op_sel_hi:[0,1]
	v_pk_mul_f32 v[12:13], v[24:25], v[12:13] op_sel_hi:[0,1]
	v_pk_mul_f32 v[6:7], v[22:23], v[6:7] op_sel_hi:[0,1]
	v_pk_mul_f32 v[8:9], v[22:23], v[8:9] op_sel_hi:[0,1]
	ds_write2_b64 v41, v[18:19], v[2:3] offset0:120 offset1:124
	v_or_b32_e32 v2, s54, v0
	s_movk_i32 s12, 0x400
	v_cvt_pk_bf16_f32 v32, v32, v33
	v_cvt_pk_bf16_f32 v33, v34, v35
	v_cvt_pk_bf16_f32 v14, v14, v15
	v_cvt_pk_bf16_f32 v15, v16, v17
	v_cvt_pk_bf16_f32 v10, v10, v11
	v_cvt_pk_bf16_f32 v11, v12, v13
	v_cvt_pk_bf16_f32 v6, v6, v7
	v_cvt_pk_bf16_f32 v7, v8, v9
	v_cmp_gt_i32_e32 vcc, s12, v2
	ds_write2_b64 v25, v[28:29], v[14:15] offset0:24 offset1:28
	ds_write2_b64 v27, v[30:31], v[10:11] offset0:56 offset1:60
	ds_write2_b64 v40, v[32:33], v[6:7] offset0:88 offset1:92
	s_waitcnt lgkmcnt(0)
	s_barrier
	s_and_saveexec_b64 s[12:13], vcc
	s_cbranch_execz .LBB0_28
	v_ashrrev_i32_e32 v8, 5, v23
	v_lshlrev_b32_e32 v0, 1, v0
	s_movk_i32 s40, 0x210
	v_mad_u64_u32 v[6:7], s[40:41], v8, s40, v[0:1]
	v_add_u32_e32 v8, s57, v8
	ds_read_b128 v[2:5], v6
	v_ashrrev_i32_e32 v9, 31, v8
	s_ashr_i32 s55, s54, 31
	v_lshlrev_b64 v[10:11], 11, v[8:9]
	v_lshl_add_u64 v[10:11], s[4:5], 0, v[10:11]
	s_lshl_b64 s[40:41], s[54:55], 1
	v_lshl_add_u64 v[10:11], v[10:11], 0, s[40:41]
	v_lshl_add_u64 v[10:11], v[10:11], 0, v[0:1]
	s_waitcnt lgkmcnt(0)
	global_store_dwordx4 v[10:11], v[2:5], off
	v_add_u32_e32 v10, 8, v8
	ds_read_b128 v[2:5], v6 offset:4224
	v_ashrrev_i32_e32 v11, 31, v10
	v_lshlrev_b64 v[10:11], 11, v[10:11]
	v_lshl_add_u64 v[10:11], s[4:5], 0, v[10:11]
	v_lshl_add_u64 v[10:11], v[10:11], 0, s[40:41]
	v_lshl_add_u64 v[10:11], v[10:11], 0, v[0:1]
	s_waitcnt lgkmcnt(0)
	global_store_dwordx4 v[10:11], v[2:5], off
	v_add_u32_e32 v10, 16, v8
	ds_read_b128 v[2:5], v6 offset:8448
	v_ashrrev_i32_e32 v11, 31, v10
	v_lshlrev_b64 v[10:11], 11, v[10:11]
	v_lshl_add_u64 v[10:11], s[4:5], 0, v[10:11]
	v_lshl_add_u64 v[10:11], v[10:11], 0, s[40:41]
	v_lshl_add_u64 v[10:11], v[10:11], 0, v[0:1]
	s_waitcnt lgkmcnt(0)
	global_store_dwordx4 v[10:11], v[2:5], off
	v_add_u32_e32 v10, 24, v8
	ds_read_b128 v[2:5], v6 offset:12672
	v_ashrrev_i32_e32 v11, 31, v10
	v_lshlrev_b64 v[10:11], 11, v[10:11]
	v_lshl_add_u64 v[10:11], s[4:5], 0, v[10:11]
	v_lshl_add_u64 v[10:11], v[10:11], 0, s[40:41]
	v_lshl_add_u64 v[10:11], v[10:11], 0, v[0:1]
	s_waitcnt lgkmcnt(0)
	global_store_dwordx4 v[10:11], v[2:5], off
	v_add_u32_e32 v10, 32, v8
	ds_read_b128 v[2:5], v6 offset:16896
	v_ashrrev_i32_e32 v11, 31, v10
	v_lshlrev_b64 v[10:11], 11, v[10:11]
	v_lshl_add_u64 v[10:11], s[4:5], 0, v[10:11]
	v_lshl_add_u64 v[10:11], v[10:11], 0, s[40:41]
	v_lshl_add_u64 v[10:11], v[10:11], 0, v[0:1]
	s_waitcnt lgkmcnt(0)
	global_store_dwordx4 v[10:11], v[2:5], off
	v_add_u32_e32 v10, 40, v8
	ds_read_b128 v[2:5], v6 offset:21120
	v_ashrrev_i32_e32 v11, 31, v10
	v_lshlrev_b64 v[10:11], 11, v[10:11]
	v_lshl_add_u64 v[10:11], s[4:5], 0, v[10:11]
	v_lshl_add_u64 v[10:11], v[10:11], 0, s[40:41]
	v_lshl_add_u64 v[10:11], v[10:11], 0, v[0:1]
	s_waitcnt lgkmcnt(0)
	global_store_dwordx4 v[10:11], v[2:5], off
	v_add_u32_e32 v10, 48, v8
	ds_read_b128 v[2:5], v6 offset:25344
	v_ashrrev_i32_e32 v11, 31, v10
	v_lshlrev_b64 v[10:11], 11, v[10:11]
	v_lshl_add_u64 v[10:11], s[4:5], 0, v[10:11]
	v_lshl_add_u64 v[10:11], v[10:11], 0, s[40:41]
	v_lshl_add_u64 v[10:11], v[10:11], 0, v[0:1]
	s_waitcnt lgkmcnt(0)
	global_store_dwordx4 v[10:11], v[2:5], off
	v_add_u32_e32 v10, 56, v8
	ds_read_b128 v[2:5], v6 offset:29568
	v_ashrrev_i32_e32 v11, 31, v10
	v_lshlrev_b64 v[10:11], 11, v[10:11]
	v_lshl_add_u64 v[10:11], s[4:5], 0, v[10:11]
	v_lshl_add_u64 v[10:11], v[10:11], 0, s[40:41]
	v_lshl_add_u64 v[10:11], v[10:11], 0, v[0:1]
	s_waitcnt lgkmcnt(0)
	global_store_dwordx4 v[10:11], v[2:5], off
	v_add_u32_e32 v10, 64, v8
	ds_read_b128 v[2:5], v6 offset:33792
	v_ashrrev_i32_e32 v11, 31, v10
	v_lshlrev_b64 v[10:11], 11, v[10:11]
	v_lshl_add_u64 v[10:11], s[4:5], 0, v[10:11]
	v_lshl_add_u64 v[10:11], v[10:11], 0, s[40:41]
	v_lshl_add_u64 v[10:11], v[10:11], 0, v[0:1]
	s_waitcnt lgkmcnt(0)
	global_store_dwordx4 v[10:11], v[2:5], off
	v_add_u32_e32 v10, 0x48, v8
	ds_read_b128 v[2:5], v6 offset:38016
	v_ashrrev_i32_e32 v11, 31, v10
	v_lshlrev_b64 v[10:11], 11, v[10:11]
	v_lshl_add_u64 v[10:11], s[4:5], 0, v[10:11]
	v_lshl_add_u64 v[10:11], v[10:11], 0, s[40:41]
	v_lshl_add_u64 v[10:11], v[10:11], 0, v[0:1]
	s_waitcnt lgkmcnt(0)
	global_store_dwordx4 v[10:11], v[2:5], off
	v_add_u32_e32 v10, 0x50, v8
	ds_read_b128 v[2:5], v6 offset:42240
	v_ashrrev_i32_e32 v11, 31, v10
	v_lshlrev_b64 v[10:11], 11, v[10:11]
	v_lshl_add_u64 v[10:11], s[4:5], 0, v[10:11]
	v_lshl_add_u64 v[10:11], v[10:11], 0, s[40:41]
	v_lshl_add_u64 v[10:11], v[10:11], 0, v[0:1]
	s_waitcnt lgkmcnt(0)
	global_store_dwordx4 v[10:11], v[2:5], off
	v_add_u32_e32 v10, 0x58, v8
	ds_read_b128 v[2:5], v6 offset:46464
	v_ashrrev_i32_e32 v11, 31, v10
	v_lshlrev_b64 v[10:11], 11, v[10:11]
	v_lshl_add_u64 v[10:11], s[4:5], 0, v[10:11]
	v_lshl_add_u64 v[10:11], v[10:11], 0, s[40:41]
	v_lshl_add_u64 v[10:11], v[10:11], 0, v[0:1]
	s_waitcnt lgkmcnt(0)
	global_store_dwordx4 v[10:11], v[2:5], off
	v_add_u32_e32 v10, 0x60, v8
	ds_read_b128 v[2:5], v6 offset:50688
	v_ashrrev_i32_e32 v11, 31, v10
	v_lshlrev_b64 v[10:11], 11, v[10:11]
	v_lshl_add_u64 v[10:11], s[4:5], 0, v[10:11]
	v_lshl_add_u64 v[10:11], v[10:11], 0, s[40:41]
	v_lshl_add_u64 v[10:11], v[10:11], 0, v[0:1]
	s_waitcnt lgkmcnt(0)
	global_store_dwordx4 v[10:11], v[2:5], off
	v_add_u32_e32 v10, 0x68, v8
	ds_read_b128 v[2:5], v6 offset:54912
	v_ashrrev_i32_e32 v11, 31, v10
	v_lshlrev_b64 v[10:11], 11, v[10:11]
	v_lshl_add_u64 v[10:11], s[4:5], 0, v[10:11]
	v_lshl_add_u64 v[10:11], v[10:11], 0, s[40:41]
	v_lshl_add_u64 v[10:11], v[10:11], 0, v[0:1]
	s_waitcnt lgkmcnt(0)
	global_store_dwordx4 v[10:11], v[2:5], off
	v_add_u32_e32 v10, 0x70, v8
	ds_read_b128 v[2:5], v6 offset:59136
	v_ashrrev_i32_e32 v11, 31, v10
	v_lshlrev_b64 v[10:11], 11, v[10:11]
	v_lshl_add_u64 v[10:11], s[4:5], 0, v[10:11]
	v_lshl_add_u64 v[10:11], v[10:11], 0, s[40:41]
	v_lshl_add_u64 v[10:11], v[10:11], 0, v[0:1]
	s_waitcnt lgkmcnt(0)
	global_store_dwordx4 v[10:11], v[2:5], off
	ds_read_b128 v[2:5], v6 offset:63360
	v_add_u32_e32 v6, 0x78, v8
	v_ashrrev_i32_e32 v7, 31, v6
	v_lshlrev_b64 v[6:7], 11, v[6:7]
	v_lshl_add_u64 v[6:7], s[4:5], 0, v[6:7]
	v_lshl_add_u64 v[6:7], v[6:7], 0, s[40:41]
	v_lshl_add_u64 v[6:7], v[6:7], 0, v[0:1]
	s_waitcnt lgkmcnt(0)
	global_store_dwordx4 v[6:7], v[2:5], off
	s_branch .LBB0_28

.LBB0_72:
	s_mul_i32 s42, s1, 0x6000
	s_add_i32 s43, s42, 0xffffa000
	s_cmp_gt_i32 s1, 0
	s_waitcnt vmcnt(6)
	s_cselect_b32 s43, s43, 0xc000
	s_waitcnt lgkmcnt(0)
	s_barrier
	s_setprio 2
	v_add3_u32 v0, s42, v177, v176
	v_add_u32_e32 v0, s14, v0
	ds_read_b128 v[180:183], v0
	ds_read_b128 v[184:187], v0 offset:1024
	ds_read_b128 v[188:191], v0 offset:2048
	ds_read_b128 v[192:195], v0 offset:3072
	v_add3_u32 v0, s42, v178, v176
	ds_read_b128 v[196:199], v0 offset:8192
	ds_read_b128 v[200:203], v0 offset:9216
	ds_read_b128 v[204:207], v0 offset:10240
	ds_read_b128 v[208:211], v0 offset:11264
	ds_read_b128 v[216:219], v0 offset:12288
	ds_read_b128 v[226:229], v0 offset:13312
	ds_read_b128 v[230:233], v0 offset:14336
	ds_read_b128 v[234:237], v0 offset:15360
	v_lshl_add_u64 v[212:213], v[174:175], 0, s[12:13]
	v_lshl_add_u64 v[212:213], v[162:163], 1, v[212:213]
	s_add_i32 s44, s43, s41
	s_mov_b32 m0, s44
	s_nop 0
	global_load_lds_dwordx4 v[212:213], off
	v_lshl_add_u64 v[212:213], v[174:175], 0, s[12:13]
	v_lshl_add_u64 v[212:213], v[164:165], 1, v[212:213]
	s_add_i32 s44, s43, s15
	s_mov_b32 m0, s44
	s_nop 0
	global_load_lds_dwordx4 v[212:213], off
	s_add_i32 s43, s40, s43
	v_lshl_add_u64 v[212:213], v[172:173], 0, s[12:13]
	s_mov_b32 m0, s43
	s_nop 0
	global_load_lds_dwordx4 v[212:213], off
	v_lshl_add_u64 v[212:213], v[170:171], 0, s[12:13]
	s_add_i32 s44, s43, 0x400
	s_mov_b32 m0, s44
	s_nop 0
	global_load_lds_dwordx4 v[212:213], off
	v_lshl_add_u64 v[212:213], v[168:169], 0, s[12:13]
	s_add_i32 s44, s43, 0x800
	s_mov_b32 m0, s44
	s_nop 0
	global_load_lds_dwordx4 v[212:213], off
	s_addk_i32 s43, 0xc00
	v_lshl_add_u64 v[212:213], v[166:167], 0, s[12:13]
	s_mov_b32 m0, s43
	s_nop 0
	global_load_lds_dwordx4 v[212:213], off
	s_setprio 0
	s_waitcnt lgkmcnt(7)
	v_mfma_f32_16x16x32_bf16 v[34:37], v[196:199], v[180:183], v[34:37]
	v_mfma_f32_16x16x32_bf16 v[38:41], v[196:199], v[184:187], v[38:41]
	v_mfma_f32_16x16x32_bf16 v[42:45], v[196:199], v[188:191], v[42:45]
	v_mfma_f32_16x16x32_bf16 v[46:49], v[196:199], v[192:195], v[46:49]
	s_waitcnt lgkmcnt(6)
	v_mfma_f32_16x16x32_bf16 v[50:53], v[200:203], v[180:183], v[50:53]
	v_mfma_f32_16x16x32_bf16 v[54:57], v[200:203], v[184:187], v[54:57]
	v_mfma_f32_16x16x32_bf16 v[58:61], v[200:203], v[188:191], v[58:61]
	v_mfma_f32_16x16x32_bf16 v[62:65], v[200:203], v[192:195], v[62:65]
	s_waitcnt lgkmcnt(5)
	v_mfma_f32_16x16x32_bf16 v[66:69], v[204:207], v[180:183], v[66:69]
	v_mfma_f32_16x16x32_bf16 v[70:73], v[204:207], v[184:187], v[70:73]
	v_mfma_f32_16x16x32_bf16 v[74:77], v[204:207], v[188:191], v[74:77]
	v_mfma_f32_16x16x32_bf16 v[78:81], v[204:207], v[192:195], v[78:81]
	s_waitcnt lgkmcnt(4)
	v_mfma_f32_16x16x32_bf16 v[82:85], v[208:211], v[180:183], v[82:85]
	v_mfma_f32_16x16x32_bf16 v[86:89], v[208:211], v[184:187], v[86:89]
	v_mfma_f32_16x16x32_bf16 v[90:93], v[208:211], v[188:191], v[90:93]
	v_mfma_f32_16x16x32_bf16 v[94:97], v[208:211], v[192:195], v[94:97]
	s_waitcnt lgkmcnt(3)
	v_mfma_f32_16x16x32_bf16 v[98:101], v[216:219], v[180:183], v[98:101]
	v_mfma_f32_16x16x32_bf16 v[102:105], v[216:219], v[184:187], v[102:105]
	v_mfma_f32_16x16x32_bf16 v[106:109], v[216:219], v[188:191], v[106:109]
	v_mfma_f32_16x16x32_bf16 v[110:113], v[216:219], v[192:195], v[110:113]
	s_waitcnt lgkmcnt(2)
	v_mfma_f32_16x16x32_bf16 v[114:117], v[226:229], v[180:183], v[114:117]
	v_mfma_f32_16x16x32_bf16 v[118:121], v[226:229], v[184:187], v[118:121]
	v_mfma_f32_16x16x32_bf16 v[122:125], v[226:229], v[188:191], v[122:125]
	v_mfma_f32_16x16x32_bf16 v[126:129], v[226:229], v[192:195], v[126:129]
	s_waitcnt lgkmcnt(1)
	v_mfma_f32_16x16x32_bf16 v[130:133], v[230:233], v[180:183], v[130:133]
	v_mfma_f32_16x16x32_bf16 v[134:137], v[230:233], v[184:187], v[134:137]
	v_mfma_f32_16x16x32_bf16 v[138:141], v[230:233], v[188:191], v[138:141]
	v_mfma_f32_16x16x32_bf16 v[142:145], v[230:233], v[192:195], v[142:145]
	s_waitcnt lgkmcnt(0)
	v_mfma_f32_16x16x32_bf16 v[146:149], v[234:237], v[180:183], v[146:149]
	v_mfma_f32_16x16x32_bf16 v[150:153], v[234:237], v[184:187], v[150:153]
	v_mfma_f32_16x16x32_bf16 v[154:157], v[234:237], v[188:191], v[154:157]
	v_mfma_f32_16x16x32_bf16 v[158:161], v[234:237], v[192:195], v[158:161]
	s_add_i32 s42, s1, 1
	s_cmp_lg_u32 s1, 2
	s_cselect_b32 s1, s42, 0
	s_add_u32 s12, s12, 64
	s_addc_u32 s13, s13, 0
	s_cmpk_eq_i32 s12, 0x780
	s_cbranch_scc0 .LBB0_72
	s_waitcnt vmcnt(6)
	v_mov_b32_e32 v162, v31
	v_mov_b32_e32 v163, v32
	v_mov_b32_e32 v31, v33
	v_mov_b32_e32 v164, v15
	v_mov_b32_e32 v165, v16
	v_pk_add_f32 v[30:31], v[162:163], v[30:31]
	v_mov_b32_e32 v15, v17
	v_pk_add_f32 v[14:15], v[164:165], v[14:15]
	v_add_f32_e32 v0, v30, v31
	v_add_f32_e32 v0, v0, v14
	v_add_f32_e32 v0, v0, v15
	s_waitcnt vmcnt(4)
	v_mov_b32_e32 v166, v27
	v_mov_b32_e32 v167, v28
	v_fmamk_f32 v0, v0, 0x3a800000, v250
	s_mov_b32 s1, 0x800000
	v_mov_b32_e32 v27, v29
	v_mov_b32_e32 v168, v11
	v_mov_b32_e32 v169, v12
	s_waitcnt vmcnt(1)
	v_mov_b32_e32 v180, v3
	v_mul_f32_e32 v3, 0x4b800000, v0
	v_cmp_gt_f32_e32 vcc, s1, v0
	v_pk_add_f32 v[14:15], v[166:167], v[26:27]
	v_mov_b32_e32 v11, v13
	v_cndmask_b32_e32 v0, v0, v3, vcc
	v_pk_add_f32 v[10:11], v[168:169], v[10:11]
	v_add_f32_e32 v3, v14, v15
	v_add_f32_e32 v3, v3, v10
	v_add_f32_e32 v3, v3, v11
	v_fmamk_f32 v3, v3, 0x3a800000, v250
	v_mov_b32_e32 v170, v23
	v_mov_b32_e32 v171, v24
	v_mov_b32_e32 v181, v4
	v_mul_f32_e32 v4, 0x4b800000, v3
	v_cmp_gt_f32_e64 s[40:41], s1, v3
	v_mov_b32_e32 v23, v25
	v_mov_b32_e32 v172, v7
	v_mov_b32_e32 v173, v8
	v_cndmask_b32_e64 v3, v3, v4, s[40:41]
	v_pk_add_f32 v[10:11], v[170:171], v[22:23]
	v_mov_b32_e32 v7, v9
	v_rsq_f32_e32 v179, v3
	v_pk_add_f32 v[6:7], v[172:173], v[6:7]
	v_add_f32_e32 v3, v10, v11
	v_add_f32_e32 v3, v3, v6
	v_add_f32_e32 v3, v3, v7
	v_fmamk_f32 v3, v3, 0x3a800000, v250
	v_mul_f32_e32 v4, 0x4b800000, v3
	v_cmp_gt_f32_e64 s[42:43], s1, v3
	s_waitcnt vmcnt(0)
	v_mov_b32_e32 v174, v19
	v_mov_b32_e32 v175, v20
	v_cndmask_b32_e64 v3, v3, v4, s[42:43]
	v_mov_b32_e32 v19, v21
	v_rsq_f32_e32 v182, v3
	v_pk_add_f32 v[6:7], v[174:175], v[18:19]
	v_mov_b32_e32 v3, v5
	v_pk_add_f32 v[2:3], v[180:181], v[2:3]
	v_add_f32_e32 v4, v6, v7
	v_add_f32_e32 v2, v4, v2
	v_add_f32_e32 v2, v2, v3
	v_fmamk_f32 v2, v2, 0x3a800000, v250
	v_mul_f32_e32 v3, 0x4b800000, v2
	v_cmp_gt_f32_e64 s[44:45], s1, v2
	s_waitcnt vmcnt(6)
	v_add_u32_e32 v183, v178, v176
	s_waitcnt lgkmcnt(0)
	s_barrier
	v_cndmask_b32_e64 v2, v2, v3, s[44:45]
	v_rsq_f32_e32 v180, v2
	ds_read_b128 v[2:5], v183 offset:15360
	ds_read_b128 v[6:9], v183 offset:14336
	ds_read_b128 v[10:13], v183 offset:13312
	ds_read_b128 v[14:17], v183 offset:12288
	ds_read_b128 v[18:21], v183 offset:11264
	ds_read_b128 v[22:25], v183 offset:10240
	ds_read_b128 v[26:29], v183 offset:9216
	ds_read_b128 v[30:33], v183 offset:8192
	v_add3_u32 v178, s14, v177, v176
	ds_read_b128 v[162:165], v178 offset:3072
	ds_read_b128 v[166:169], v178 offset:2048
	ds_read_b128 v[170:173], v178 offset:1024
	ds_read_b128 v[174:177], v178
	v_rsq_f32_e32 v0, v0
	v_mul_f32_e32 v184, 0x45800000, v179
	v_mul_f32_e32 v185, 0x45800000, v182
	v_mul_f32_e32 v186, 0x45800000, v180
	v_mul_f32_e32 v181, 0x45800000, v0
	s_waitcnt lgkmcnt(0)
	v_mfma_f32_16x16x32_bf16 v[34:37], v[30:33], v[174:177], v[34:37]
	v_mfma_f32_16x16x32_bf16 v[38:41], v[30:33], v[170:173], v[38:41]
	v_mfma_f32_16x16x32_bf16 v[42:45], v[30:33], v[166:169], v[42:45]
	v_mfma_f32_16x16x32_bf16 v[46:49], v[30:33], v[162:165], v[46:49]
	v_mfma_f32_16x16x32_bf16 v[50:53], v[26:29], v[174:177], v[50:53]
	v_mfma_f32_16x16x32_bf16 v[54:57], v[26:29], v[170:173], v[54:57]
	v_mfma_f32_16x16x32_bf16 v[58:61], v[26:29], v[166:169], v[58:61]
	v_mfma_f32_16x16x32_bf16 v[62:65], v[26:29], v[162:165], v[62:65]
	v_mfma_f32_16x16x32_bf16 v[66:69], v[22:25], v[174:177], v[66:69]
	v_mfma_f32_16x16x32_bf16 v[70:73], v[22:25], v[170:173], v[70:73]
	v_mfma_f32_16x16x32_bf16 v[74:77], v[22:25], v[166:169], v[74:77]
	v_mfma_f32_16x16x32_bf16 v[22:25], v[22:25], v[162:165], v[78:81]
	v_mfma_f32_16x16x32_bf16 v[78:81], v[18:21], v[174:177], v[82:85]
	v_mfma_f32_16x16x32_bf16 v[82:85], v[18:21], v[170:173], v[86:89]
	v_mfma_f32_16x16x32_bf16 v[86:89], v[18:21], v[166:169], v[90:93]
	v_mfma_f32_16x16x32_bf16 v[18:21], v[18:21], v[162:165], v[94:97]
	v_mfma_f32_16x16x32_bf16 v[90:93], v[14:17], v[174:177], v[98:101]
	v_mfma_f32_16x16x32_bf16 v[94:97], v[14:17], v[170:173], v[102:105]
	v_mfma_f32_16x16x32_bf16 v[98:101], v[14:17], v[166:169], v[106:109]
	v_mfma_f32_16x16x32_bf16 v[14:17], v[14:17], v[162:165], v[110:113]
	v_mfma_f32_16x16x32_bf16 v[102:105], v[10:13], v[174:177], v[114:117]
	v_mfma_f32_16x16x32_bf16 v[106:109], v[10:13], v[170:173], v[118:121]
	v_mfma_f32_16x16x32_bf16 v[110:113], v[10:13], v[166:169], v[122:125]
	v_mfma_f32_16x16x32_bf16 v[10:13], v[10:13], v[162:165], v[126:129]
	v_mfma_f32_16x16x32_bf16 v[114:117], v[6:9], v[174:177], v[130:133]
	v_mfma_f32_16x16x32_bf16 v[118:121], v[6:9], v[170:173], v[134:137]
	v_mfma_f32_16x16x32_bf16 v[122:125], v[6:9], v[166:169], v[138:141]
	v_mfma_f32_16x16x32_bf16 v[6:9], v[6:9], v[162:165], v[142:145]
	v_mfma_f32_16x16x32_bf16 v[126:129], v[2:5], v[174:177], v[146:149]
	v_mfma_f32_16x16x32_bf16 v[130:133], v[2:5], v[170:173], v[150:153]
	v_mfma_f32_16x16x32_bf16 v[134:137], v[2:5], v[166:169], v[154:157]
	v_mfma_f32_16x16x32_bf16 v[2:5], v[2:5], v[162:165], v[158:161]
	s_waitcnt vmcnt(0)
	v_cndmask_b32_e32 v30, v0, v181, vcc
	v_cndmask_b32_e64 v28, v179, v184, s[40:41]
	v_cndmask_b32_e64 v26, v182, v185, s[42:43]
	v_cndmask_b32_e64 v0, v180, v186, s[44:45]
	s_waitcnt lgkmcnt(0)
	s_barrier
	ds_read_b128 v[138:141], v178 offset:24576
	ds_read_b128 v[142:145], v178 offset:25600
	ds_read_b128 v[146:149], v178 offset:26624
	ds_read_b128 v[150:153], v178 offset:27648
	ds_read_b128 v[154:157], v183 offset:32768
	ds_read_b128 v[158:161], v183 offset:33792
	ds_read_b128 v[162:165], v183 offset:34816
	ds_read_b128 v[166:169], v183 offset:35840
	ds_read_b128 v[170:173], v183 offset:36864
	ds_read_b128 v[174:177], v183 offset:37888
	ds_read_b128 v[178:181], v183 offset:38912
	ds_read_b128 v[182:185], v183 offset:39936
	s_waitcnt lgkmcnt(7)
	v_mfma_f32_16x16x32_bf16 v[32:35], v[154:157], v[138:141], v[34:37]
	v_mfma_f32_16x16x32_bf16 v[36:39], v[154:157], v[142:145], v[38:41]
	v_mfma_f32_16x16x32_bf16 v[40:43], v[154:157], v[146:149], v[42:45]
	v_mfma_f32_16x16x32_bf16 v[44:47], v[154:157], v[150:153], v[46:49]
	s_waitcnt lgkmcnt(6)
	v_mfma_f32_16x16x32_bf16 v[48:51], v[158:161], v[138:141], v[50:53]
	v_mfma_f32_16x16x32_bf16 v[52:55], v[158:161], v[142:145], v[54:57]
	v_mfma_f32_16x16x32_bf16 v[56:59], v[158:161], v[146:149], v[58:61]
	v_mfma_f32_16x16x32_bf16 v[60:63], v[158:161], v[150:153], v[62:65]
	s_waitcnt lgkmcnt(5)
	v_mfma_f32_16x16x32_bf16 v[64:67], v[162:165], v[138:141], v[66:69]
	v_mfma_f32_16x16x32_bf16 v[68:71], v[162:165], v[142:145], v[70:73]
	v_mfma_f32_16x16x32_bf16 v[72:75], v[162:165], v[146:149], v[74:77]
	v_mfma_f32_16x16x32_bf16 v[154:157], v[162:165], v[150:153], v[22:25]
	s_waitcnt lgkmcnt(4)
	v_mfma_f32_16x16x32_bf16 v[76:79], v[166:169], v[138:141], v[78:81]
	v_mfma_f32_16x16x32_bf16 v[80:83], v[166:169], v[142:145], v[82:85]
	v_mfma_f32_16x16x32_bf16 v[84:87], v[166:169], v[146:149], v[86:89]
	v_mfma_f32_16x16x32_bf16 v[158:161], v[166:169], v[150:153], v[18:21]
	s_waitcnt lgkmcnt(3)
	v_mfma_f32_16x16x32_bf16 v[88:91], v[170:173], v[138:141], v[90:93]
	v_mfma_f32_16x16x32_bf16 v[92:95], v[170:173], v[142:145], v[94:97]
	v_mfma_f32_16x16x32_bf16 v[96:99], v[170:173], v[146:149], v[98:101]
	v_mfma_f32_16x16x32_bf16 v[162:165], v[170:173], v[150:153], v[14:17]
	s_waitcnt lgkmcnt(2)
	v_mfma_f32_16x16x32_bf16 v[100:103], v[174:177], v[138:141], v[102:105]
	v_mfma_f32_16x16x32_bf16 v[104:107], v[174:177], v[142:145], v[106:109]
	v_mfma_f32_16x16x32_bf16 v[108:111], v[174:177], v[146:149], v[110:113]
	v_mfma_f32_16x16x32_bf16 v[166:169], v[174:177], v[150:153], v[10:13]
	s_waitcnt lgkmcnt(1)
	v_mfma_f32_16x16x32_bf16 v[112:115], v[178:181], v[138:141], v[114:117]
	v_mfma_f32_16x16x32_bf16 v[116:119], v[178:181], v[142:145], v[118:121]
	v_mfma_f32_16x16x32_bf16 v[22:25], v[178:181], v[146:149], v[122:125]
	v_mfma_f32_16x16x32_bf16 v[18:21], v[178:181], v[150:153], v[6:9]
	s_waitcnt lgkmcnt(0)
	v_mfma_f32_16x16x32_bf16 v[14:17], v[182:185], v[138:141], v[126:129]
	v_mfma_f32_16x16x32_bf16 v[10:13], v[182:185], v[142:145], v[130:133]
	v_mfma_f32_16x16x32_bf16 v[6:9], v[182:185], v[146:149], v[134:137]
	v_mfma_f32_16x16x32_bf16 v[2:5], v[182:185], v[150:153], v[2:5]
	v_mov_b32_e32 v27, v224
	s_movk_i32 s1, 0x210
	v_lshrrev_b32_e32 v120, 1, v27
	v_and_b32_e32 v31, 0x7fffff80, v27
	v_and_b32_e32 v120, 24, v120
	v_and_b32_e32 v29, 0x4f, v27
	v_lshl_or_b32 v31, v31, 1, v120
	v_pk_mul_f32 v[32:33], v[30:31], v[32:33] op_sel_hi:[0,1]
	v_pk_mul_f32 v[34:35], v[30:31], v[34:35] op_sel_hi:[0,1]
	v_mad_u32_u24 v29, v29, s1, v31
	v_cvt_pk_bf16_f32 v32, v32, v33
	v_cvt_pk_bf16_f32 v33, v34, v35
	v_pk_mul_f32 v[34:35], v[28:29], v[36:37] op_sel_hi:[0,1]
	v_pk_mul_f32 v[36:37], v[28:29], v[38:39] op_sel_hi:[0,1]
	v_cvt_pk_bf16_f32 v34, v34, v35
	v_cvt_pk_bf16_f32 v35, v36, v37
	v_pk_mul_f32 v[36:37], v[26:27], v[40:41] op_sel_hi:[0,1]
	v_pk_mul_f32 v[38:39], v[26:27], v[42:43] op_sel_hi:[0,1]
	v_cvt_pk_bf16_f32 v36, v36, v37
	v_cvt_pk_bf16_f32 v37, v38, v39
	v_pk_mul_f32 v[38:39], v[0:1], v[44:45] op_sel_hi:[0,1]
	v_pk_mul_f32 v[40:41], v[0:1], v[46:47] op_sel_hi:[0,1]
	v_cvt_pk_bf16_f32 v38, v38, v39
	v_cvt_pk_bf16_f32 v39, v40, v41
	v_pk_mul_f32 v[40:41], v[30:31], v[48:49] op_sel_hi:[0,1]
	v_pk_mul_f32 v[42:43], v[30:31], v[50:51] op_sel_hi:[0,1]
	v_cvt_pk_bf16_f32 v40, v40, v41
	v_cvt_pk_bf16_f32 v41, v42, v43
	s_barrier
	ds_write2_b64 v29, v[32:33], v[40:41] offset1:4
	v_pk_mul_f32 v[32:33], v[28:29], v[52:53] op_sel_hi:[0,1]
	v_pk_mul_f32 v[40:41], v[28:29], v[54:55] op_sel_hi:[0,1]
	v_cvt_pk_bf16_f32 v32, v32, v33
	v_cvt_pk_bf16_f32 v33, v40, v41
	v_add_u32_e32 v31, 0x2000, v29
	ds_write2_b64 v31, v[34:35], v[32:33] offset0:32 offset1:36
	v_pk_mul_f32 v[32:33], v[26:27], v[56:57] op_sel_hi:[0,1]
	v_pk_mul_f32 v[34:35], v[26:27], v[58:59] op_sel_hi:[0,1]
	v_cvt_pk_bf16_f32 v32, v32, v33
	v_cvt_pk_bf16_f32 v33, v34, v35
	v_add_u32_e32 v44, 0x4000, v29
	ds_write2_b64 v44, v[36:37], v[32:33] offset0:64 offset1:68
	v_pk_mul_f32 v[32:33], v[0:1], v[60:61] op_sel_hi:[0,1]
	v_pk_mul_f32 v[34:35], v[0:1], v[62:63] op_sel_hi:[0,1]
	v_cvt_pk_bf16_f32 v32, v32, v33
	v_cvt_pk_bf16_f32 v33, v34, v35
	v_add_u32_e32 v45, 0x6000, v29
	ds_write2_b64 v45, v[38:39], v[32:33] offset0:96 offset1:100
	v_pk_mul_f32 v[32:33], v[30:31], v[64:65] op_sel_hi:[0,1]
	v_pk_mul_f32 v[34:35], v[30:31], v[66:67] op_sel_hi:[0,1]
	v_cvt_pk_bf16_f32 v32, v32, v33
	v_cvt_pk_bf16_f32 v33, v34, v35
	v_pk_mul_f32 v[34:35], v[28:29], v[68:69] op_sel_hi:[0,1]
	v_pk_mul_f32 v[36:37], v[28:29], v[70:71] op_sel_hi:[0,1]
	v_cvt_pk_bf16_f32 v34, v34, v35
	v_cvt_pk_bf16_f32 v35, v36, v37
	v_pk_mul_f32 v[36:37], v[26:27], v[72:73] op_sel_hi:[0,1]
	v_pk_mul_f32 v[38:39], v[26:27], v[74:75] op_sel_hi:[0,1]
	v_cvt_pk_bf16_f32 v36, v36, v37
	v_cvt_pk_bf16_f32 v37, v38, v39
	v_pk_mul_f32 v[38:39], v[0:1], v[154:155] op_sel_hi:[0,1]
	v_pk_mul_f32 v[40:41], v[0:1], v[156:157] op_sel_hi:[0,1]
	v_cvt_pk_bf16_f32 v38, v38, v39
	v_cvt_pk_bf16_f32 v39, v40, v41
	v_pk_mul_f32 v[40:41], v[30:31], v[76:77] op_sel_hi:[0,1]
	v_pk_mul_f32 v[42:43], v[30:31], v[78:79] op_sel_hi:[0,1]
	v_cvt_pk_bf16_f32 v40, v40, v41
	v_cvt_pk_bf16_f32 v41, v42, v43
	ds_write2_b64 v29, v[32:33], v[40:41] offset0:8 offset1:12
	v_pk_mul_f32 v[32:33], v[28:29], v[80:81] op_sel_hi:[0,1]
	v_pk_mul_f32 v[40:41], v[28:29], v[82:83] op_sel_hi:[0,1]
	v_cvt_pk_bf16_f32 v32, v32, v33
	v_cvt_pk_bf16_f32 v33, v40, v41
	ds_write2_b64 v31, v[34:35], v[32:33] offset0:40 offset1:44
	v_pk_mul_f32 v[32:33], v[26:27], v[84:85] op_sel_hi:[0,1]
	v_pk_mul_f32 v[34:35], v[26:27], v[86:87] op_sel_hi:[0,1]
	v_cvt_pk_bf16_f32 v32, v32, v33
	v_cvt_pk_bf16_f32 v33, v34, v35
	ds_write2_b64 v44, v[36:37], v[32:33] offset0:72 offset1:76
	v_pk_mul_f32 v[32:33], v[0:1], v[158:159] op_sel_hi:[0,1]
	v_pk_mul_f32 v[34:35], v[0:1], v[160:161] op_sel_hi:[0,1]
	v_cvt_pk_bf16_f32 v32, v32, v33
	v_cvt_pk_bf16_f32 v33, v34, v35
	ds_write2_b64 v45, v[38:39], v[32:33] offset0:104 offset1:108
	v_pk_mul_f32 v[32:33], v[30:31], v[88:89] op_sel_hi:[0,1]
	v_pk_mul_f32 v[34:35], v[30:31], v[90:91] op_sel_hi:[0,1]
	v_cvt_pk_bf16_f32 v32, v32, v33
	v_cvt_pk_bf16_f32 v33, v34, v35
	v_pk_mul_f32 v[34:35], v[28:29], v[92:93] op_sel_hi:[0,1]
	v_pk_mul_f32 v[36:37], v[28:29], v[94:95] op_sel_hi:[0,1]
	v_cvt_pk_bf16_f32 v34, v34, v35
	v_cvt_pk_bf16_f32 v35, v36, v37
	v_pk_mul_f32 v[36:37], v[26:27], v[96:97] op_sel_hi:[0,1]
	v_pk_mul_f32 v[38:39], v[26:27], v[98:99] op_sel_hi:[0,1]
	v_cvt_pk_bf16_f32 v36, v36, v37
	v_cvt_pk_bf16_f32 v37, v38, v39
	v_pk_mul_f32 v[38:39], v[0:1], v[162:163] op_sel_hi:[0,1]
	v_pk_mul_f32 v[40:41], v[0:1], v[164:165] op_sel_hi:[0,1]
	v_cvt_pk_bf16_f32 v38, v38, v39
	v_cvt_pk_bf16_f32 v39, v40, v41
	v_pk_mul_f32 v[40:41], v[30:31], v[100:101] op_sel_hi:[0,1]
	v_pk_mul_f32 v[42:43], v[30:31], v[102:103] op_sel_hi:[0,1]
	v_cvt_pk_bf16_f32 v40, v40, v41
	v_cvt_pk_bf16_f32 v41, v42, v43
	ds_write2_b64 v29, v[32:33], v[40:41] offset0:16 offset1:20
	v_pk_mul_f32 v[32:33], v[28:29], v[104:105] op_sel_hi:[0,1]
	v_pk_mul_f32 v[40:41], v[28:29], v[106:107] op_sel_hi:[0,1]
	v_cvt_pk_bf16_f32 v32, v32, v33
	v_cvt_pk_bf16_f32 v33, v40, v41
	ds_write2_b64 v31, v[34:35], v[32:33] offset0:48 offset1:52
	v_pk_mul_f32 v[32:33], v[26:27], v[108:109] op_sel_hi:[0,1]
	v_pk_mul_f32 v[34:35], v[26:27], v[110:111] op_sel_hi:[0,1]
	v_cvt_pk_bf16_f32 v32, v32, v33
	v_cvt_pk_bf16_f32 v33, v34, v35
	ds_write2_b64 v44, v[36:37], v[32:33] offset0:80 offset1:84
	v_pk_mul_f32 v[32:33], v[0:1], v[166:167] op_sel_hi:[0,1]
	v_pk_mul_f32 v[34:35], v[0:1], v[168:169] op_sel_hi:[0,1]
	v_cvt_pk_bf16_f32 v32, v32, v33
	v_cvt_pk_bf16_f32 v33, v34, v35
	v_pk_mul_f32 v[18:19], v[0:1], v[18:19] op_sel_hi:[0,1]
	v_pk_mul_f32 v[20:21], v[0:1], v[20:21] op_sel_hi:[0,1]
	v_pk_mul_f32 v[2:3], v[0:1], v[2:3] op_sel_hi:[0,1]
	v_pk_mul_f32 v[4:5], v[0:1], v[4:5] op_sel_hi:[0,1]
	v_lshlrev_b32_e32 v0, 3, v27
	ds_write2_b64 v45, v[38:39], v[32:33] offset0:112 offset1:116
	v_pk_mul_f32 v[32:33], v[30:31], v[112:113] op_sel_hi:[0,1]
	v_pk_mul_f32 v[34:35], v[30:31], v[114:115] op_sel_hi:[0,1]
	v_cvt_pk_bf16_f32 v18, v18, v19
	v_cvt_pk_bf16_f32 v19, v20, v21
	v_cvt_pk_bf16_f32 v2, v2, v3
	v_cvt_pk_bf16_f32 v3, v4, v5
	v_and_b32_e32 v0, 0xf8, v0
	v_cvt_pk_bf16_f32 v32, v32, v33
	v_cvt_pk_bf16_f32 v33, v34, v35
	v_pk_mul_f32 v[34:35], v[28:29], v[116:117] op_sel_hi:[0,1]
	v_pk_mul_f32 v[36:37], v[28:29], v[118:119] op_sel_hi:[0,1]
	v_pk_mul_f32 v[22:23], v[26:27], v[22:23] op_sel_hi:[0,1]
	v_pk_mul_f32 v[24:25], v[26:27], v[24:25] op_sel_hi:[0,1]
	v_pk_mul_f32 v[14:15], v[30:31], v[14:15] op_sel_hi:[0,1]
	v_pk_mul_f32 v[16:17], v[30:31], v[16:17] op_sel_hi:[0,1]
	v_pk_mul_f32 v[10:11], v[28:29], v[10:11] op_sel_hi:[0,1]
	v_pk_mul_f32 v[12:13], v[28:29], v[12:13] op_sel_hi:[0,1]
	v_pk_mul_f32 v[6:7], v[26:27], v[6:7] op_sel_hi:[0,1]
	v_pk_mul_f32 v[8:9], v[26:27], v[8:9] op_sel_hi:[0,1]
	ds_write2_b64 v45, v[18:19], v[2:3] offset0:120 offset1:124
	v_or_b32_e32 v2, s0, v0
	s_movk_i32 s1, 0x400
	v_cvt_pk_bf16_f32 v34, v34, v35
	v_cvt_pk_bf16_f32 v35, v36, v37
	v_cvt_pk_bf16_f32 v22, v22, v23
	v_cvt_pk_bf16_f32 v23, v24, v25
	v_cvt_pk_bf16_f32 v14, v14, v15
	v_cvt_pk_bf16_f32 v15, v16, v17
	v_cvt_pk_bf16_f32 v10, v10, v11
	v_cvt_pk_bf16_f32 v11, v12, v13
	v_cvt_pk_bf16_f32 v6, v6, v7
	v_cvt_pk_bf16_f32 v7, v8, v9
	v_cmp_gt_i32_e64 s[44:45], s1, v2
	ds_write2_b64 v29, v[32:33], v[14:15] offset0:24 offset1:28
	ds_write2_b64 v31, v[34:35], v[10:11] offset0:56 offset1:60
	ds_write2_b64 v44, v[22:23], v[6:7] offset0:88 offset1:92
	s_waitcnt lgkmcnt(0)
	s_barrier
	s_mov_b64 s[12:13], 11
	s_mov_b64 s[40:41], s[46:47]
	s_branch .LBB0_78

.LBB0_76:
	s_mul_i32 s41, s12, 0x6000
	s_add_i32 s42, s41, 0xffffa000
	s_cmp_gt_i32 s12, 0
	s_waitcnt vmcnt(6)
	s_cselect_b32 s42, s42, 0xc000
	s_waitcnt lgkmcnt(0)
	s_barrier
	s_setprio 2
	v_add3_u32 v0, s41, v177, v176
	v_add_u32_e32 v0, s13, v0
	ds_read_b128 v[180:183], v0
	ds_read_b128 v[184:187], v0 offset:1024
	ds_read_b128 v[188:191], v0 offset:2048
	ds_read_b128 v[192:195], v0 offset:3072
	v_add3_u32 v0, s41, v178, v176
	ds_read_b128 v[196:199], v0 offset:8192
	ds_read_b128 v[200:203], v0 offset:9216
	ds_read_b128 v[204:207], v0 offset:10240
	ds_read_b128 v[208:211], v0 offset:11264
	ds_read_b128 v[216:219], v0 offset:12288
	ds_read_b128 v[226:229], v0 offset:13312
	ds_read_b128 v[230:233], v0 offset:14336
	ds_read_b128 v[234:237], v0 offset:15360
	v_lshl_add_u64 v[212:213], v[174:175], 0, s[0:1]
	v_lshl_add_u64 v[212:213], v[162:163], 1, v[212:213]
	s_add_i32 s43, s42, s40
	s_mov_b32 m0, s43
	s_nop 0
	global_load_lds_dwordx4 v[212:213], off
	v_lshl_add_u64 v[212:213], v[174:175], 0, s[0:1]
	v_lshl_add_u64 v[212:213], v[164:165], 1, v[212:213]
	s_add_i32 s43, s42, s14
	s_mov_b32 m0, s43
	s_nop 0
	global_load_lds_dwordx4 v[212:213], off
	s_add_i32 s42, s15, s42
	v_lshl_add_u64 v[212:213], v[172:173], 0, s[0:1]
	s_mov_b32 m0, s42
	s_nop 0
	global_load_lds_dwordx4 v[212:213], off
	v_lshl_add_u64 v[212:213], v[170:171], 0, s[0:1]
	s_add_i32 s43, s42, 0x400
	s_mov_b32 m0, s43
	s_nop 0
	global_load_lds_dwordx4 v[212:213], off
	v_lshl_add_u64 v[212:213], v[168:169], 0, s[0:1]
	s_add_i32 s43, s42, 0x800
	s_mov_b32 m0, s43
	s_nop 0
	global_load_lds_dwordx4 v[212:213], off
	s_addk_i32 s42, 0xc00
	v_lshl_add_u64 v[212:213], v[166:167], 0, s[0:1]
	s_mov_b32 m0, s42
	s_nop 0
	global_load_lds_dwordx4 v[212:213], off
	s_setprio 0
	s_waitcnt lgkmcnt(7)
	v_mfma_f32_16x16x32_bf16 v[34:37], v[196:199], v[180:183], v[34:37]
	v_mfma_f32_16x16x32_bf16 v[38:41], v[196:199], v[184:187], v[38:41]
	v_mfma_f32_16x16x32_bf16 v[42:45], v[196:199], v[188:191], v[42:45]
	v_mfma_f32_16x16x32_bf16 v[46:49], v[196:199], v[192:195], v[46:49]
	s_waitcnt lgkmcnt(6)
	v_mfma_f32_16x16x32_bf16 v[50:53], v[200:203], v[180:183], v[50:53]
	v_mfma_f32_16x16x32_bf16 v[54:57], v[200:203], v[184:187], v[54:57]
	v_mfma_f32_16x16x32_bf16 v[58:61], v[200:203], v[188:191], v[58:61]
	v_mfma_f32_16x16x32_bf16 v[62:65], v[200:203], v[192:195], v[62:65]
	s_waitcnt lgkmcnt(5)
	v_mfma_f32_16x16x32_bf16 v[66:69], v[204:207], v[180:183], v[66:69]
	v_mfma_f32_16x16x32_bf16 v[70:73], v[204:207], v[184:187], v[70:73]
	v_mfma_f32_16x16x32_bf16 v[74:77], v[204:207], v[188:191], v[74:77]
	v_mfma_f32_16x16x32_bf16 v[78:81], v[204:207], v[192:195], v[78:81]
	s_waitcnt lgkmcnt(4)
	v_mfma_f32_16x16x32_bf16 v[82:85], v[208:211], v[180:183], v[82:85]
	v_mfma_f32_16x16x32_bf16 v[86:89], v[208:211], v[184:187], v[86:89]
	v_mfma_f32_16x16x32_bf16 v[90:93], v[208:211], v[188:191], v[90:93]
	v_mfma_f32_16x16x32_bf16 v[94:97], v[208:211], v[192:195], v[94:97]
	s_waitcnt lgkmcnt(3)
	v_mfma_f32_16x16x32_bf16 v[98:101], v[216:219], v[180:183], v[98:101]
	v_mfma_f32_16x16x32_bf16 v[102:105], v[216:219], v[184:187], v[102:105]
	v_mfma_f32_16x16x32_bf16 v[106:109], v[216:219], v[188:191], v[106:109]
	v_mfma_f32_16x16x32_bf16 v[110:113], v[216:219], v[192:195], v[110:113]
	s_waitcnt lgkmcnt(2)
	v_mfma_f32_16x16x32_bf16 v[114:117], v[226:229], v[180:183], v[114:117]
	v_mfma_f32_16x16x32_bf16 v[118:121], v[226:229], v[184:187], v[118:121]
	v_mfma_f32_16x16x32_bf16 v[122:125], v[226:229], v[188:191], v[122:125]
	v_mfma_f32_16x16x32_bf16 v[126:129], v[226:229], v[192:195], v[126:129]
	s_waitcnt lgkmcnt(1)
	v_mfma_f32_16x16x32_bf16 v[130:133], v[230:233], v[180:183], v[130:133]
	v_mfma_f32_16x16x32_bf16 v[134:137], v[230:233], v[184:187], v[134:137]
	v_mfma_f32_16x16x32_bf16 v[138:141], v[230:233], v[188:191], v[138:141]
	v_mfma_f32_16x16x32_bf16 v[142:145], v[230:233], v[192:195], v[142:145]
	s_waitcnt lgkmcnt(0)
	v_mfma_f32_16x16x32_bf16 v[146:149], v[234:237], v[180:183], v[146:149]
	v_mfma_f32_16x16x32_bf16 v[150:153], v[234:237], v[184:187], v[150:153]
	v_mfma_f32_16x16x32_bf16 v[154:157], v[234:237], v[188:191], v[154:157]
	v_mfma_f32_16x16x32_bf16 v[158:161], v[234:237], v[192:195], v[158:161]
	s_add_i32 s41, s12, 1
	s_cmp_lg_u32 s12, 2
	s_cselect_b32 s12, s41, 0
	s_add_u32 s0, s0, 64
	s_addc_u32 s1, s1, 0
	s_cmpk_eq_i32 s0, 0x780
	s_cbranch_scc0 .LBB0_76
	s_waitcnt vmcnt(6)
	v_mov_b32_e32 v162, v23
	v_mov_b32_e32 v163, v24
	v_mov_b32_e32 v23, v25
	v_mov_b32_e32 v164, v7
	v_mov_b32_e32 v165, v8
	v_pk_add_f32 v[22:23], v[162:163], v[22:23]
	v_mov_b32_e32 v7, v9
	v_pk_add_f32 v[6:7], v[164:165], v[6:7]
	v_add_f32_e32 v0, v22, v23
	v_add_f32_e32 v0, v0, v6
	v_add_f32_e32 v0, v0, v7
	v_fmamk_f32 v0, v0, 0x3a800000, v250
	s_mov_b32 s0, 0x800000
	s_waitcnt vmcnt(4)
	v_mov_b32_e32 v166, v19
	v_mov_b32_e32 v167, v20
	v_mov_b32_e32 v168, v3
	v_mul_f32_e32 v3, 0x4b800000, v0
	v_cmp_gt_f32_e32 vcc, s0, v0
	v_mov_b32_e32 v19, v21
	v_mov_b32_e32 v169, v4
	v_cndmask_b32_e32 v0, v0, v3, vcc
	v_pk_add_f32 v[6:7], v[166:167], v[18:19]
	v_mov_b32_e32 v3, v5
	v_pk_add_f32 v[2:3], v[168:169], v[2:3]
	v_add_f32_e32 v4, v6, v7
	v_add_f32_e32 v2, v4, v2
	v_add_f32_e32 v2, v2, v3
	v_fmamk_f32 v2, v2, 0x3a800000, v250
	v_mul_f32_e32 v3, 0x4b800000, v2
	v_cmp_gt_f32_e64 s[40:41], s0, v2
	s_waitcnt vmcnt(2)
	v_mov_b32_e32 v170, v27
	v_mov_b32_e32 v171, v28
	v_cndmask_b32_e64 v2, v2, v3, s[40:41]
	v_mov_b32_e32 v27, v29
	v_mov_b32_e32 v172, v11
	v_mov_b32_e32 v173, v12
	v_rsq_f32_e32 v179, v2
	v_pk_add_f32 v[2:3], v[170:171], v[26:27]
	v_mov_b32_e32 v11, v13
	v_pk_add_f32 v[4:5], v[172:173], v[10:11]
	v_add_f32_e32 v2, v2, v3
	v_add_f32_e32 v2, v2, v4
	v_add_f32_e32 v2, v2, v5
	v_fmamk_f32 v2, v2, 0x3a800000, v250
	v_mul_f32_e32 v3, 0x4b800000, v2
	v_cmp_gt_f32_e64 s[42:43], s0, v2
	s_waitcnt vmcnt(0)
	v_mov_b32_e32 v174, v31
	v_mov_b32_e32 v175, v32
	v_cndmask_b32_e64 v2, v2, v3, s[42:43]
	v_mov_b32_e32 v31, v33
	v_mov_b32_e32 v180, v15
	v_mov_b32_e32 v181, v16
	v_rsq_f32_e32 v182, v2
	v_pk_add_f32 v[2:3], v[174:175], v[30:31]
	v_mov_b32_e32 v15, v17
	v_pk_add_f32 v[4:5], v[180:181], v[14:15]
	v_add_f32_e32 v2, v2, v3
	v_add_f32_e32 v2, v2, v4
	v_add_f32_e32 v2, v2, v5
	v_fmamk_f32 v2, v2, 0x3a800000, v250
	v_mul_f32_e32 v3, 0x4b800000, v2
	v_cmp_gt_f32_e64 s[44:45], s0, v2
	s_waitcnt vmcnt(6)
	v_add_u32_e32 v183, v178, v176
	s_waitcnt lgkmcnt(0)
	s_barrier
	v_cndmask_b32_e64 v2, v2, v3, s[44:45]
	v_rsq_f32_e32 v180, v2
	ds_read_b128 v[2:5], v183 offset:15360
	ds_read_b128 v[6:9], v183 offset:14336
	ds_read_b128 v[10:13], v183 offset:13312
	ds_read_b128 v[14:17], v183 offset:12288
	ds_read_b128 v[18:21], v183 offset:11264
	ds_read_b128 v[22:25], v183 offset:10240
	ds_read_b128 v[26:29], v183 offset:9216
	ds_read_b128 v[30:33], v183 offset:8192
	v_add3_u32 v178, s13, v177, v176
	ds_read_b128 v[162:165], v178 offset:3072
	ds_read_b128 v[166:169], v178 offset:2048
	ds_read_b128 v[170:173], v178 offset:1024
	ds_read_b128 v[174:177], v178
	v_rsq_f32_e32 v0, v0
	v_mul_f32_e32 v184, 0x45800000, v179
	v_mul_f32_e32 v185, 0x45800000, v182
	v_mul_f32_e32 v186, 0x45800000, v180
	v_mul_f32_e32 v181, 0x45800000, v0
	s_waitcnt lgkmcnt(0)
	v_mfma_f32_16x16x32_bf16 v[34:37], v[30:33], v[174:177], v[34:37]
	v_mfma_f32_16x16x32_bf16 v[38:41], v[30:33], v[170:173], v[38:41]
	v_mfma_f32_16x16x32_bf16 v[42:45], v[30:33], v[166:169], v[42:45]
	v_mfma_f32_16x16x32_bf16 v[46:49], v[30:33], v[162:165], v[46:49]
	v_mfma_f32_16x16x32_bf16 v[50:53], v[26:29], v[174:177], v[50:53]
	v_mfma_f32_16x16x32_bf16 v[54:57], v[26:29], v[170:173], v[54:57]
	v_mfma_f32_16x16x32_bf16 v[58:61], v[26:29], v[166:169], v[58:61]
	v_mfma_f32_16x16x32_bf16 v[62:65], v[26:29], v[162:165], v[62:65]
	v_mfma_f32_16x16x32_bf16 v[66:69], v[22:25], v[174:177], v[66:69]
	v_mfma_f32_16x16x32_bf16 v[70:73], v[22:25], v[170:173], v[70:73]
	v_mfma_f32_16x16x32_bf16 v[74:77], v[22:25], v[166:169], v[74:77]
	v_mfma_f32_16x16x32_bf16 v[22:25], v[22:25], v[162:165], v[78:81]
	v_mfma_f32_16x16x32_bf16 v[78:81], v[18:21], v[174:177], v[82:85]
	v_mfma_f32_16x16x32_bf16 v[82:85], v[18:21], v[170:173], v[86:89]
	v_mfma_f32_16x16x32_bf16 v[86:89], v[18:21], v[166:169], v[90:93]
	v_mfma_f32_16x16x32_bf16 v[18:21], v[18:21], v[162:165], v[94:97]
	v_mfma_f32_16x16x32_bf16 v[90:93], v[14:17], v[174:177], v[98:101]
	v_mfma_f32_16x16x32_bf16 v[94:97], v[14:17], v[170:173], v[102:105]
	v_mfma_f32_16x16x32_bf16 v[98:101], v[14:17], v[166:169], v[106:109]
	v_mfma_f32_16x16x32_bf16 v[14:17], v[14:17], v[162:165], v[110:113]
	v_mfma_f32_16x16x32_bf16 v[102:105], v[10:13], v[174:177], v[114:117]
	v_mfma_f32_16x16x32_bf16 v[106:109], v[10:13], v[170:173], v[118:121]
	v_mfma_f32_16x16x32_bf16 v[110:113], v[10:13], v[166:169], v[122:125]
	v_mfma_f32_16x16x32_bf16 v[10:13], v[10:13], v[162:165], v[126:129]
	v_mfma_f32_16x16x32_bf16 v[114:117], v[6:9], v[174:177], v[130:133]
	v_mfma_f32_16x16x32_bf16 v[118:121], v[6:9], v[170:173], v[134:137]
	v_mfma_f32_16x16x32_bf16 v[122:125], v[6:9], v[166:169], v[138:141]
	v_mfma_f32_16x16x32_bf16 v[6:9], v[6:9], v[162:165], v[142:145]
	v_mfma_f32_16x16x32_bf16 v[126:129], v[2:5], v[174:177], v[146:149]
	v_mfma_f32_16x16x32_bf16 v[130:133], v[2:5], v[170:173], v[150:153]
	v_mfma_f32_16x16x32_bf16 v[134:137], v[2:5], v[166:169], v[154:157]
	v_mfma_f32_16x16x32_bf16 v[2:5], v[2:5], v[162:165], v[158:161]
	s_waitcnt vmcnt(0)
	v_cndmask_b32_e32 v30, v0, v181, vcc
	v_cndmask_b32_e64 v28, v179, v184, s[40:41]
	v_cndmask_b32_e64 v26, v182, v185, s[42:43]
	v_cndmask_b32_e64 v0, v180, v186, s[44:45]
	s_waitcnt lgkmcnt(0)
	s_barrier
	ds_read_b128 v[138:141], v178 offset:24576
	ds_read_b128 v[142:145], v178 offset:25600
	ds_read_b128 v[146:149], v178 offset:26624
	ds_read_b128 v[150:153], v178 offset:27648
	ds_read_b128 v[154:157], v183 offset:32768
	ds_read_b128 v[158:161], v183 offset:33792
	ds_read_b128 v[162:165], v183 offset:34816
	ds_read_b128 v[166:169], v183 offset:35840
	ds_read_b128 v[170:173], v183 offset:36864
	ds_read_b128 v[174:177], v183 offset:37888
	ds_read_b128 v[178:181], v183 offset:38912
	ds_read_b128 v[182:185], v183 offset:39936
	s_waitcnt lgkmcnt(7)
	v_mfma_f32_16x16x32_bf16 v[32:35], v[154:157], v[138:141], v[34:37]
	v_mfma_f32_16x16x32_bf16 v[36:39], v[154:157], v[142:145], v[38:41]
	v_mfma_f32_16x16x32_bf16 v[40:43], v[154:157], v[146:149], v[42:45]
	v_mfma_f32_16x16x32_bf16 v[44:47], v[154:157], v[150:153], v[46:49]
	s_waitcnt lgkmcnt(6)
	v_mfma_f32_16x16x32_bf16 v[48:51], v[158:161], v[138:141], v[50:53]
	v_mfma_f32_16x16x32_bf16 v[52:55], v[158:161], v[142:145], v[54:57]
	v_mfma_f32_16x16x32_bf16 v[56:59], v[158:161], v[146:149], v[58:61]
	v_mfma_f32_16x16x32_bf16 v[60:63], v[158:161], v[150:153], v[62:65]
	s_waitcnt lgkmcnt(5)
	v_mfma_f32_16x16x32_bf16 v[64:67], v[162:165], v[138:141], v[66:69]
	v_mfma_f32_16x16x32_bf16 v[68:71], v[162:165], v[142:145], v[70:73]
	v_mfma_f32_16x16x32_bf16 v[72:75], v[162:165], v[146:149], v[74:77]
	v_mfma_f32_16x16x32_bf16 v[154:157], v[162:165], v[150:153], v[22:25]
	s_waitcnt lgkmcnt(4)
	v_mfma_f32_16x16x32_bf16 v[76:79], v[166:169], v[138:141], v[78:81]
	v_mfma_f32_16x16x32_bf16 v[80:83], v[166:169], v[142:145], v[82:85]
	v_mfma_f32_16x16x32_bf16 v[84:87], v[166:169], v[146:149], v[86:89]
	v_mfma_f32_16x16x32_bf16 v[158:161], v[166:169], v[150:153], v[18:21]
	s_waitcnt lgkmcnt(3)
	v_mfma_f32_16x16x32_bf16 v[88:91], v[170:173], v[138:141], v[90:93]
	v_mfma_f32_16x16x32_bf16 v[92:95], v[170:173], v[142:145], v[94:97]
	v_mfma_f32_16x16x32_bf16 v[96:99], v[170:173], v[146:149], v[98:101]
	v_mfma_f32_16x16x32_bf16 v[162:165], v[170:173], v[150:153], v[14:17]
	s_waitcnt lgkmcnt(2)
	v_mfma_f32_16x16x32_bf16 v[100:103], v[174:177], v[138:141], v[102:105]
	v_mfma_f32_16x16x32_bf16 v[104:107], v[174:177], v[142:145], v[106:109]
	v_mfma_f32_16x16x32_bf16 v[108:111], v[174:177], v[146:149], v[110:113]
	v_mfma_f32_16x16x32_bf16 v[166:169], v[174:177], v[150:153], v[10:13]
	s_waitcnt lgkmcnt(1)
	v_mfma_f32_16x16x32_bf16 v[112:115], v[178:181], v[138:141], v[114:117]
	v_mfma_f32_16x16x32_bf16 v[116:119], v[178:181], v[142:145], v[118:121]
	v_mfma_f32_16x16x32_bf16 v[22:25], v[178:181], v[146:149], v[122:125]
	v_mfma_f32_16x16x32_bf16 v[18:21], v[178:181], v[150:153], v[6:9]
	s_waitcnt lgkmcnt(0)
	v_mfma_f32_16x16x32_bf16 v[14:17], v[182:185], v[138:141], v[126:129]
	v_mfma_f32_16x16x32_bf16 v[10:13], v[182:185], v[142:145], v[130:133]
	v_mfma_f32_16x16x32_bf16 v[6:9], v[182:185], v[146:149], v[134:137]
	v_mfma_f32_16x16x32_bf16 v[2:5], v[182:185], v[150:153], v[2:5]
	v_mov_b32_e32 v27, v224
	s_movk_i32 s0, 0x210
	v_lshrrev_b32_e32 v120, 1, v27
	v_and_b32_e32 v31, 0x7fffff80, v27
	v_and_b32_e32 v120, 24, v120
	v_and_b32_e32 v29, 0x4f, v27
	v_lshl_or_b32 v31, v31, 1, v120
	v_pk_mul_f32 v[32:33], v[30:31], v[32:33] op_sel_hi:[0,1]
	v_pk_mul_f32 v[34:35], v[30:31], v[34:35] op_sel_hi:[0,1]
	v_mad_u32_u24 v29, v29, s0, v31
	v_cvt_pk_bf16_f32 v32, v32, v33
	v_cvt_pk_bf16_f32 v33, v34, v35
	v_pk_mul_f32 v[34:35], v[28:29], v[36:37] op_sel_hi:[0,1]
	v_pk_mul_f32 v[36:37], v[28:29], v[38:39] op_sel_hi:[0,1]
	v_cvt_pk_bf16_f32 v34, v34, v35
	v_cvt_pk_bf16_f32 v35, v36, v37
	v_pk_mul_f32 v[36:37], v[26:27], v[40:41] op_sel_hi:[0,1]
	v_pk_mul_f32 v[38:39], v[26:27], v[42:43] op_sel_hi:[0,1]
	v_cvt_pk_bf16_f32 v36, v36, v37
	v_cvt_pk_bf16_f32 v37, v38, v39
	v_pk_mul_f32 v[38:39], v[0:1], v[44:45] op_sel_hi:[0,1]
	v_pk_mul_f32 v[40:41], v[0:1], v[46:47] op_sel_hi:[0,1]
	v_cvt_pk_bf16_f32 v38, v38, v39
	v_cvt_pk_bf16_f32 v39, v40, v41
	v_pk_mul_f32 v[40:41], v[30:31], v[48:49] op_sel_hi:[0,1]
	v_pk_mul_f32 v[42:43], v[30:31], v[50:51] op_sel_hi:[0,1]
	v_cvt_pk_bf16_f32 v40, v40, v41
	v_cvt_pk_bf16_f32 v41, v42, v43
	s_barrier
	ds_write2_b64 v29, v[32:33], v[40:41] offset1:4
	v_pk_mul_f32 v[32:33], v[28:29], v[52:53] op_sel_hi:[0,1]
	v_pk_mul_f32 v[40:41], v[28:29], v[54:55] op_sel_hi:[0,1]
	v_cvt_pk_bf16_f32 v32, v32, v33
	v_cvt_pk_bf16_f32 v33, v40, v41
	v_add_u32_e32 v31, 0x2000, v29
	ds_write2_b64 v31, v[34:35], v[32:33] offset0:32 offset1:36
	v_pk_mul_f32 v[32:33], v[26:27], v[56:57] op_sel_hi:[0,1]
	v_pk_mul_f32 v[34:35], v[26:27], v[58:59] op_sel_hi:[0,1]
	v_cvt_pk_bf16_f32 v32, v32, v33
	v_cvt_pk_bf16_f32 v33, v34, v35
	v_add_u32_e32 v44, 0x4000, v29
	ds_write2_b64 v44, v[36:37], v[32:33] offset0:64 offset1:68
	v_pk_mul_f32 v[32:33], v[0:1], v[60:61] op_sel_hi:[0,1]
	v_pk_mul_f32 v[34:35], v[0:1], v[62:63] op_sel_hi:[0,1]
	v_cvt_pk_bf16_f32 v32, v32, v33
	v_cvt_pk_bf16_f32 v33, v34, v35
	v_add_u32_e32 v45, 0x6000, v29
	ds_write2_b64 v45, v[38:39], v[32:33] offset0:96 offset1:100
	v_pk_mul_f32 v[32:33], v[30:31], v[64:65] op_sel_hi:[0,1]
	v_pk_mul_f32 v[34:35], v[30:31], v[66:67] op_sel_hi:[0,1]
	v_cvt_pk_bf16_f32 v32, v32, v33
	v_cvt_pk_bf16_f32 v33, v34, v35
	v_pk_mul_f32 v[34:35], v[28:29], v[68:69] op_sel_hi:[0,1]
	v_pk_mul_f32 v[36:37], v[28:29], v[70:71] op_sel_hi:[0,1]
	v_cvt_pk_bf16_f32 v34, v34, v35
	v_cvt_pk_bf16_f32 v35, v36, v37
	v_pk_mul_f32 v[36:37], v[26:27], v[72:73] op_sel_hi:[0,1]
	v_pk_mul_f32 v[38:39], v[26:27], v[74:75] op_sel_hi:[0,1]
	v_cvt_pk_bf16_f32 v36, v36, v37
	v_cvt_pk_bf16_f32 v37, v38, v39
	v_pk_mul_f32 v[38:39], v[0:1], v[154:155] op_sel_hi:[0,1]
	v_pk_mul_f32 v[40:41], v[0:1], v[156:157] op_sel_hi:[0,1]
	v_cvt_pk_bf16_f32 v38, v38, v39
	v_cvt_pk_bf16_f32 v39, v40, v41
	v_pk_mul_f32 v[40:41], v[30:31], v[76:77] op_sel_hi:[0,1]
	v_pk_mul_f32 v[42:43], v[30:31], v[78:79] op_sel_hi:[0,1]
	v_cvt_pk_bf16_f32 v40, v40, v41
	v_cvt_pk_bf16_f32 v41, v42, v43
	ds_write2_b64 v29, v[32:33], v[40:41] offset0:8 offset1:12
	v_pk_mul_f32 v[32:33], v[28:29], v[80:81] op_sel_hi:[0,1]
	v_pk_mul_f32 v[40:41], v[28:29], v[82:83] op_sel_hi:[0,1]
	v_cvt_pk_bf16_f32 v32, v32, v33
	v_cvt_pk_bf16_f32 v33, v40, v41
	ds_write2_b64 v31, v[34:35], v[32:33] offset0:40 offset1:44
	v_pk_mul_f32 v[32:33], v[26:27], v[84:85] op_sel_hi:[0,1]
	v_pk_mul_f32 v[34:35], v[26:27], v[86:87] op_sel_hi:[0,1]
	v_cvt_pk_bf16_f32 v32, v32, v33
	v_cvt_pk_bf16_f32 v33, v34, v35
	ds_write2_b64 v44, v[36:37], v[32:33] offset0:72 offset1:76
	v_pk_mul_f32 v[32:33], v[0:1], v[158:159] op_sel_hi:[0,1]
	v_pk_mul_f32 v[34:35], v[0:1], v[160:161] op_sel_hi:[0,1]
	v_cvt_pk_bf16_f32 v32, v32, v33
	v_cvt_pk_bf16_f32 v33, v34, v35
	ds_write2_b64 v45, v[38:39], v[32:33] offset0:104 offset1:108
	v_pk_mul_f32 v[32:33], v[30:31], v[88:89] op_sel_hi:[0,1]
	v_pk_mul_f32 v[34:35], v[30:31], v[90:91] op_sel_hi:[0,1]
	v_cvt_pk_bf16_f32 v32, v32, v33
	v_cvt_pk_bf16_f32 v33, v34, v35
	v_pk_mul_f32 v[34:35], v[28:29], v[92:93] op_sel_hi:[0,1]
	v_pk_mul_f32 v[36:37], v[28:29], v[94:95] op_sel_hi:[0,1]
	v_cvt_pk_bf16_f32 v34, v34, v35
	v_cvt_pk_bf16_f32 v35, v36, v37
	v_pk_mul_f32 v[36:37], v[26:27], v[96:97] op_sel_hi:[0,1]
	v_pk_mul_f32 v[38:39], v[26:27], v[98:99] op_sel_hi:[0,1]
	v_cvt_pk_bf16_f32 v36, v36, v37
	v_cvt_pk_bf16_f32 v37, v38, v39
	v_pk_mul_f32 v[38:39], v[0:1], v[162:163] op_sel_hi:[0,1]
	v_pk_mul_f32 v[40:41], v[0:1], v[164:165] op_sel_hi:[0,1]
	v_cvt_pk_bf16_f32 v38, v38, v39
	v_cvt_pk_bf16_f32 v39, v40, v41
	v_pk_mul_f32 v[40:41], v[30:31], v[100:101] op_sel_hi:[0,1]
	v_pk_mul_f32 v[42:43], v[30:31], v[102:103] op_sel_hi:[0,1]
	v_cvt_pk_bf16_f32 v40, v40, v41
	v_cvt_pk_bf16_f32 v41, v42, v43
	ds_write2_b64 v29, v[32:33], v[40:41] offset0:16 offset1:20
	v_pk_mul_f32 v[32:33], v[28:29], v[104:105] op_sel_hi:[0,1]
	v_pk_mul_f32 v[40:41], v[28:29], v[106:107] op_sel_hi:[0,1]
	v_cvt_pk_bf16_f32 v32, v32, v33
	v_cvt_pk_bf16_f32 v33, v40, v41
	ds_write2_b64 v31, v[34:35], v[32:33] offset0:48 offset1:52
	v_pk_mul_f32 v[32:33], v[26:27], v[108:109] op_sel_hi:[0,1]
	v_pk_mul_f32 v[34:35], v[26:27], v[110:111] op_sel_hi:[0,1]
	v_cvt_pk_bf16_f32 v32, v32, v33
	v_cvt_pk_bf16_f32 v33, v34, v35
	ds_write2_b64 v44, v[36:37], v[32:33] offset0:80 offset1:84
	v_pk_mul_f32 v[32:33], v[0:1], v[166:167] op_sel_hi:[0,1]
	v_pk_mul_f32 v[34:35], v[0:1], v[168:169] op_sel_hi:[0,1]
	v_cvt_pk_bf16_f32 v32, v32, v33
	v_cvt_pk_bf16_f32 v33, v34, v35
	v_pk_mul_f32 v[18:19], v[0:1], v[18:19] op_sel_hi:[0,1]
	v_pk_mul_f32 v[20:21], v[0:1], v[20:21] op_sel_hi:[0,1]
	v_pk_mul_f32 v[2:3], v[0:1], v[2:3] op_sel_hi:[0,1]
	v_pk_mul_f32 v[4:5], v[0:1], v[4:5] op_sel_hi:[0,1]
	v_lshlrev_b32_e32 v0, 3, v27
	ds_write2_b64 v45, v[38:39], v[32:33] offset0:112 offset1:116
	v_pk_mul_f32 v[32:33], v[30:31], v[112:113] op_sel_hi:[0,1]
	v_pk_mul_f32 v[34:35], v[30:31], v[114:115] op_sel_hi:[0,1]
	v_cvt_pk_bf16_f32 v18, v18, v19
	v_cvt_pk_bf16_f32 v19, v20, v21
	v_cvt_pk_bf16_f32 v2, v2, v3
	v_cvt_pk_bf16_f32 v3, v4, v5
	v_and_b32_e32 v0, 0xf8, v0
	v_cvt_pk_bf16_f32 v32, v32, v33
	v_cvt_pk_bf16_f32 v33, v34, v35
	v_pk_mul_f32 v[34:35], v[28:29], v[116:117] op_sel_hi:[0,1]
	v_pk_mul_f32 v[36:37], v[28:29], v[118:119] op_sel_hi:[0,1]
	v_pk_mul_f32 v[22:23], v[26:27], v[22:23] op_sel_hi:[0,1]
	v_pk_mul_f32 v[24:25], v[26:27], v[24:25] op_sel_hi:[0,1]
	v_pk_mul_f32 v[14:15], v[30:31], v[14:15] op_sel_hi:[0,1]
	v_pk_mul_f32 v[16:17], v[30:31], v[16:17] op_sel_hi:[0,1]
	v_pk_mul_f32 v[10:11], v[28:29], v[10:11] op_sel_hi:[0,1]
	v_pk_mul_f32 v[12:13], v[28:29], v[12:13] op_sel_hi:[0,1]
	v_pk_mul_f32 v[6:7], v[26:27], v[6:7] op_sel_hi:[0,1]
	v_pk_mul_f32 v[8:9], v[26:27], v[8:9] op_sel_hi:[0,1]
	ds_write2_b64 v45, v[18:19], v[2:3] offset0:120 offset1:124
	v_or_b32_e32 v2, s82, v0
	s_movk_i32 s0, 0x800
	v_cvt_pk_bf16_f32 v34, v34, v35
	v_cvt_pk_bf16_f32 v35, v36, v37
	v_cvt_pk_bf16_f32 v22, v22, v23
	v_cvt_pk_bf16_f32 v23, v24, v25
	v_cvt_pk_bf16_f32 v14, v14, v15
	v_cvt_pk_bf16_f32 v15, v16, v17
	v_cvt_pk_bf16_f32 v10, v10, v11
	v_cvt_pk_bf16_f32 v11, v12, v13
	v_cvt_pk_bf16_f32 v6, v6, v7
	v_cvt_pk_bf16_f32 v7, v8, v9
	v_cmp_gt_i32_e64 s[44:45], s0, v2
	s_mov_b64 s[12:13], 12
	s_mov_b64 s[40:41], s[54:55]
	s_mov_b32 s0, s82
	ds_write2_b64 v29, v[32:33], v[14:15] offset0:24 offset1:28
	ds_write2_b64 v31, v[34:35], v[10:11] offset0:56 offset1:60
	ds_write2_b64 v44, v[22:23], v[6:7] offset0:88 offset1:92
	s_waitcnt lgkmcnt(0)
	s_barrier

.LBB0_119:
	s_mul_i32 s68, s1, 0x6000
	s_add_i32 s69, s68, 0xffffa000
	s_cmp_gt_i32 s1, 0
	s_waitcnt vmcnt(6)
	s_cselect_b32 s69, s69, 0xc000
	s_waitcnt lgkmcnt(0)
	s_barrier
	s_setprio 2
	v_or_b32_e32 v0, s68, v146
	v_add_u32_e32 v0, v0, v144
	ds_read_b128 v[148:151], v0
	ds_read_b128 v[152:155], v0 offset:1024
	ds_read_b128 v[156:159], v0 offset:2048
	ds_read_b128 v[160:163], v0 offset:3072
	v_add3_u32 v0, s68, v145, v144
	s_waitcnt lgkmcnt(4)
	ds_read_b128 v[164:167], v0 offset:8192
	ds_read_b128 v[168:171], v0 offset:9216
	ds_read_b128 v[172:175], v0 offset:10240
	ds_read_b128 v[176:179], v0 offset:11264
	ds_read_b128 v[180:183], v0 offset:12288
	ds_read_b128 v[184:187], v0 offset:13312
	ds_read_b128 v[188:191], v0 offset:14336
	ds_read_b128 v[192:195], v0 offset:15360
	v_lshl_add_u64 v[212:213], v[142:143], 0, s[42:43]
	v_lshl_add_u64 v[212:213], v[130:131], 1, v[212:213]
	s_add_i32 s70, s69, s15
	s_mov_b32 m0, s70
	s_nop 0
	global_load_lds_dwordx4 v[212:213], off
	v_lshl_add_u64 v[212:213], v[142:143], 0, s[42:43]
	v_lshl_add_u64 v[212:213], v[132:133], 1, v[212:213]
	s_add_i32 s70, s69, s13
	s_mov_b32 m0, s70
	s_nop 0
	global_load_lds_dwordx4 v[212:213], off
	s_add_i32 s69, s14, s69
	v_lshl_add_u64 v[212:213], v[140:141], 0, s[42:43]
	s_mov_b32 m0, s69
	s_nop 0
	global_load_lds_dwordx4 v[212:213], off
	v_lshl_add_u64 v[212:213], v[138:139], 0, s[42:43]
	s_add_i32 s70, s69, 0x400
	s_mov_b32 m0, s70
	s_nop 0
	global_load_lds_dwordx4 v[212:213], off
	v_lshl_add_u64 v[212:213], v[136:137], 0, s[42:43]
	s_add_i32 s70, s69, 0x800
	s_mov_b32 m0, s70
	s_nop 0
	global_load_lds_dwordx4 v[212:213], off
	v_lshl_add_u64 v[212:213], v[134:135], 0, s[42:43]
	s_addk_i32 s69, 0xc00
	s_mov_b32 m0, s69
	s_nop 0
	global_load_lds_dwordx4 v[212:213], off
	s_setprio 0
	s_waitcnt lgkmcnt(7)
	v_mfma_f32_16x16x32_bf16 v[126:129], v[164:167], v[148:151], v[126:129]
	v_mfma_f32_16x16x32_bf16 v[122:125], v[164:167], v[152:155], v[122:125]
	v_mfma_f32_16x16x32_bf16 v[118:121], v[164:167], v[156:159], v[118:121]
	v_mfma_f32_16x16x32_bf16 v[114:117], v[164:167], v[160:163], v[114:117]
	s_waitcnt lgkmcnt(6)
	v_mfma_f32_16x16x32_bf16 v[110:113], v[168:171], v[148:151], v[110:113]
	v_mfma_f32_16x16x32_bf16 v[106:109], v[168:171], v[152:155], v[106:109]
	v_mfma_f32_16x16x32_bf16 v[102:105], v[168:171], v[156:159], v[102:105]
	v_mfma_f32_16x16x32_bf16 v[98:101], v[168:171], v[160:163], v[98:101]
	s_waitcnt lgkmcnt(5)
	v_mfma_f32_16x16x32_bf16 v[94:97], v[172:175], v[148:151], v[94:97]
	v_mfma_f32_16x16x32_bf16 v[90:93], v[172:175], v[152:155], v[90:93]
	v_mfma_f32_16x16x32_bf16 v[86:89], v[172:175], v[156:159], v[86:89]
	v_mfma_f32_16x16x32_bf16 v[82:85], v[172:175], v[160:163], v[82:85]
	s_waitcnt lgkmcnt(4)
	v_mfma_f32_16x16x32_bf16 v[78:81], v[176:179], v[148:151], v[78:81]
	v_mfma_f32_16x16x32_bf16 v[74:77], v[176:179], v[152:155], v[74:77]
	v_mfma_f32_16x16x32_bf16 v[70:73], v[176:179], v[156:159], v[70:73]
	v_mfma_f32_16x16x32_bf16 v[66:69], v[176:179], v[160:163], v[66:69]
	s_waitcnt lgkmcnt(3)
	v_mfma_f32_16x16x32_bf16 v[62:65], v[180:183], v[148:151], v[62:65]
	v_mfma_f32_16x16x32_bf16 v[58:61], v[180:183], v[152:155], v[58:61]
	v_mfma_f32_16x16x32_bf16 v[54:57], v[180:183], v[156:159], v[54:57]
	v_mfma_f32_16x16x32_bf16 v[50:53], v[180:183], v[160:163], v[50:53]
	s_waitcnt lgkmcnt(2)
	v_mfma_f32_16x16x32_bf16 v[46:49], v[184:187], v[148:151], v[46:49]
	v_mfma_f32_16x16x32_bf16 v[42:45], v[184:187], v[152:155], v[42:45]
	v_mfma_f32_16x16x32_bf16 v[38:41], v[184:187], v[156:159], v[38:41]
	v_mfma_f32_16x16x32_bf16 v[34:37], v[184:187], v[160:163], v[34:37]
	s_waitcnt lgkmcnt(1)
	v_mfma_f32_16x16x32_bf16 v[30:33], v[188:191], v[148:151], v[30:33]
	v_mfma_f32_16x16x32_bf16 v[26:29], v[188:191], v[152:155], v[26:29]
	v_mfma_f32_16x16x32_bf16 v[22:25], v[188:191], v[156:159], v[22:25]
	v_mfma_f32_16x16x32_bf16 v[18:21], v[188:191], v[160:163], v[18:21]
	s_waitcnt lgkmcnt(0)
	v_mfma_f32_16x16x32_bf16 v[14:17], v[192:195], v[148:151], v[14:17]
	v_mfma_f32_16x16x32_bf16 v[10:13], v[192:195], v[152:155], v[10:13]
	v_mfma_f32_16x16x32_bf16 v[6:9], v[192:195], v[156:159], v[6:9]
	v_mfma_f32_16x16x32_bf16 v[2:5], v[192:195], v[160:163], v[2:5]
	s_add_i32 s68, s1, 1
	s_cmp_lg_u32 s1, 2
	s_cselect_b32 s1, s68, 0
	s_add_u32 s42, s42, 64
	s_addc_u32 s43, s43, 0
	s_cmpk_eq_i32 s42, 0x1500
	s_cbranch_scc0 .LBB0_119
	s_waitcnt vmcnt(6)
	v_add_u32_e32 v0, v146, v144
	v_add_u32_e32 v221, v145, v144
	s_waitcnt lgkmcnt(0)
	s_barrier
	ds_read_b128 v[130:133], v0
	ds_read_b128 v[134:137], v0 offset:1024
	ds_read_b128 v[138:141], v0 offset:2048
	ds_read_b128 v[146:149], v0 offset:3072
	ds_read_b128 v[142:145], v221 offset:8192
	ds_read_b128 v[150:153], v221 offset:9216
	ds_read_b128 v[154:157], v221 offset:10240
	ds_read_b128 v[158:161], v221 offset:11264
	ds_read_b128 v[162:165], v221 offset:12288
	ds_read_b128 v[166:169], v221 offset:13312
	ds_read_b128 v[170:173], v221 offset:14336
	ds_read_b128 v[174:177], v221 offset:15360
	s_waitcnt lgkmcnt(7)
	v_mfma_f32_16x16x32_bf16 v[126:129], v[142:145], v[130:133], v[126:129]
	v_mfma_f32_16x16x32_bf16 v[122:125], v[142:145], v[134:137], v[122:125]
	v_mfma_f32_16x16x32_bf16 v[118:121], v[142:145], v[138:141], v[118:121]
	v_mfma_f32_16x16x32_bf16 v[114:117], v[142:145], v[146:149], v[114:117]
	s_waitcnt lgkmcnt(6)
	v_mfma_f32_16x16x32_bf16 v[110:113], v[150:153], v[130:133], v[110:113]
	v_mfma_f32_16x16x32_bf16 v[106:109], v[150:153], v[134:137], v[106:109]
	v_mfma_f32_16x16x32_bf16 v[102:105], v[150:153], v[138:141], v[102:105]
	v_mfma_f32_16x16x32_bf16 v[98:101], v[150:153], v[146:149], v[98:101]
	s_waitcnt lgkmcnt(5)
	v_mfma_f32_16x16x32_bf16 v[94:97], v[154:157], v[130:133], v[94:97]
	v_mfma_f32_16x16x32_bf16 v[90:93], v[154:157], v[134:137], v[90:93]
	v_mfma_f32_16x16x32_bf16 v[86:89], v[154:157], v[138:141], v[86:89]
	v_mfma_f32_16x16x32_bf16 v[82:85], v[154:157], v[146:149], v[82:85]
	s_waitcnt lgkmcnt(4)
	v_mfma_f32_16x16x32_bf16 v[78:81], v[158:161], v[130:133], v[78:81]
	v_mfma_f32_16x16x32_bf16 v[74:77], v[158:161], v[134:137], v[74:77]
	v_mfma_f32_16x16x32_bf16 v[70:73], v[158:161], v[138:141], v[70:73]
	v_mfma_f32_16x16x32_bf16 v[66:69], v[158:161], v[146:149], v[66:69]
	s_waitcnt lgkmcnt(3)
	v_mfma_f32_16x16x32_bf16 v[142:145], v[162:165], v[130:133], v[62:65]
	v_mfma_f32_16x16x32_bf16 v[150:153], v[162:165], v[134:137], v[58:61]
	v_mfma_f32_16x16x32_bf16 v[154:157], v[162:165], v[138:141], v[54:57]
	v_mfma_f32_16x16x32_bf16 v[158:161], v[162:165], v[146:149], v[50:53]
	s_waitcnt lgkmcnt(2)
	v_mfma_f32_16x16x32_bf16 v[162:165], v[166:169], v[130:133], v[46:49]
	v_mfma_f32_16x16x32_bf16 v[178:181], v[166:169], v[134:137], v[42:45]
	v_mfma_f32_16x16x32_bf16 v[182:185], v[166:169], v[138:141], v[38:41]
	v_mfma_f32_16x16x32_bf16 v[166:169], v[166:169], v[146:149], v[34:37]
	s_waitcnt lgkmcnt(1)
	v_mfma_f32_16x16x32_bf16 v[186:189], v[170:173], v[130:133], v[30:33]
	v_mfma_f32_16x16x32_bf16 v[190:193], v[170:173], v[134:137], v[26:29]
	v_mfma_f32_16x16x32_bf16 v[194:197], v[170:173], v[138:141], v[22:25]
	v_mfma_f32_16x16x32_bf16 v[170:173], v[170:173], v[146:149], v[18:21]
	s_waitcnt lgkmcnt(0)
	v_mfma_f32_16x16x32_bf16 v[130:133], v[174:177], v[130:133], v[14:17]
	v_mfma_f32_16x16x32_bf16 v[134:137], v[174:177], v[134:137], v[10:13]
	v_mfma_f32_16x16x32_bf16 v[138:141], v[174:177], v[138:141], v[6:9]
	v_mfma_f32_16x16x32_bf16 v[146:149], v[174:177], v[146:149], v[2:5]
	s_waitcnt vmcnt(0)
	s_waitcnt lgkmcnt(0)
	s_barrier
	ds_read_b128 v[174:177], v0 offset:24576
	ds_read_b128 v[198:201], v0 offset:25600
	ds_read_b128 v[202:205], v0 offset:26624
	ds_read_b128 v[206:209], v0 offset:27648
	ds_read_b128 v[14:17], v221 offset:32768
	ds_read_b128 v[30:33], v221 offset:33792
	ds_read_b128 v[46:49], v221 offset:34816
	ds_read_b128 v[62:65], v221 offset:35840
	ds_read_b128 v[210:213], v221 offset:36864
	ds_read_b128 v[216:219], v221 offset:37888
	ds_read_b128 v[226:229], v221 offset:38912
	ds_read_b128 v[230:233], v221 offset:39936
	s_waitcnt lgkmcnt(7)
	v_mfma_f32_16x16x32_bf16 v[2:5], v[14:17], v[174:177], v[126:129]
	v_mfma_f32_16x16x32_bf16 v[6:9], v[14:17], v[198:201], v[122:125]
	v_mfma_f32_16x16x32_bf16 v[10:13], v[14:17], v[202:205], v[118:121]
	v_mfma_f32_16x16x32_bf16 v[14:17], v[14:17], v[206:209], v[114:117]
	s_waitcnt lgkmcnt(6)
	v_mfma_f32_16x16x32_bf16 v[18:21], v[30:33], v[174:177], v[110:113]
	v_mfma_f32_16x16x32_bf16 v[22:25], v[30:33], v[198:201], v[106:109]
	v_mfma_f32_16x16x32_bf16 v[26:29], v[30:33], v[202:205], v[102:105]
	v_mfma_f32_16x16x32_bf16 v[30:33], v[30:33], v[206:209], v[98:101]
	s_waitcnt lgkmcnt(5)
	v_mfma_f32_16x16x32_bf16 v[34:37], v[46:49], v[174:177], v[94:97]
	v_mfma_f32_16x16x32_bf16 v[38:41], v[46:49], v[198:201], v[90:93]
	v_mfma_f32_16x16x32_bf16 v[42:45], v[46:49], v[202:205], v[86:89]
	v_mfma_f32_16x16x32_bf16 v[46:49], v[46:49], v[206:209], v[82:85]
	s_waitcnt lgkmcnt(4)
	v_mfma_f32_16x16x32_bf16 v[50:53], v[62:65], v[174:177], v[78:81]
	v_mfma_f32_16x16x32_bf16 v[54:57], v[62:65], v[198:201], v[74:77]
	v_mfma_f32_16x16x32_bf16 v[58:61], v[62:65], v[202:205], v[70:73]
	v_mfma_f32_16x16x32_bf16 v[62:65], v[62:65], v[206:209], v[66:69]
	s_waitcnt lgkmcnt(3)
	v_mfma_f32_16x16x32_bf16 v[66:69], v[210:213], v[174:177], v[142:145]
	v_mfma_f32_16x16x32_bf16 v[70:73], v[210:213], v[198:201], v[150:153]
	v_mfma_f32_16x16x32_bf16 v[74:77], v[210:213], v[202:205], v[154:157]
	v_mfma_f32_16x16x32_bf16 v[78:81], v[210:213], v[206:209], v[158:161]
	s_waitcnt lgkmcnt(2)
	v_mfma_f32_16x16x32_bf16 v[82:85], v[216:219], v[174:177], v[162:165]
	v_mfma_f32_16x16x32_bf16 v[86:89], v[216:219], v[198:201], v[178:181]
	v_mfma_f32_16x16x32_bf16 v[90:93], v[216:219], v[202:205], v[182:185]
	v_mfma_f32_16x16x32_bf16 v[94:97], v[216:219], v[206:209], v[166:169]
	s_waitcnt lgkmcnt(1)
	v_mfma_f32_16x16x32_bf16 v[98:101], v[226:229], v[174:177], v[186:189]
	v_mfma_f32_16x16x32_bf16 v[102:105], v[226:229], v[198:201], v[190:193]
	v_mfma_f32_16x16x32_bf16 v[106:109], v[226:229], v[202:205], v[194:197]
	v_mfma_f32_16x16x32_bf16 v[110:113], v[226:229], v[206:209], v[170:173]
	s_waitcnt lgkmcnt(0)
	v_mfma_f32_16x16x32_bf16 v[114:117], v[230:233], v[174:177], v[130:133]
	v_mfma_f32_16x16x32_bf16 v[118:121], v[230:233], v[198:201], v[134:137]
	v_mfma_f32_16x16x32_bf16 v[122:125], v[230:233], v[202:205], v[138:141]
	v_mfma_f32_16x16x32_bf16 v[126:129], v[230:233], v[206:209], v[146:149]
	v_mov_b32_e32 v130, v224
	s_ashr_i32 s13, s12, 31
	v_and_b32_e32 v131, 31, v130
	v_ashrrev_i32_e32 v197, 7, v130
	v_ashrrev_i32_e32 v132, 5, v130
	v_lshlrev_b32_e32 v0, 2, v131
	s_lshl_b64 s[68:69], s[12:13], 11
	v_lshlrev_b32_e32 v164, 4, v131
	v_cmp_eq_u32_e64 s[42:43], 0, v131
	v_and_b32_e32 v131, 0x4f, v130
	v_and_b32_e32 v130, 48, v130
	s_movk_i32 s13, 0x210
	v_cmp_lt_i32_e32 vcc, v247, v214
	v_mad_u32_u24 v202, v131, s13, v130
	s_ashr_i32 s1, s0, 31
	v_cndmask_b32_e32 v130, v225, v247, vcc
	v_cmp_lt_i32_e32 vcc, v248, v214
	v_lshlrev_b32_e32 v203, 2, v130
	s_lshl_b32 s70, s87, 1
	v_cndmask_b32_e32 v130, v225, v248, vcc
	v_cmp_lt_i32_e32 vcc, v249, v214
	v_lshlrev_b32_e32 v204, 2, v130
	v_lshl_or_b32 v0, v132, 10, v0
	v_cndmask_b32_e32 v130, v225, v249, vcc
	v_cmp_lt_i32_e32 vcc, v223, v214
	v_lshlrev_b32_e32 v205, 2, v130
	v_mul_lo_u32 v165, v132, s13
	v_cndmask_b32_e32 v130, v225, v223, vcc
	v_cmp_lt_i32_e32 vcc, v252, v214
	v_lshlrev_b32_e32 v206, 2, v130
	s_mov_b32 s14, 0
	v_cndmask_b32_e32 v130, v225, v252, vcc
	v_lshlrev_b32_e32 v207, 2, v130
	v_add_u32_e32 v130, s12, v132
	v_ashrrev_i32_e32 v131, 31, v130
	s_add_u32 s12, s74, s68
	v_lshlrev_b64 v[132:133], 5, v[130:131]
	v_add_u32_e32 v134, 8, v130
	v_add_u32_e32 v136, 16, v130
	v_add_u32_e32 v138, 24, v130
	v_add_u32_e32 v140, 32, v130
	v_add_u32_e32 v142, 40, v130
	v_add_u32_e32 v144, 48, v130
	v_add_u32_e32 v146, 56, v130
	v_add_u32_e32 v148, 64, v130
	v_add_u32_e32 v150, 0x48, v130
	v_add_u32_e32 v152, 0x50, v130
	v_add_u32_e32 v154, 0x58, v130
	v_add_u32_e32 v156, 0x60, v130
	v_add_u32_e32 v158, 0x68, v130
	v_add_u32_e32 v160, 0x70, v130
	v_add_u32_e32 v130, 0x78, v130
	s_addc_u32 s13, s75, s69
	s_lshl_b64 s[0:1], s[0:1], 1
	v_ashrrev_i32_e32 v135, 31, v134
	v_ashrrev_i32_e32 v137, 31, v136
	v_ashrrev_i32_e32 v139, 31, v138
	v_ashrrev_i32_e32 v141, 31, v140
	v_ashrrev_i32_e32 v143, 31, v142
	v_ashrrev_i32_e32 v145, 31, v144
	v_ashrrev_i32_e32 v147, 31, v146
	v_ashrrev_i32_e32 v149, 31, v148
	v_ashrrev_i32_e32 v151, 31, v150
	v_ashrrev_i32_e32 v153, 31, v152
	v_ashrrev_i32_e32 v155, 31, v154
	v_ashrrev_i32_e32 v157, 31, v156
	v_ashrrev_i32_e32 v159, 31, v158
	v_ashrrev_i32_e32 v161, 31, v160
	v_ashrrev_i32_e32 v131, 31, v130
	s_add_u32 s0, s12, s0
	v_lshlrev_b64 v[134:135], 5, v[134:135]
	v_lshlrev_b64 v[136:137], 5, v[136:137]
	v_lshlrev_b64 v[138:139], 5, v[138:139]
	v_lshlrev_b64 v[140:141], 5, v[140:141]
	v_lshlrev_b64 v[142:143], 5, v[142:143]
	v_lshlrev_b64 v[144:145], 5, v[144:145]
	v_lshlrev_b64 v[146:147], 5, v[146:147]
	v_lshlrev_b64 v[148:149], 5, v[148:149]
	v_lshlrev_b64 v[150:151], 5, v[150:151]
	v_lshlrev_b64 v[152:153], 5, v[152:153]
	v_lshlrev_b64 v[154:155], 5, v[154:155]
	v_lshlrev_b64 v[156:157], 5, v[156:157]
	v_lshlrev_b64 v[158:159], 5, v[158:159]
	v_lshlrev_b64 v[160:161], 5, v[160:161]
	v_lshlrev_b64 v[162:163], 5, v[130:131]
	s_addc_u32 s1, s13, s1
	v_lshl_add_u64 v[130:131], v[0:1], 1, s[0:1]
	v_lshl_add_u64 v[132:133], s[44:45], 0, v[132:133]
	v_lshl_add_u64 v[134:135], s[44:45], 0, v[134:135]
	v_lshl_add_u64 v[136:137], s[44:45], 0, v[136:137]
	v_lshl_add_u64 v[138:139], s[44:45], 0, v[138:139]
	v_lshl_add_u64 v[140:141], s[44:45], 0, v[140:141]
	v_lshl_add_u64 v[142:143], s[44:45], 0, v[142:143]
	v_lshl_add_u64 v[144:145], s[44:45], 0, v[144:145]
	v_lshl_add_u64 v[146:147], s[44:45], 0, v[146:147]
	v_lshl_add_u64 v[148:149], s[44:45], 0, v[148:149]
	v_lshl_add_u64 v[150:151], s[44:45], 0, v[150:151]
	v_lshl_add_u64 v[152:153], s[44:45], 0, v[152:153]
	v_lshl_add_u64 v[154:155], s[44:45], 0, v[154:155]
	v_lshl_add_u64 v[156:157], s[44:45], 0, v[156:157]
	v_lshl_add_u64 v[158:159], s[44:45], 0, v[158:159]
	v_lshl_add_u64 v[160:161], s[44:45], 0, v[160:161]
	v_lshl_add_u64 v[162:163], s[44:45], 0, v[162:163]
	s_mov_b64 s[0:1], -1
	v_add_u32_e32 v0, v164, v165
	s_branch .LBB0_122

.LBB0_167:
	s_mul_i32 s4, s43, 0x6000
	s_add_i32 s5, s4, 0xffffa000
	s_cmp_gt_i32 s43, 0
	s_waitcnt vmcnt(6)
	s_cselect_b32 s5, s5, 0xc000
	s_waitcnt lgkmcnt(0)
	s_barrier
	s_setprio 2
	v_add3_u32 v0, s4, v177, v176
	v_add_u32_e32 v0, s47, v0
	ds_read_b128 v[180:183], v0
	ds_read_b128 v[184:187], v0 offset:1024
	ds_read_b128 v[188:191], v0 offset:2048
	ds_read_b128 v[192:195], v0 offset:3072
	v_add3_u32 v0, s4, v178, v176
	ds_read_b128 v[196:199], v0 offset:8192
	ds_read_b128 v[200:203], v0 offset:9216
	ds_read_b128 v[204:207], v0 offset:10240
	ds_read_b128 v[208:211], v0 offset:11264
	ds_read_b128 v[216:219], v0 offset:12288
	ds_read_b128 v[226:229], v0 offset:13312
	ds_read_b128 v[230:233], v0 offset:14336
	ds_read_b128 v[234:237], v0 offset:15360
	v_lshl_add_u64 v[212:213], v[174:175], 0, s[12:13]
	v_lshl_add_u64 v[212:213], v[162:163], 1, v[212:213]
	s_add_i32 s44, s5, s42
	s_mov_b32 m0, s44
	s_nop 0
	global_load_lds_dwordx4 v[212:213], off
	v_lshl_add_u64 v[212:213], v[174:175], 0, s[12:13]
	v_lshl_add_u64 v[212:213], v[164:165], 1, v[212:213]
	s_add_i32 s44, s5, s40
	s_mov_b32 m0, s44
	s_nop 0
	global_load_lds_dwordx4 v[212:213], off
	s_add_i32 s5, s41, s5
	v_lshl_add_u64 v[212:213], v[172:173], 0, s[12:13]
	s_mov_b32 m0, s5
	s_nop 0
	global_load_lds_dwordx4 v[212:213], off
	v_lshl_add_u64 v[212:213], v[170:171], 0, s[12:13]
	s_add_i32 s44, s5, 0x400
	s_mov_b32 m0, s44
	s_nop 0
	global_load_lds_dwordx4 v[212:213], off
	v_lshl_add_u64 v[212:213], v[168:169], 0, s[12:13]
	s_add_i32 s44, s5, 0x800
	s_mov_b32 m0, s44
	s_nop 0
	global_load_lds_dwordx4 v[212:213], off
	s_addk_i32 s5, 0xc00
	v_lshl_add_u64 v[212:213], v[166:167], 0, s[12:13]
	s_mov_b32 m0, s5
	s_nop 0
	global_load_lds_dwordx4 v[212:213], off
	s_setprio 0
	s_waitcnt lgkmcnt(7)
	v_mfma_f32_16x16x32_bf16 v[34:37], v[196:199], v[180:183], v[34:37]
	v_mfma_f32_16x16x32_bf16 v[38:41], v[196:199], v[184:187], v[38:41]
	v_mfma_f32_16x16x32_bf16 v[42:45], v[196:199], v[188:191], v[42:45]
	v_mfma_f32_16x16x32_bf16 v[46:49], v[196:199], v[192:195], v[46:49]
	s_waitcnt lgkmcnt(6)
	v_mfma_f32_16x16x32_bf16 v[50:53], v[200:203], v[180:183], v[50:53]
	v_mfma_f32_16x16x32_bf16 v[54:57], v[200:203], v[184:187], v[54:57]
	v_mfma_f32_16x16x32_bf16 v[58:61], v[200:203], v[188:191], v[58:61]
	v_mfma_f32_16x16x32_bf16 v[62:65], v[200:203], v[192:195], v[62:65]
	s_waitcnt lgkmcnt(5)
	v_mfma_f32_16x16x32_bf16 v[66:69], v[204:207], v[180:183], v[66:69]
	v_mfma_f32_16x16x32_bf16 v[70:73], v[204:207], v[184:187], v[70:73]
	v_mfma_f32_16x16x32_bf16 v[74:77], v[204:207], v[188:191], v[74:77]
	v_mfma_f32_16x16x32_bf16 v[78:81], v[204:207], v[192:195], v[78:81]
	s_waitcnt lgkmcnt(4)
	v_mfma_f32_16x16x32_bf16 v[82:85], v[208:211], v[180:183], v[82:85]
	v_mfma_f32_16x16x32_bf16 v[86:89], v[208:211], v[184:187], v[86:89]
	v_mfma_f32_16x16x32_bf16 v[90:93], v[208:211], v[188:191], v[90:93]
	v_mfma_f32_16x16x32_bf16 v[94:97], v[208:211], v[192:195], v[94:97]
	s_waitcnt lgkmcnt(3)
	v_mfma_f32_16x16x32_bf16 v[98:101], v[216:219], v[180:183], v[98:101]
	v_mfma_f32_16x16x32_bf16 v[102:105], v[216:219], v[184:187], v[102:105]
	v_mfma_f32_16x16x32_bf16 v[106:109], v[216:219], v[188:191], v[106:109]
	v_mfma_f32_16x16x32_bf16 v[110:113], v[216:219], v[192:195], v[110:113]
	s_waitcnt lgkmcnt(2)
	v_mfma_f32_16x16x32_bf16 v[114:117], v[226:229], v[180:183], v[114:117]
	v_mfma_f32_16x16x32_bf16 v[118:121], v[226:229], v[184:187], v[118:121]
	v_mfma_f32_16x16x32_bf16 v[122:125], v[226:229], v[188:191], v[122:125]
	v_mfma_f32_16x16x32_bf16 v[126:129], v[226:229], v[192:195], v[126:129]
	s_waitcnt lgkmcnt(1)
	v_mfma_f32_16x16x32_bf16 v[130:133], v[230:233], v[180:183], v[130:133]
	v_mfma_f32_16x16x32_bf16 v[134:137], v[230:233], v[184:187], v[134:137]
	v_mfma_f32_16x16x32_bf16 v[138:141], v[230:233], v[188:191], v[138:141]
	v_mfma_f32_16x16x32_bf16 v[142:145], v[230:233], v[192:195], v[142:145]
	s_waitcnt lgkmcnt(0)
	v_mfma_f32_16x16x32_bf16 v[146:149], v[234:237], v[180:183], v[146:149]
	v_mfma_f32_16x16x32_bf16 v[150:153], v[234:237], v[184:187], v[150:153]
	v_mfma_f32_16x16x32_bf16 v[154:157], v[234:237], v[188:191], v[154:157]
	v_mfma_f32_16x16x32_bf16 v[158:161], v[234:237], v[192:195], v[158:161]
	s_add_i32 s4, s43, 1
	s_cmp_lg_u32 s43, 2
	s_cselect_b32 s43, s4, 0
	s_add_u32 s12, s12, 64
	s_addc_u32 s13, s13, 0
	s_cmpk_eq_i32 s12, 0x780
	s_cbranch_scc0 .LBB0_167
	s_waitcnt vmcnt(6)
	v_mov_b32_e32 v162, v23
	v_mov_b32_e32 v163, v24
	v_mov_b32_e32 v23, v25
	v_mov_b32_e32 v164, v7
	v_mov_b32_e32 v165, v8
	v_pk_add_f32 v[22:23], v[162:163], v[22:23]
	v_mov_b32_e32 v7, v9
	v_pk_add_f32 v[6:7], v[164:165], v[6:7]
	v_add_f32_e32 v0, v22, v23
	v_add_f32_e32 v0, v0, v6
	v_add_f32_e32 v0, v0, v7
	v_fmamk_f32 v0, v0, 0x3a800000, v250
	s_mov_b32 s4, 0x800000
	s_waitcnt vmcnt(4)
	v_mov_b32_e32 v166, v19
	v_mov_b32_e32 v167, v20
	v_mov_b32_e32 v168, v3
	v_mul_f32_e32 v3, 0x4b800000, v0
	v_cmp_gt_f32_e32 vcc, s4, v0
	v_mov_b32_e32 v19, v21
	v_mov_b32_e32 v169, v4
	v_cndmask_b32_e32 v0, v0, v3, vcc
	v_pk_add_f32 v[6:7], v[166:167], v[18:19]
	v_mov_b32_e32 v3, v5
	v_pk_add_f32 v[2:3], v[168:169], v[2:3]
	v_add_f32_e32 v4, v6, v7
	v_add_f32_e32 v2, v4, v2
	v_add_f32_e32 v2, v2, v3
	v_fmamk_f32 v2, v2, 0x3a800000, v250
	v_mul_f32_e32 v3, 0x4b800000, v2
	v_cmp_gt_f32_e64 s[40:41], s4, v2
	s_waitcnt vmcnt(2)
	v_mov_b32_e32 v170, v27
	v_mov_b32_e32 v171, v28
	v_cndmask_b32_e64 v2, v2, v3, s[40:41]
	v_mov_b32_e32 v27, v29
	v_mov_b32_e32 v172, v11
	v_mov_b32_e32 v173, v12
	v_rsq_f32_e32 v182, v2
	v_pk_add_f32 v[2:3], v[170:171], v[26:27]
	v_mov_b32_e32 v11, v13
	v_pk_add_f32 v[4:5], v[172:173], v[10:11]
	v_add_f32_e32 v2, v2, v3
	v_add_f32_e32 v2, v2, v4
	v_add_f32_e32 v2, v2, v5
	v_fmamk_f32 v2, v2, 0x3a800000, v250
	v_mul_f32_e32 v3, 0x4b800000, v2
	v_cmp_gt_f32_e64 s[42:43], s4, v2
	s_waitcnt vmcnt(0)
	v_mov_b32_e32 v174, v31
	v_mov_b32_e32 v175, v32
	v_cndmask_b32_e64 v2, v2, v3, s[42:43]
	v_mov_b32_e32 v31, v33
	v_mov_b32_e32 v180, v15
	v_mov_b32_e32 v181, v16
	v_rsq_f32_e32 v183, v2
	v_pk_add_f32 v[2:3], v[174:175], v[30:31]
	v_mov_b32_e32 v15, v17
	v_pk_add_f32 v[4:5], v[180:181], v[14:15]
	v_add_f32_e32 v2, v2, v3
	v_add_f32_e32 v2, v2, v4
	v_add_f32_e32 v2, v2, v5
	v_fmamk_f32 v2, v2, 0x3a800000, v250
	v_mul_f32_e32 v3, 0x4b800000, v2
	v_cmp_gt_f32_e64 s[44:45], s4, v2
	s_waitcnt vmcnt(6)
	v_add_u32_e32 v185, v178, v176
	s_waitcnt lgkmcnt(0)
	s_barrier
	v_cndmask_b32_e64 v2, v2, v3, s[44:45]
	v_rsq_f32_e32 v184, v2
	ds_read_b128 v[2:5], v185 offset:15360
	ds_read_b128 v[6:9], v185 offset:14336
	ds_read_b128 v[10:13], v185 offset:13312
	ds_read_b128 v[14:17], v185 offset:12288
	ds_read_b128 v[18:21], v185 offset:11264
	ds_read_b128 v[22:25], v185 offset:10240
	ds_read_b128 v[26:29], v185 offset:9216
	ds_read_b128 v[30:33], v185 offset:8192
	v_add3_u32 v186, s47, v177, v176
	ds_read_b128 v[162:165], v186 offset:3072
	ds_read_b128 v[166:169], v186 offset:2048
	ds_read_b128 v[170:173], v186 offset:1024
	ds_read_b128 v[174:177], v186
	v_rsq_f32_e32 v0, v0
	v_mul_f32_e32 v188, 0x45800000, v182
	v_mul_f32_e32 v189, 0x45800000, v183
	v_mul_f32_e32 v190, 0x45800000, v184
	v_mul_f32_e32 v187, 0x45800000, v0
	s_waitcnt lgkmcnt(0)
	v_mfma_f32_16x16x32_bf16 v[34:37], v[30:33], v[174:177], v[34:37]
	v_mfma_f32_16x16x32_bf16 v[38:41], v[30:33], v[170:173], v[38:41]
	v_mfma_f32_16x16x32_bf16 v[178:181], v[30:33], v[166:169], v[42:45]
	v_mfma_f32_16x16x32_bf16 v[30:33], v[30:33], v[162:165], v[46:49]
	v_mfma_f32_16x16x32_bf16 v[48:51], v[26:29], v[174:177], v[50:53]
	v_mfma_f32_16x16x32_bf16 v[52:55], v[26:29], v[170:173], v[54:57]
	v_mfma_f32_16x16x32_bf16 v[56:59], v[26:29], v[166:169], v[58:61]
	v_mfma_f32_16x16x32_bf16 v[26:29], v[26:29], v[162:165], v[62:65]
	v_mfma_f32_16x16x32_bf16 v[60:63], v[22:25], v[174:177], v[66:69]
	v_mfma_f32_16x16x32_bf16 v[64:67], v[22:25], v[170:173], v[70:73]
	v_mfma_f32_16x16x32_bf16 v[68:71], v[22:25], v[166:169], v[74:77]
	v_mfma_f32_16x16x32_bf16 v[22:25], v[22:25], v[162:165], v[78:81]
	v_mfma_f32_16x16x32_bf16 v[72:75], v[18:21], v[174:177], v[82:85]
	v_mfma_f32_16x16x32_bf16 v[76:79], v[18:21], v[170:173], v[86:89]
	v_mfma_f32_16x16x32_bf16 v[80:83], v[18:21], v[166:169], v[90:93]
	v_mfma_f32_16x16x32_bf16 v[18:21], v[18:21], v[162:165], v[94:97]
	v_mfma_f32_16x16x32_bf16 v[84:87], v[14:17], v[174:177], v[98:101]
	v_mfma_f32_16x16x32_bf16 v[88:91], v[14:17], v[170:173], v[102:105]
	v_mfma_f32_16x16x32_bf16 v[92:95], v[14:17], v[166:169], v[106:109]
	v_mfma_f32_16x16x32_bf16 v[14:17], v[14:17], v[162:165], v[110:113]
	v_mfma_f32_16x16x32_bf16 v[96:99], v[10:13], v[174:177], v[114:117]
	v_mfma_f32_16x16x32_bf16 v[100:103], v[10:13], v[170:173], v[118:121]
	v_mfma_f32_16x16x32_bf16 v[104:107], v[10:13], v[166:169], v[122:125]
	v_mfma_f32_16x16x32_bf16 v[10:13], v[10:13], v[162:165], v[126:129]
	v_mfma_f32_16x16x32_bf16 v[108:111], v[6:9], v[174:177], v[130:133]
	v_mfma_f32_16x16x32_bf16 v[112:115], v[6:9], v[170:173], v[134:137]
	v_mfma_f32_16x16x32_bf16 v[116:119], v[6:9], v[166:169], v[138:141]
	v_mfma_f32_16x16x32_bf16 v[120:123], v[2:5], v[174:177], v[146:149]
	v_mfma_f32_16x16x32_bf16 v[124:127], v[2:5], v[170:173], v[150:153]
	v_mfma_f32_16x16x32_bf16 v[128:131], v[2:5], v[166:169], v[154:157]
	v_mfma_f32_16x16x32_bf16 v[6:9], v[6:9], v[162:165], v[142:145]
	v_mfma_f32_16x16x32_bf16 v[2:5], v[2:5], v[162:165], v[158:161]
	s_waitcnt vmcnt(0)
	v_cndmask_b32_e32 v46, v0, v187, vcc
	v_cndmask_b32_e64 v44, v182, v188, s[40:41]
	v_cndmask_b32_e64 v42, v183, v189, s[42:43]
	v_cndmask_b32_e64 v0, v184, v190, s[44:45]
	s_waitcnt lgkmcnt(0)
	s_barrier
	ds_read_b128 v[132:135], v186 offset:24576
	ds_read_b128 v[136:139], v186 offset:25600
	ds_read_b128 v[140:143], v186 offset:26624
	ds_read_b128 v[144:147], v186 offset:27648
	ds_read_b128 v[148:151], v185 offset:32768
	ds_read_b128 v[152:155], v185 offset:33792
	ds_read_b128 v[156:159], v185 offset:34816
	ds_read_b128 v[160:163], v185 offset:35840
	ds_read_b128 v[164:167], v185 offset:36864
	ds_read_b128 v[168:171], v185 offset:37888
	ds_read_b128 v[172:175], v185 offset:38912
	ds_read_b128 v[182:185], v185 offset:39936
	s_waitcnt lgkmcnt(4)
	v_mfma_f32_16x16x32_bf16 v[242:245], v[160:163], v[140:143], v[80:83]
	v_mfma_f32_16x16x32_bf16 v[246:249], v[160:163], v[144:147], v[18:21]
	s_waitcnt lgkmcnt(3)
	v_mfma_f32_16x16x32_bf16 v[210:213], v[164:167], v[132:135], v[84:87]
	v_mfma_f32_16x16x32_bf16 v[194:197], v[164:167], v[136:139], v[88:91]
	v_mfma_f32_16x16x32_bf16 v[206:209], v[164:167], v[140:143], v[92:95]
	v_mfma_f32_16x16x32_bf16 v[164:167], v[164:167], v[144:147], v[14:17]
	v_mfma_f32_16x16x32_bf16 v[186:189], v[148:151], v[132:135], v[34:37]
	v_mfma_f32_16x16x32_bf16 v[190:193], v[148:151], v[136:139], v[38:41]
	v_mfma_f32_16x16x32_bf16 v[176:179], v[148:151], v[140:143], v[178:181]
	v_mfma_f32_16x16x32_bf16 v[198:201], v[148:151], v[144:147], v[30:33]
	v_mfma_f32_16x16x32_bf16 v[48:51], v[152:155], v[132:135], v[48:51]
	v_mfma_f32_16x16x32_bf16 v[52:55], v[152:155], v[136:139], v[52:55]
	v_mfma_f32_16x16x32_bf16 v[56:59], v[152:155], v[140:143], v[56:59]
	v_mfma_f32_16x16x32_bf16 v[202:205], v[152:155], v[144:147], v[26:29]
	v_mfma_f32_16x16x32_bf16 v[60:63], v[156:159], v[132:135], v[60:63]
	v_mfma_f32_16x16x32_bf16 v[216:219], v[156:159], v[136:139], v[64:67]
	v_mfma_f32_16x16x32_bf16 v[226:229], v[156:159], v[140:143], v[68:71]
	v_mfma_f32_16x16x32_bf16 v[230:233], v[156:159], v[144:147], v[22:25]
	v_mfma_f32_16x16x32_bf16 v[234:237], v[160:163], v[132:135], v[72:75]
	v_mfma_f32_16x16x32_bf16 v[238:241], v[160:163], v[136:139], v[76:79]
	s_waitcnt lgkmcnt(2)
	v_mfma_f32_16x16x32_bf16 v[150:153], v[168:171], v[132:135], v[96:99]
	v_mfma_f32_16x16x32_bf16 v[160:163], v[168:171], v[136:139], v[100:103]
	v_mfma_f32_16x16x32_bf16 v[38:41], v[168:171], v[140:143], v[104:107]
	v_mfma_f32_16x16x32_bf16 v[34:37], v[168:171], v[144:147], v[10:13]
	s_waitcnt lgkmcnt(1)
	v_mfma_f32_16x16x32_bf16 v[30:33], v[172:175], v[132:135], v[108:111]
	v_mfma_f32_16x16x32_bf16 v[26:29], v[172:175], v[136:139], v[112:115]
	v_mfma_f32_16x16x32_bf16 v[22:25], v[172:175], v[140:143], v[116:119]
	v_mfma_f32_16x16x32_bf16 v[18:21], v[172:175], v[144:147], v[6:9]
	s_waitcnt lgkmcnt(0)
	v_mfma_f32_16x16x32_bf16 v[14:17], v[182:185], v[132:135], v[120:123]
	v_mfma_f32_16x16x32_bf16 v[10:13], v[182:185], v[136:139], v[124:127]
	v_mfma_f32_16x16x32_bf16 v[6:9], v[182:185], v[140:143], v[128:131]
	v_mfma_f32_16x16x32_bf16 v[2:5], v[182:185], v[144:147], v[2:5]
	v_mov_b32_e32 v43, v224
	s_lshl_b32 s4, s46, 3
	v_lshrrev_b32_e32 v65, 1, v43
	v_lshlrev_b32_e32 v45, 3, v43
	v_and_b32_e32 v140, 24, v65
	v_ashrrev_i32_e32 v65, 4, v43
	v_and_b32_e32 v47, 56, v45
	v_add_u32_e32 v66, 0x7c, v65
	v_cmp_gt_i32_e32 vcc, 2, v65
	v_ashrrev_i32_e32 v142, 7, v43
	v_and_b32_e32 v64, 0x4f, v43
	v_cmp_gt_i32_e64 s[40:41], 64, v43
	v_cndmask_b32_e32 v66, v66, v65, vcc
	v_and_b32_e32 v67, 0x78, v45
	v_bfe_u32 v45, v45, 6, 1
	v_lshl_add_u32 v65, v65, 1, s4
	v_ashrrev_i32_e32 v43, 3, v43
	s_movk_i32 s4, 0xffe1
	v_pk_mul_f32 v[48:49], v[46:47], v[48:49] op_sel_hi:[0,1]
	v_or_b32_e32 v45, v65, v45
	v_cmp_lt_i32_e64 s[44:45], s4, v43
	s_movk_i32 s4, 0xffc1
	v_cvt_pk_bf16_f32 v74, v48, v49
	v_pk_mul_f32 v[48:49], v[46:47], v[50:51] op_sel_hi:[0,1]
	s_movk_i32 s5, 0x110
	v_add_u32_e32 v132, s15, v43
	v_cmp_lt_i32_e64 s[46:47], s4, v43
	s_movk_i32 s4, 0xffa1
	v_cvt_pk_bf16_f32 v75, v48, v49
	v_pk_mul_f32 v[48:49], v[44:45], v[52:53] op_sel_hi:[0,1]
	v_mul_u32_u24_e32 v141, 0x110, v64
	v_cmp_lt_i32_e64 s[42:43], 1, v43
	v_mul_lo_u32 v64, v43, s5
	v_cmp_lt_i32_e64 s[48:49], s4, v43
	v_add_u32_e32 v43, 0x60, v132
	v_cvt_pk_bf16_f32 v76, v48, v49
	v_pk_mul_f32 v[48:49], v[44:45], v[54:55] op_sel_hi:[0,1]
	v_cvt_pk_bf16_f32 v77, v48, v49
	v_pk_mul_f32 v[48:49], v[42:43], v[56:57] op_sel_hi:[0,1]
	v_cvt_pk_bf16_f32 v78, v48, v49
	v_pk_mul_f32 v[48:49], v[42:43], v[58:59] op_sel_hi:[0,1]
	v_cvt_pk_bf16_f32 v79, v48, v49
	v_pk_mul_f32 v[48:49], v[0:1], v[202:203] op_sel_hi:[0,1]
	v_cvt_pk_bf16_f32 v80, v48, v49
	v_pk_mul_f32 v[48:49], v[0:1], v[204:205] op_sel_hi:[0,1]
	v_cvt_pk_bf16_f32 v81, v48, v49
	v_pk_mul_f32 v[48:49], v[46:47], v[60:61] op_sel_hi:[0,1]
	v_cvt_pk_bf16_f32 v82, v48, v49
	v_pk_mul_f32 v[48:49], v[46:47], v[62:63] op_sel_hi:[0,1]
	v_cvt_pk_bf16_f32 v83, v48, v49
	v_pk_mul_f32 v[48:49], v[44:45], v[216:217] op_sel_hi:[0,1]
	v_cvt_pk_bf16_f32 v84, v48, v49
	v_pk_mul_f32 v[48:49], v[44:45], v[218:219] op_sel_hi:[0,1]
	v_cvt_pk_bf16_f32 v85, v48, v49
	v_pk_mul_f32 v[48:49], v[42:43], v[226:227] op_sel_hi:[0,1]
	v_cvt_pk_bf16_f32 v86, v48, v49
	v_pk_mul_f32 v[48:49], v[42:43], v[228:229] op_sel_hi:[0,1]
	v_cvt_pk_bf16_f32 v87, v48, v49
	v_pk_mul_f32 v[48:49], v[0:1], v[230:231] op_sel_hi:[0,1]
	v_cvt_pk_bf16_f32 v88, v48, v49
	v_pk_mul_f32 v[48:49], v[0:1], v[232:233] op_sel_hi:[0,1]
	v_cvt_pk_bf16_f32 v89, v48, v49
	v_pk_mul_f32 v[48:49], v[46:47], v[234:235] op_sel_hi:[0,1]
	v_cvt_pk_bf16_f32 v90, v48, v49
	v_pk_mul_f32 v[48:49], v[46:47], v[236:237] op_sel_hi:[0,1]
	v_cvt_pk_bf16_f32 v91, v48, v49
	v_pk_mul_f32 v[48:49], v[44:45], v[238:239] op_sel_hi:[0,1]
	v_cvt_pk_bf16_f32 v92, v48, v49
	v_pk_mul_f32 v[48:49], v[44:45], v[240:241] op_sel_hi:[0,1]
	v_cvt_pk_bf16_f32 v93, v48, v49
	v_pk_mul_f32 v[48:49], v[42:43], v[242:243] op_sel_hi:[0,1]
	v_cvt_pk_bf16_f32 v94, v48, v49
	v_pk_mul_f32 v[48:49], v[42:43], v[244:245] op_sel_hi:[0,1]
	v_cvt_pk_bf16_f32 v95, v48, v49
	v_pk_mul_f32 v[48:49], v[0:1], v[246:247] op_sel_hi:[0,1]
	v_cvt_pk_bf16_f32 v96, v48, v49
	v_pk_mul_f32 v[48:49], v[0:1], v[248:249] op_sel_hi:[0,1]
	v_cvt_pk_bf16_f32 v97, v48, v49
	v_pk_mul_f32 v[48:49], v[46:47], v[210:211] op_sel_hi:[0,1]
	v_cvt_pk_bf16_f32 v98, v48, v49
	v_pk_mul_f32 v[48:49], v[46:47], v[212:213] op_sel_hi:[0,1]
	v_cvt_pk_bf16_f32 v99, v48, v49
	v_pk_mul_f32 v[48:49], v[44:45], v[194:195] op_sel_hi:[0,1]
	v_cvt_pk_bf16_f32 v100, v48, v49
	v_pk_mul_f32 v[48:49], v[44:45], v[196:197] op_sel_hi:[0,1]
	v_mul_lo_u32 v66, v66, s5
	v_lshl_add_u32 v144, v47, 1, v64
	v_pk_mul_f32 v[64:65], v[46:47], v[186:187] op_sel_hi:[0,1]
	v_cvt_pk_bf16_f32 v101, v48, v49
	v_pk_mul_f32 v[48:49], v[42:43], v[206:207] op_sel_hi:[0,1]
	v_lshl_add_u32 v143, v67, 1, v66
	v_cvt_pk_bf16_f32 v66, v64, v65
	v_pk_mul_f32 v[64:65], v[46:47], v[188:189] op_sel_hi:[0,1]
	v_cvt_pk_bf16_f32 v102, v48, v49
	v_pk_mul_f32 v[48:49], v[42:43], v[208:209] op_sel_hi:[0,1]
	v_cvt_pk_bf16_f32 v67, v64, v65
	v_pk_mul_f32 v[64:65], v[44:45], v[190:191] op_sel_hi:[0,1]
	v_cvt_pk_bf16_f32 v103, v48, v49
	v_pk_mul_f32 v[48:49], v[0:1], v[164:165] op_sel_hi:[0,1]
	v_cvt_pk_bf16_f32 v68, v64, v65
	v_pk_mul_f32 v[64:65], v[44:45], v[192:193] op_sel_hi:[0,1]
	v_cvt_pk_bf16_f32 v104, v48, v49
	v_pk_mul_f32 v[48:49], v[0:1], v[166:167] op_sel_hi:[0,1]
	v_pk_mul_f32 v[2:3], v[0:1], v[2:3] op_sel_hi:[0,1]
	v_cvt_pk_bf16_f32 v69, v64, v65
	v_pk_mul_f32 v[64:65], v[42:43], v[176:177] op_sel_hi:[0,1]
	v_cvt_pk_bf16_f32 v105, v48, v49
	v_pk_mul_f32 v[48:49], v[46:47], v[150:151] op_sel_hi:[0,1]
	v_cvt_pk_bf16_f32 v128, v2, v3
	v_pk_mul_f32 v[2:3], v[0:1], v[4:5] op_sel_hi:[0,1]
	v_cvt_pk_bf16_f32 v70, v64, v65
	v_pk_mul_f32 v[64:65], v[42:43], v[178:179] op_sel_hi:[0,1]
	v_cvt_pk_bf16_f32 v106, v48, v49
	v_pk_mul_f32 v[48:49], v[46:47], v[152:153] op_sel_hi:[0,1]
	v_cvt_pk_bf16_f32 v129, v2, v3
	v_mov_b64_e32 v[2:3], s[54:55]
	v_add_u32_e32 v134, 32, v132
	v_add_u32_e32 v136, 64, v132
	v_cvt_pk_bf16_f32 v71, v64, v65
	v_pk_mul_f32 v[64:65], v[0:1], v[198:199] op_sel_hi:[0,1]
	v_cvt_pk_bf16_f32 v107, v48, v49
	v_pk_mul_f32 v[48:49], v[44:45], v[160:161] op_sel_hi:[0,1]
	v_pk_mul_f32 v[38:39], v[42:43], v[38:39] op_sel_hi:[0,1]
	v_pk_mul_f32 v[34:35], v[0:1], v[34:35] op_sel_hi:[0,1]
	v_pk_mul_f32 v[30:31], v[46:47], v[30:31] op_sel_hi:[0,1]
	v_pk_mul_f32 v[26:27], v[44:45], v[26:27] op_sel_hi:[0,1]
	v_pk_mul_f32 v[22:23], v[42:43], v[22:23] op_sel_hi:[0,1]
	v_pk_mul_f32 v[18:19], v[0:1], v[18:19] op_sel_hi:[0,1]
	v_pk_mul_f32 v[14:15], v[46:47], v[14:15] op_sel_hi:[0,1]
	v_pk_mul_f32 v[10:11], v[44:45], v[10:11] op_sel_hi:[0,1]
	v_pk_mul_f32 v[6:7], v[42:43], v[6:7] op_sel_hi:[0,1]
	v_mad_i64_i32 v[130:131], s[4:5], v45, s19, v[2:3]
	v_mov_b64_e32 v[2:3], s[52:53]
	v_cvt_pk_bf16_f32 v72, v64, v65
	v_pk_mul_f32 v[64:65], v[0:1], v[200:201] op_sel_hi:[0,1]
	v_cvt_pk_bf16_f32 v108, v48, v49
	v_pk_mul_f32 v[48:49], v[44:45], v[162:163] op_sel_hi:[0,1]
	v_cvt_pk_bf16_f32 v110, v38, v39
	v_pk_mul_f32 v[38:39], v[42:43], v[40:41] op_sel_hi:[0,1]
	v_cvt_pk_bf16_f32 v112, v34, v35
	v_pk_mul_f32 v[34:35], v[0:1], v[36:37] op_sel_hi:[0,1]
	v_cvt_pk_bf16_f32 v114, v30, v31
	v_pk_mul_f32 v[30:31], v[46:47], v[32:33] op_sel_hi:[0,1]
	v_cvt_pk_bf16_f32 v116, v26, v27
	v_pk_mul_f32 v[26:27], v[44:45], v[28:29] op_sel_hi:[0,1]
	v_cvt_pk_bf16_f32 v118, v22, v23
	v_pk_mul_f32 v[22:23], v[42:43], v[24:25] op_sel_hi:[0,1]
	v_cvt_pk_bf16_f32 v120, v18, v19
	v_pk_mul_f32 v[18:19], v[0:1], v[20:21] op_sel_hi:[0,1]
	v_cvt_pk_bf16_f32 v122, v14, v15
	v_pk_mul_f32 v[14:15], v[46:47], v[16:17] op_sel_hi:[0,1]
	v_cvt_pk_bf16_f32 v124, v10, v11
	v_pk_mul_f32 v[10:11], v[44:45], v[12:13] op_sel_hi:[0,1]
	v_cvt_pk_bf16_f32 v126, v6, v7
	v_pk_mul_f32 v[6:7], v[42:43], v[8:9] op_sel_hi:[0,1]
	v_mad_i64_i32 v[132:133], s[4:5], v132, s19, v[2:3]
	v_mad_i64_i32 v[134:135], s[4:5], v134, s19, v[2:3]
	v_mad_i64_i32 v[136:137], s[4:5], v136, s19, v[2:3]
	v_mad_i64_i32 v[138:139], s[4:5], v43, s19, v[2:3]
	v_add_u32_e32 v145, 0xfffffef0, v144
	v_add_u32_e32 v146, 0xffffff70, v144
	v_add_u32_e32 v147, 0xfffffde0, v144
	v_add_u32_e32 v148, 0xfffffe60, v144
	v_add_u32_e32 v149, 0x2200, v144
	v_add_u32_e32 v168, 0x20f0, v144
	v_add_u32_e32 v169, 0x2170, v144
	v_add_u32_e32 v170, 0x1fe0, v144
	v_add_u32_e32 v171, 0x2060, v144
	v_add_u32_e32 v154, 0x4400, v144
	v_add_u32_e32 v155, 0x42f0, v144
	v_add_u32_e32 v156, 0x4370, v144
	v_add_u32_e32 v157, 0x41e0, v144
	v_add_u32_e32 v158, 0x4260, v144
	v_add_u32_e32 v159, 0x6600, v144
	v_add_u32_e32 v172, 0x64f0, v144
	v_add_u32_e32 v173, 0x6570, v144
	v_add_u32_e32 v174, 0x63e0, v144
	v_add_u32_e32 v175, 0x6460, v144
	v_cvt_pk_bf16_f32 v73, v64, v65
	v_cvt_pk_bf16_f32 v109, v48, v49
	v_cvt_pk_bf16_f32 v111, v38, v39
	v_cvt_pk_bf16_f32 v113, v34, v35
	v_cvt_pk_bf16_f32 v115, v30, v31
	v_cvt_pk_bf16_f32 v117, v26, v27
	v_cvt_pk_bf16_f32 v119, v22, v23
	v_cvt_pk_bf16_f32 v121, v18, v19
	v_cvt_pk_bf16_f32 v123, v14, v15
	v_cvt_pk_bf16_f32 v125, v10, v11
	v_cvt_pk_bf16_f32 v127, v6, v7
	v_lshl_or_b32 v0, s14, 7, v47
	s_mov_b32 s4, 0
	s_mov_b64 s[12:13], -1
	v_add_u32_e32 v164, v140, v141
	v_xor_b32_e32 v246, 32, v225
	v_xor_b32_e32 v247, 16, v225
	v_xor_b32_e32 v248, 8, v225
	v_xor_b32_e32 v249, 4, v225
	v_mov_b32_e32 v243, v221
	s_branch .LBB0_171

.LBB0_194:
	s_mul_i32 s48, s13, 0x6000
	s_add_i32 s49, s48, 0xffffa000
	s_cmp_gt_i32 s13, 0
	s_waitcnt vmcnt(6)
	s_cselect_b32 s49, s49, 0xc000
	s_waitcnt lgkmcnt(0)
	s_barrier
	s_setprio 2
	v_or_b32_e32 v0, s48, v146
	v_add_u32_e32 v0, v0, v144
	ds_read_b128 v[148:151], v0
	ds_read_b128 v[152:155], v0 offset:1024
	ds_read_b128 v[156:159], v0 offset:2048
	ds_read_b128 v[160:163], v0 offset:3072
	v_add3_u32 v0, s48, v145, v144
	ds_read_b128 v[164:167], v0 offset:8192
	ds_read_b128 v[168:171], v0 offset:9216
	ds_read_b128 v[172:175], v0 offset:10240
	ds_read_b128 v[176:179], v0 offset:11264
	ds_read_b128 v[180:183], v0 offset:12288
	ds_read_b128 v[184:187], v0 offset:13312
	ds_read_b128 v[188:191], v0 offset:14336
	ds_read_b128 v[198:201], v0 offset:15360
	v_lshl_add_u64 v[212:213], v[142:143], 0, s[40:41]
	v_lshl_add_u64 v[212:213], v[130:131], 1, v[212:213]
	s_add_i32 s69, s49, s47
	s_mov_b32 m0, s69
	s_nop 0
	global_load_lds_dwordx4 v[212:213], off
	v_lshl_add_u64 v[212:213], v[142:143], 0, s[40:41]
	v_lshl_add_u64 v[212:213], v[132:133], 1, v[212:213]
	s_add_i32 s69, s49, s14
	s_mov_b32 m0, s69
	s_nop 0
	global_load_lds_dwordx4 v[212:213], off
	s_add_i32 s49, s15, s49
	v_lshl_add_u64 v[212:213], v[140:141], 0, s[40:41]
	s_mov_b32 m0, s49
	s_nop 0
	global_load_lds_dwordx4 v[212:213], off
	v_lshl_add_u64 v[212:213], v[138:139], 0, s[40:41]
	s_add_i32 s69, s49, 0x400
	s_mov_b32 m0, s69
	s_nop 0
	global_load_lds_dwordx4 v[212:213], off
	v_lshl_add_u64 v[212:213], v[136:137], 0, s[40:41]
	s_add_i32 s69, s49, 0x800
	s_mov_b32 m0, s69
	s_nop 0
	global_load_lds_dwordx4 v[212:213], off
	v_lshl_add_u64 v[212:213], v[134:135], 0, s[40:41]
	s_addk_i32 s49, 0xc00
	s_mov_b32 m0, s49
	s_nop 0
	global_load_lds_dwordx4 v[212:213], off
	s_setprio 0
	s_waitcnt lgkmcnt(7)
	v_mfma_f32_16x16x32_bf16 v[126:129], v[164:167], v[148:151], v[126:129]
	v_mfma_f32_16x16x32_bf16 v[122:125], v[164:167], v[152:155], v[122:125]
	v_mfma_f32_16x16x32_bf16 v[118:121], v[164:167], v[156:159], v[118:121]
	v_mfma_f32_16x16x32_bf16 v[114:117], v[164:167], v[160:163], v[114:117]
	s_waitcnt lgkmcnt(6)
	v_mfma_f32_16x16x32_bf16 v[110:113], v[168:171], v[148:151], v[110:113]
	v_mfma_f32_16x16x32_bf16 v[106:109], v[168:171], v[152:155], v[106:109]
	v_mfma_f32_16x16x32_bf16 v[102:105], v[168:171], v[156:159], v[102:105]
	v_mfma_f32_16x16x32_bf16 v[98:101], v[168:171], v[160:163], v[98:101]
	s_waitcnt lgkmcnt(5)
	v_mfma_f32_16x16x32_bf16 v[94:97], v[172:175], v[148:151], v[94:97]
	v_mfma_f32_16x16x32_bf16 v[90:93], v[172:175], v[152:155], v[90:93]
	v_mfma_f32_16x16x32_bf16 v[86:89], v[172:175], v[156:159], v[86:89]
	v_mfma_f32_16x16x32_bf16 v[82:85], v[172:175], v[160:163], v[82:85]
	s_waitcnt lgkmcnt(4)
	v_mfma_f32_16x16x32_bf16 v[78:81], v[176:179], v[148:151], v[78:81]
	v_mfma_f32_16x16x32_bf16 v[74:77], v[176:179], v[152:155], v[74:77]
	v_mfma_f32_16x16x32_bf16 v[70:73], v[176:179], v[156:159], v[70:73]
	v_mfma_f32_16x16x32_bf16 v[66:69], v[176:179], v[160:163], v[66:69]
	s_waitcnt lgkmcnt(3)
	v_mfma_f32_16x16x32_bf16 v[62:65], v[180:183], v[148:151], v[62:65]
	v_mfma_f32_16x16x32_bf16 v[58:61], v[180:183], v[152:155], v[58:61]
	v_mfma_f32_16x16x32_bf16 v[54:57], v[180:183], v[156:159], v[54:57]
	v_mfma_f32_16x16x32_bf16 v[50:53], v[180:183], v[160:163], v[50:53]
	s_waitcnt lgkmcnt(2)
	v_mfma_f32_16x16x32_bf16 v[46:49], v[184:187], v[148:151], v[46:49]
	v_mfma_f32_16x16x32_bf16 v[42:45], v[184:187], v[152:155], v[42:45]
	v_mfma_f32_16x16x32_bf16 v[38:41], v[184:187], v[156:159], v[38:41]
	v_mfma_f32_16x16x32_bf16 v[34:37], v[184:187], v[160:163], v[34:37]
	s_waitcnt lgkmcnt(1)
	v_mfma_f32_16x16x32_bf16 v[30:33], v[188:191], v[148:151], v[30:33]
	v_mfma_f32_16x16x32_bf16 v[26:29], v[188:191], v[152:155], v[26:29]
	v_mfma_f32_16x16x32_bf16 v[22:25], v[188:191], v[156:159], v[22:25]
	v_mfma_f32_16x16x32_bf16 v[18:21], v[188:191], v[160:163], v[18:21]
	s_waitcnt lgkmcnt(0)
	v_mfma_f32_16x16x32_bf16 v[14:17], v[198:201], v[148:151], v[14:17]
	v_mfma_f32_16x16x32_bf16 v[10:13], v[198:201], v[152:155], v[10:13]
	v_mfma_f32_16x16x32_bf16 v[6:9], v[198:201], v[156:159], v[6:9]
	v_mfma_f32_16x16x32_bf16 v[2:5], v[198:201], v[160:163], v[2:5]
	s_add_i32 s48, s13, 1
	s_cmp_lg_u32 s13, 2
	s_cselect_b32 s13, s48, 0
	s_add_u32 s40, s40, 64
	s_addc_u32 s41, s41, 0
	s_cmpk_eq_i32 s40, 0x780
	s_cbranch_scc0 .LBB0_194
	s_waitcnt vmcnt(6)
	v_add_u32_e32 v0, v146, v144
	v_add_u32_e32 v194, v145, v144
	s_waitcnt lgkmcnt(0)
	s_barrier
	ds_read_b128 v[130:133], v0
	ds_read_b128 v[134:137], v0 offset:1024
	ds_read_b128 v[138:141], v0 offset:2048
	ds_read_b128 v[146:149], v0 offset:3072
	ds_read_b128 v[142:145], v194 offset:8192
	ds_read_b128 v[150:153], v194 offset:9216
	ds_read_b128 v[154:157], v194 offset:10240
	ds_read_b128 v[158:161], v194 offset:11264
	ds_read_b128 v[162:165], v194 offset:12288
	ds_read_b128 v[166:169], v194 offset:13312
	ds_read_b128 v[170:173], v194 offset:14336
	ds_read_b128 v[174:177], v194 offset:15360
	s_waitcnt lgkmcnt(7)
	v_mfma_f32_16x16x32_bf16 v[126:129], v[142:145], v[130:133], v[126:129]
	v_mfma_f32_16x16x32_bf16 v[122:125], v[142:145], v[134:137], v[122:125]
	v_mfma_f32_16x16x32_bf16 v[118:121], v[142:145], v[138:141], v[118:121]
	v_mfma_f32_16x16x32_bf16 v[114:117], v[142:145], v[146:149], v[114:117]
	s_waitcnt lgkmcnt(6)
	v_mfma_f32_16x16x32_bf16 v[110:113], v[150:153], v[130:133], v[110:113]
	v_mfma_f32_16x16x32_bf16 v[106:109], v[150:153], v[134:137], v[106:109]
	v_mfma_f32_16x16x32_bf16 v[102:105], v[150:153], v[138:141], v[102:105]
	v_mfma_f32_16x16x32_bf16 v[98:101], v[150:153], v[146:149], v[98:101]
	s_waitcnt lgkmcnt(5)
	v_mfma_f32_16x16x32_bf16 v[94:97], v[154:157], v[130:133], v[94:97]
	v_mfma_f32_16x16x32_bf16 v[90:93], v[154:157], v[134:137], v[90:93]
	v_mfma_f32_16x16x32_bf16 v[86:89], v[154:157], v[138:141], v[86:89]
	v_mfma_f32_16x16x32_bf16 v[82:85], v[154:157], v[146:149], v[82:85]
	s_waitcnt lgkmcnt(4)
	v_mfma_f32_16x16x32_bf16 v[78:81], v[158:161], v[130:133], v[78:81]
	v_mfma_f32_16x16x32_bf16 v[74:77], v[158:161], v[134:137], v[74:77]
	v_mfma_f32_16x16x32_bf16 v[70:73], v[158:161], v[138:141], v[70:73]
	v_mfma_f32_16x16x32_bf16 v[66:69], v[158:161], v[146:149], v[66:69]
	s_waitcnt lgkmcnt(3)
	v_mfma_f32_16x16x32_bf16 v[142:145], v[162:165], v[130:133], v[62:65]
	v_mfma_f32_16x16x32_bf16 v[150:153], v[162:165], v[134:137], v[58:61]
	v_mfma_f32_16x16x32_bf16 v[154:157], v[162:165], v[138:141], v[54:57]
	v_mfma_f32_16x16x32_bf16 v[158:161], v[162:165], v[146:149], v[50:53]
	s_waitcnt lgkmcnt(2)
	v_mfma_f32_16x16x32_bf16 v[162:165], v[166:169], v[130:133], v[46:49]
	v_mfma_f32_16x16x32_bf16 v[178:181], v[166:169], v[134:137], v[42:45]
	v_mfma_f32_16x16x32_bf16 v[182:185], v[166:169], v[138:141], v[38:41]
	v_mfma_f32_16x16x32_bf16 v[166:169], v[166:169], v[146:149], v[34:37]
	s_waitcnt lgkmcnt(1)
	v_mfma_f32_16x16x32_bf16 v[186:189], v[170:173], v[130:133], v[30:33]
	v_mfma_f32_16x16x32_bf16 v[190:193], v[170:173], v[134:137], v[26:29]
	v_mfma_f32_16x16x32_bf16 v[198:201], v[170:173], v[138:141], v[22:25]
	v_mfma_f32_16x16x32_bf16 v[170:173], v[170:173], v[146:149], v[18:21]
	s_waitcnt lgkmcnt(0)
	v_mfma_f32_16x16x32_bf16 v[130:133], v[174:177], v[130:133], v[14:17]
	v_mfma_f32_16x16x32_bf16 v[134:137], v[174:177], v[134:137], v[10:13]
	v_mfma_f32_16x16x32_bf16 v[138:141], v[174:177], v[138:141], v[6:9]
	v_mfma_f32_16x16x32_bf16 v[146:149], v[174:177], v[146:149], v[2:5]
	s_waitcnt vmcnt(0)
	s_waitcnt lgkmcnt(0)
	s_barrier
	ds_read_b128 v[174:177], v0 offset:24576
	ds_read_b128 v[202:205], v0 offset:25600
	ds_read_b128 v[216:219], v0 offset:26624
	ds_read_b128 v[226:229], v0 offset:27648
	ds_read_b128 v[14:17], v194 offset:32768
	ds_read_b128 v[30:33], v194 offset:33792
	ds_read_b128 v[46:49], v194 offset:34816
	ds_read_b128 v[62:65], v194 offset:35840
	ds_read_b128 v[230:233], v194 offset:36864
	ds_read_b128 v[234:237], v194 offset:37888
	ds_read_b128 v[238:241], v194 offset:38912
	ds_read_b128 v[242:245], v194 offset:39936
	s_waitcnt lgkmcnt(7)
	v_mfma_f32_16x16x32_bf16 v[2:5], v[14:17], v[174:177], v[126:129]
	v_mfma_f32_16x16x32_bf16 v[6:9], v[14:17], v[202:205], v[122:125]
	v_mfma_f32_16x16x32_bf16 v[10:13], v[14:17], v[216:219], v[118:121]
	v_mfma_f32_16x16x32_bf16 v[14:17], v[14:17], v[226:229], v[114:117]
	s_waitcnt lgkmcnt(6)
	v_mfma_f32_16x16x32_bf16 v[18:21], v[30:33], v[174:177], v[110:113]
	v_mfma_f32_16x16x32_bf16 v[22:25], v[30:33], v[202:205], v[106:109]
	v_mfma_f32_16x16x32_bf16 v[26:29], v[30:33], v[216:219], v[102:105]
	v_mfma_f32_16x16x32_bf16 v[30:33], v[30:33], v[226:229], v[98:101]
	s_waitcnt lgkmcnt(5)
	v_mfma_f32_16x16x32_bf16 v[34:37], v[46:49], v[174:177], v[94:97]
	v_mfma_f32_16x16x32_bf16 v[38:41], v[46:49], v[202:205], v[90:93]
	v_mfma_f32_16x16x32_bf16 v[42:45], v[46:49], v[216:219], v[86:89]
	v_mfma_f32_16x16x32_bf16 v[46:49], v[46:49], v[226:229], v[82:85]
	s_waitcnt lgkmcnt(4)
	v_mfma_f32_16x16x32_bf16 v[50:53], v[62:65], v[174:177], v[78:81]
	v_mfma_f32_16x16x32_bf16 v[54:57], v[62:65], v[202:205], v[74:77]
	v_mfma_f32_16x16x32_bf16 v[58:61], v[62:65], v[216:219], v[70:73]
	v_mfma_f32_16x16x32_bf16 v[62:65], v[62:65], v[226:229], v[66:69]
	s_waitcnt lgkmcnt(3)
	v_mfma_f32_16x16x32_bf16 v[66:69], v[230:233], v[174:177], v[142:145]
	v_mfma_f32_16x16x32_bf16 v[70:73], v[230:233], v[202:205], v[150:153]
	v_mfma_f32_16x16x32_bf16 v[74:77], v[230:233], v[216:219], v[154:157]
	v_mfma_f32_16x16x32_bf16 v[78:81], v[230:233], v[226:229], v[158:161]
	s_waitcnt lgkmcnt(2)
	v_mfma_f32_16x16x32_bf16 v[82:85], v[234:237], v[174:177], v[162:165]
	v_mfma_f32_16x16x32_bf16 v[86:89], v[234:237], v[202:205], v[178:181]
	v_mfma_f32_16x16x32_bf16 v[90:93], v[234:237], v[216:219], v[182:185]
	v_mfma_f32_16x16x32_bf16 v[94:97], v[234:237], v[226:229], v[166:169]
	s_waitcnt lgkmcnt(1)
	v_mfma_f32_16x16x32_bf16 v[98:101], v[238:241], v[174:177], v[186:189]
	v_mfma_f32_16x16x32_bf16 v[102:105], v[238:241], v[202:205], v[190:193]
	v_mfma_f32_16x16x32_bf16 v[106:109], v[238:241], v[216:219], v[198:201]
	v_mfma_f32_16x16x32_bf16 v[110:113], v[238:241], v[226:229], v[170:173]
	s_waitcnt lgkmcnt(0)
	v_mfma_f32_16x16x32_bf16 v[114:117], v[242:245], v[174:177], v[130:133]
	v_mfma_f32_16x16x32_bf16 v[118:121], v[242:245], v[202:205], v[134:137]
	v_mfma_f32_16x16x32_bf16 v[122:125], v[242:245], v[216:219], v[138:141]
	v_mfma_f32_16x16x32_bf16 v[126:129], v[242:245], v[226:229], v[146:149]
	v_mov_b32_e32 v130, v224
	s_ashr_i32 s13, s12, 31
	v_and_b32_e32 v131, 31, v130
	v_ashrrev_i32_e32 v197, 7, v130
	v_ashrrev_i32_e32 v132, 5, v130
	v_lshlrev_b32_e32 v0, 2, v131
	s_lshl_b64 s[48:49], s[12:13], 11
	v_lshlrev_b32_e32 v164, 4, v131
	v_cmp_eq_u32_e64 s[40:41], 0, v131
	v_and_b32_e32 v131, 0x4f, v130
	v_and_b32_e32 v130, 48, v130
	s_movk_i32 s13, 0x210
	v_cmp_lt_i32_e32 vcc, v247, v214
	v_mad_u32_u24 v202, v131, s13, v130
	s_ashr_i32 s47, s46, 31
	v_cndmask_b32_e32 v130, v225, v247, vcc
	v_cmp_lt_i32_e32 vcc, v248, v214
	v_lshlrev_b32_e32 v203, 2, v130
	s_lshl_b32 s69, s57, 1
	v_cndmask_b32_e32 v130, v225, v248, vcc
	v_cmp_lt_i32_e32 vcc, v249, v214
	v_lshlrev_b32_e32 v204, 2, v130
	s_add_u32 s15, s53, s48
	v_cndmask_b32_e32 v130, v225, v249, vcc
	v_cmp_lt_i32_e32 vcc, v223, v214
	v_lshlrev_b32_e32 v205, 2, v130
	v_lshl_or_b32 v0, v132, 10, v0
	v_cndmask_b32_e32 v130, v225, v223, vcc
	v_cmp_lt_i32_e32 vcc, v252, v214
	v_lshlrev_b32_e32 v206, 2, v130
	v_mul_lo_u32 v165, v132, s13
	v_cndmask_b32_e32 v130, v225, v252, vcc
	v_lshlrev_b32_e32 v207, 2, v130
	v_add_u32_e32 v130, s12, v132
	v_ashrrev_i32_e32 v131, 31, v130
	v_lshlrev_b64 v[132:133], 5, v[130:131]
	v_add_u32_e32 v134, 8, v130
	v_add_u32_e32 v136, 16, v130
	v_add_u32_e32 v138, 24, v130
	v_add_u32_e32 v140, 32, v130
	v_add_u32_e32 v142, 40, v130
	v_add_u32_e32 v144, 48, v130
	v_add_u32_e32 v146, 56, v130
	v_add_u32_e32 v148, 64, v130
	v_add_u32_e32 v150, 0x48, v130
	v_add_u32_e32 v152, 0x50, v130
	v_add_u32_e32 v154, 0x58, v130
	v_add_u32_e32 v156, 0x60, v130
	v_add_u32_e32 v158, 0x68, v130
	v_add_u32_e32 v160, 0x70, v130
	v_add_u32_e32 v130, 0x78, v130
	s_addc_u32 s48, s54, s49
	s_lshl_b64 s[12:13], s[46:47], 1
	v_ashrrev_i32_e32 v135, 31, v134
	v_ashrrev_i32_e32 v137, 31, v136
	v_ashrrev_i32_e32 v139, 31, v138
	v_ashrrev_i32_e32 v141, 31, v140
	v_ashrrev_i32_e32 v143, 31, v142
	v_ashrrev_i32_e32 v145, 31, v144
	v_ashrrev_i32_e32 v147, 31, v146
	v_ashrrev_i32_e32 v149, 31, v148
	v_ashrrev_i32_e32 v151, 31, v150
	v_ashrrev_i32_e32 v153, 31, v152
	v_ashrrev_i32_e32 v155, 31, v154
	v_ashrrev_i32_e32 v157, 31, v156
	v_ashrrev_i32_e32 v159, 31, v158
	v_ashrrev_i32_e32 v161, 31, v160
	v_ashrrev_i32_e32 v131, 31, v130
	s_add_u32 s12, s15, s12
	v_lshlrev_b64 v[134:135], 5, v[134:135]
	v_lshlrev_b64 v[136:137], 5, v[136:137]
	v_lshlrev_b64 v[138:139], 5, v[138:139]
	v_lshlrev_b64 v[140:141], 5, v[140:141]
	v_lshlrev_b64 v[142:143], 5, v[142:143]
	v_lshlrev_b64 v[144:145], 5, v[144:145]
	v_lshlrev_b64 v[146:147], 5, v[146:147]
	v_lshlrev_b64 v[148:149], 5, v[148:149]
	v_lshlrev_b64 v[150:151], 5, v[150:151]
	v_lshlrev_b64 v[152:153], 5, v[152:153]
	v_lshlrev_b64 v[154:155], 5, v[154:155]
	v_lshlrev_b64 v[156:157], 5, v[156:157]
	v_lshlrev_b64 v[158:159], 5, v[158:159]
	v_lshlrev_b64 v[160:161], 5, v[160:161]
	v_lshlrev_b64 v[162:163], 5, v[130:131]
	s_addc_u32 s13, s48, s13
	s_mov_b32 s14, 0
	v_lshl_add_u64 v[130:131], v[0:1], 1, s[12:13]
	v_lshl_add_u64 v[132:133], s[42:43], 0, v[132:133]
	v_lshl_add_u64 v[134:135], s[42:43], 0, v[134:135]
	v_lshl_add_u64 v[136:137], s[42:43], 0, v[136:137]
	v_lshl_add_u64 v[138:139], s[42:43], 0, v[138:139]
	v_lshl_add_u64 v[140:141], s[42:43], 0, v[140:141]
	v_lshl_add_u64 v[142:143], s[42:43], 0, v[142:143]
	v_lshl_add_u64 v[144:145], s[42:43], 0, v[144:145]
	v_lshl_add_u64 v[146:147], s[42:43], 0, v[146:147]
	v_lshl_add_u64 v[148:149], s[42:43], 0, v[148:149]
	v_lshl_add_u64 v[150:151], s[42:43], 0, v[150:151]
	v_lshl_add_u64 v[152:153], s[42:43], 0, v[152:153]
	v_lshl_add_u64 v[154:155], s[42:43], 0, v[154:155]
	v_lshl_add_u64 v[156:157], s[42:43], 0, v[156:157]
	v_lshl_add_u64 v[158:159], s[42:43], 0, v[158:159]
	v_lshl_add_u64 v[160:161], s[42:43], 0, v[160:161]
	v_lshl_add_u64 v[162:163], s[42:43], 0, v[162:163]
	s_mov_b64 s[46:47], -1
	v_add_u32_e32 v0, v164, v165
	v_mov_b32_e32 v243, 0x7f800000
	s_branch .LBB0_197

.LBB0_407:
	v_mul_f32_e32 v170, 0xbe38aa3b, v169
	v_cndmask_b32_e64 v170, v222, v170, s[40:41]
	v_fmamk_f32 v18, v18, 0x3e38aa3b, v170
	v_fmamk_f32 v2, v2, 0x3e38aa3b, v170
	v_exp_f32_e32 v18, v18
	v_exp_f32_e32 v2, v2
	v_fmamk_f32 v19, v19, 0x3e38aa3b, v170
	v_fmamk_f32 v3, v3, 0x3e38aa3b, v170
	v_exp_f32_e32 v19, v19
	v_exp_f32_e32 v3, v3
	v_add_f32_e32 v177, v18, v2
	v_fmamk_f32 v20, v20, 0x3e38aa3b, v170
	v_fmamk_f32 v4, v4, 0x3e38aa3b, v170
	v_exp_f32_e32 v20, v20
	v_exp_f32_e32 v4, v4
	v_add_f32_e32 v176, v19, v3
	v_add_f32_e32 v177, v176, v177
	v_fmamk_f32 v21, v21, 0x3e38aa3b, v170
	v_fmamk_f32 v5, v5, 0x3e38aa3b, v170
	v_exp_f32_e32 v21, v21
	v_exp_f32_e32 v5, v5
	v_add_f32_e32 v176, v20, v4
	v_add_f32_e32 v177, v176, v177
	v_fmamk_f32 v22, v22, 0x3e38aa3b, v170
	v_fmamk_f32 v6, v6, 0x3e38aa3b, v170
	v_exp_f32_e32 v22, v22
	v_exp_f32_e32 v6, v6
	v_add_f32_e32 v176, v21, v5
	v_add_f32_e32 v177, v176, v177
	v_fmamk_f32 v23, v23, 0x3e38aa3b, v170
	v_fmamk_f32 v7, v7, 0x3e38aa3b, v170
	v_exp_f32_e32 v23, v23
	v_exp_f32_e32 v7, v7
	v_add_f32_e32 v176, v22, v6
	v_add_f32_e32 v177, v176, v177
	v_fmamk_f32 v24, v24, 0x3e38aa3b, v170
	v_fmamk_f32 v8, v8, 0x3e38aa3b, v170
	v_exp_f32_e32 v24, v24
	v_exp_f32_e32 v8, v8
	v_add_f32_e32 v176, v23, v7
	v_add_f32_e32 v177, v176, v177
	v_fmamk_f32 v25, v25, 0x3e38aa3b, v170
	v_fmamk_f32 v9, v9, 0x3e38aa3b, v170
	v_exp_f32_e32 v25, v25
	v_exp_f32_e32 v9, v9
	v_add_f32_e32 v176, v24, v8
	v_add_f32_e32 v177, v176, v177
	v_fmamk_f32 v26, v26, 0x3e38aa3b, v170
	v_fmamk_f32 v10, v10, 0x3e38aa3b, v170
	v_exp_f32_e32 v26, v26
	v_exp_f32_e32 v10, v10
	v_add_f32_e32 v176, v25, v9
	v_add_f32_e32 v177, v176, v177
	v_fmamk_f32 v27, v27, 0x3e38aa3b, v170
	v_fmamk_f32 v11, v11, 0x3e38aa3b, v170
	v_exp_f32_e32 v27, v27
	v_exp_f32_e32 v11, v11
	v_add_f32_e32 v176, v26, v10
	v_add_f32_e32 v177, v176, v177
	v_fmamk_f32 v28, v28, 0x3e38aa3b, v170
	v_fmamk_f32 v12, v12, 0x3e38aa3b, v170
	v_exp_f32_e32 v28, v28
	v_exp_f32_e32 v12, v12
	v_add_f32_e32 v176, v27, v11
	v_add_f32_e32 v177, v176, v177
	v_fmamk_f32 v29, v29, 0x3e38aa3b, v170
	v_fmamk_f32 v13, v13, 0x3e38aa3b, v170
	v_exp_f32_e32 v29, v29
	v_exp_f32_e32 v13, v13
	v_add_f32_e32 v176, v28, v12
	v_add_f32_e32 v177, v176, v177
	v_fmamk_f32 v30, v30, 0x3e38aa3b, v170
	v_fmamk_f32 v14, v14, 0x3e38aa3b, v170
	v_exp_f32_e32 v30, v30
	v_exp_f32_e32 v14, v14
	v_add_f32_e32 v176, v29, v13
	v_add_f32_e32 v177, v176, v177
	v_fmamk_f32 v31, v31, 0x3e38aa3b, v170
	v_fmamk_f32 v15, v15, 0x3e38aa3b, v170
	v_exp_f32_e32 v31, v31
	v_exp_f32_e32 v15, v15
	v_add_f32_e32 v176, v30, v14
	v_add_f32_e32 v177, v176, v177
	v_fmamk_f32 v32, v32, 0x3e38aa3b, v170
	v_fmamk_f32 v16, v16, 0x3e38aa3b, v170
	v_exp_f32_e32 v32, v32
	v_exp_f32_e32 v16, v16
	v_add_f32_e32 v176, v31, v15
	v_add_f32_e32 v177, v176, v177
	v_fmamk_f32 v33, v33, 0x3e38aa3b, v170
	v_fmamk_f32 v17, v17, 0x3e38aa3b, v170
	v_exp_f32_e32 v33, v33
	v_exp_f32_e32 v17, v17
	v_add_f32_e32 v176, v32, v16
	v_add_f32_e32 v177, v176, v177
	v_add_f32_e32 v176, v33, v17
	v_add_f32_e32 v177, v176, v177
	v_cvt_pk_bf16_f32 v172, v18, v19
	v_cvt_pk_bf16_f32 v173, v20, v21
	v_cvt_pk_bf16_f32 v174, v22, v23
	v_cvt_pk_bf16_f32 v175, v24, v25
	v_cvt_pk_bf16_f32 v9, v8, v9
	v_cvt_pk_bf16_f32 v8, v6, v7
	v_mfma_f32_32x32x16_bf16 v[82:97], v[158:161], v[172:175], v[82:97]
	v_cvt_pk_bf16_f32 v7, v4, v5
	v_cvt_pk_bf16_f32 v6, v2, v3
	v_mfma_f32_32x32x16_bf16 v[66:81], v[126:129], v[172:175], v[66:81]
	v_cvt_pk_bf16_f32 v2, v10, v11
	v_cvt_pk_bf16_f32 v3, v12, v13
	v_cvt_pk_bf16_f32 v4, v14, v15
	v_cvt_pk_bf16_f32 v5, v16, v17
	v_cvt_pk_bf16_f32 v10, v26, v27
	v_cvt_pk_bf16_f32 v11, v28, v29
	v_cvt_pk_bf16_f32 v12, v30, v31
	v_cvt_pk_bf16_f32 v13, v32, v33
	v_add_f32_e32 v201, v177, v201
	s_nop 0
	v_mfma_f32_32x32x16_bf16 v[82:97], v[154:157], v[10:13], v[82:97]
	v_mfma_f32_32x32x16_bf16 v[66:81], v[122:125], v[10:13], v[66:81]
	v_mfma_f32_32x32x16_bf16 v[82:97], v[150:153], v[6:9], v[82:97]
	v_mfma_f32_32x32x16_bf16 v[66:81], v[118:121], v[6:9], v[66:81]
	v_mfma_f32_32x32x16_bf16 v[82:97], v[146:149], v[2:5], v[82:97]
	v_mfma_f32_32x32x16_bf16 v[66:81], v[114:117], v[2:5], v[66:81]
	s_xor_b32 s49, s49, 1
	s_cmp_le_i32 s1, s80
	s_cbranch_scc1 .LBB0_409
	s_branch .LBB0_410

.LBB0_418:
	v_mul_f32_e32 v194, 0xbe38aa3b, v0
	s_add_i32 s94, s94, 1
	v_fmamk_f32 v114, v114, 0x3e38aa3b, v194
	v_fmamk_f32 v98, v98, 0x3e38aa3b, v194
	v_exp_f32_e32 v114, v114
	v_exp_f32_e32 v98, v98
	v_fmamk_f32 v115, v115, 0x3e38aa3b, v194
	v_fmamk_f32 v99, v99, 0x3e38aa3b, v194
	v_exp_f32_e32 v115, v115
	v_exp_f32_e32 v99, v99
	v_add_f32_e32 v196, v114, v98
	v_fmamk_f32 v116, v116, 0x3e38aa3b, v194
	v_fmamk_f32 v100, v100, 0x3e38aa3b, v194
	v_exp_f32_e32 v116, v116
	v_exp_f32_e32 v100, v100
	v_add_f32_e32 v195, v115, v99
	v_add_f32_e32 v196, v195, v196
	v_fmamk_f32 v117, v117, 0x3e38aa3b, v194
	v_fmamk_f32 v101, v101, 0x3e38aa3b, v194
	v_exp_f32_e32 v117, v117
	v_exp_f32_e32 v101, v101
	v_add_f32_e32 v195, v116, v100
	v_add_f32_e32 v196, v195, v196
	v_fmamk_f32 v118, v118, 0x3e38aa3b, v194
	v_fmamk_f32 v102, v102, 0x3e38aa3b, v194
	v_exp_f32_e32 v118, v118
	v_exp_f32_e32 v102, v102
	v_add_f32_e32 v195, v117, v101
	v_add_f32_e32 v196, v195, v196
	v_fmamk_f32 v119, v119, 0x3e38aa3b, v194
	v_fmamk_f32 v103, v103, 0x3e38aa3b, v194
	v_exp_f32_e32 v119, v119
	v_exp_f32_e32 v103, v103
	v_add_f32_e32 v195, v118, v102
	v_add_f32_e32 v196, v195, v196
	v_fmamk_f32 v120, v120, 0x3e38aa3b, v194
	v_fmamk_f32 v104, v104, 0x3e38aa3b, v194
	v_exp_f32_e32 v120, v120
	v_exp_f32_e32 v104, v104
	v_add_f32_e32 v195, v119, v103
	v_add_f32_e32 v196, v195, v196
	v_fmamk_f32 v121, v121, 0x3e38aa3b, v194
	v_fmamk_f32 v105, v105, 0x3e38aa3b, v194
	v_exp_f32_e32 v121, v121
	v_exp_f32_e32 v105, v105
	v_add_f32_e32 v195, v120, v104
	v_add_f32_e32 v196, v195, v196
	v_fmamk_f32 v122, v122, 0x3e38aa3b, v194
	v_fmamk_f32 v106, v106, 0x3e38aa3b, v194
	v_exp_f32_e32 v122, v122
	v_exp_f32_e32 v106, v106
	v_add_f32_e32 v195, v121, v105
	v_add_f32_e32 v196, v195, v196
	v_fmamk_f32 v123, v123, 0x3e38aa3b, v194
	v_fmamk_f32 v107, v107, 0x3e38aa3b, v194
	v_exp_f32_e32 v123, v123
	v_exp_f32_e32 v107, v107
	v_add_f32_e32 v195, v122, v106
	v_add_f32_e32 v196, v195, v196
	v_fmamk_f32 v124, v124, 0x3e38aa3b, v194
	v_fmamk_f32 v108, v108, 0x3e38aa3b, v194
	v_exp_f32_e32 v124, v124
	v_exp_f32_e32 v108, v108
	v_add_f32_e32 v195, v123, v107
	v_add_f32_e32 v196, v195, v196
	v_fmamk_f32 v125, v125, 0x3e38aa3b, v194
	v_fmamk_f32 v109, v109, 0x3e38aa3b, v194
	v_exp_f32_e32 v125, v125
	v_exp_f32_e32 v109, v109
	v_add_f32_e32 v195, v124, v108
	v_add_f32_e32 v196, v195, v196
	v_fmamk_f32 v126, v126, 0x3e38aa3b, v194
	v_fmamk_f32 v110, v110, 0x3e38aa3b, v194
	v_exp_f32_e32 v126, v126
	v_exp_f32_e32 v110, v110
	v_add_f32_e32 v195, v125, v109
	v_add_f32_e32 v196, v195, v196
	v_fmamk_f32 v127, v127, 0x3e38aa3b, v194
	v_fmamk_f32 v111, v111, 0x3e38aa3b, v194
	v_exp_f32_e32 v127, v127
	v_exp_f32_e32 v111, v111
	v_add_f32_e32 v195, v126, v110
	v_add_f32_e32 v196, v195, v196
	v_fmamk_f32 v128, v128, 0x3e38aa3b, v194
	v_fmamk_f32 v112, v112, 0x3e38aa3b, v194
	v_exp_f32_e32 v128, v128
	v_exp_f32_e32 v112, v112
	v_add_f32_e32 v195, v127, v111
	v_add_f32_e32 v196, v195, v196
	v_fmamk_f32 v129, v129, 0x3e38aa3b, v194
	v_fmamk_f32 v113, v113, 0x3e38aa3b, v194
	v_exp_f32_e32 v129, v129
	v_exp_f32_e32 v113, v113
	v_add_f32_e32 v195, v128, v112
	v_add_f32_e32 v196, v195, v196
	v_add_f32_e32 v195, v129, v113
	v_add_f32_e32 v196, v195, v196
	v_cvt_pk_bf16_f32 v208, v114, v115
	v_cvt_pk_bf16_f32 v209, v116, v117
	v_cvt_pk_bf16_f32 v210, v118, v119
	v_cvt_pk_bf16_f32 v211, v120, v121
	v_cvt_pk_bf16_f32 v105, v104, v105
	v_cvt_pk_bf16_f32 v104, v102, v103
	v_mfma_f32_32x32x16_bf16 v[2:17], v[190:193], v[208:211], v[2:17]
	v_cvt_pk_bf16_f32 v103, v100, v101
	v_cvt_pk_bf16_f32 v102, v98, v99
	v_mfma_f32_32x32x16_bf16 v[18:33], v[174:177], v[208:211], v[18:33]
	v_cvt_pk_bf16_f32 v98, v106, v107
	v_cvt_pk_bf16_f32 v99, v108, v109
	v_cvt_pk_bf16_f32 v100, v110, v111
	v_cvt_pk_bf16_f32 v101, v112, v113
	v_cvt_pk_bf16_f32 v106, v122, v123
	v_cvt_pk_bf16_f32 v107, v124, v125
	v_cvt_pk_bf16_f32 v108, v126, v127
	v_cvt_pk_bf16_f32 v109, v128, v129
	v_add_f32_e32 v203, v196, v203
	s_nop 0
	v_mfma_f32_32x32x16_bf16 v[2:17], v[186:189], v[106:109], v[2:17]
	v_mfma_f32_32x32x16_bf16 v[18:33], v[170:173], v[106:109], v[18:33]
	v_mfma_f32_32x32x16_bf16 v[2:17], v[182:185], v[102:105], v[2:17]
	v_mfma_f32_32x32x16_bf16 v[18:33], v[166:169], v[102:105], v[18:33]
	v_mfma_f32_32x32x16_bf16 v[2:17], v[178:181], v[98:101], v[2:17]
	v_mfma_f32_32x32x16_bf16 v[18:33], v[162:165], v[98:101], v[18:33]
	s_xor_b32 s14, s14, 1
	s_add_i32 s13, s13, 64
	s_add_u32 s0, s0, 0x2000
	s_addc_u32 s1, s1, 0
	s_andn2_b64 vcc, exec, s[44:45]
	s_cbranch_vccz .LBB0_235
	v_mov_b32_e32 v242, v0
	s_branch .LBB0_412

.LBB0_643:
	s_mul_i32 s44, s43, 0x6000
	s_add_i32 s45, s44, 0xffffa000
	s_cmp_gt_i32 s43, 0
	s_waitcnt vmcnt(6)
	s_cselect_b32 s45, s45, 0xc000
	s_waitcnt lgkmcnt(0)
	s_barrier
	s_setprio 2
	v_add3_u32 v0, s44, v177, v176
	v_add_u32_e32 v0, s55, v0
	ds_read_b128 v[180:183], v0
	ds_read_b128 v[184:187], v0 offset:1024
	ds_read_b128 v[188:191], v0 offset:2048
	ds_read_b128 v[198:201], v0 offset:3072
	v_add3_u32 v0, s44, v178, v176
	ds_read_b128 v[202:205], v0 offset:8192
	ds_read_b128 v[234:237], v0 offset:9216
	ds_read_b128 v[238:241], v0 offset:10240
	ds_read_b128 v[242:245], v0 offset:11264
	ds_read_b128 v[246:249], v0 offset:12288
	ds_read_b128 v[226:229], v0 offset:13312
	ds_read_b128 v[216:219], v0 offset:14336
	ds_read_b128 v[230:233], v0 offset:15360
	v_lshl_add_u64 v[212:213], v[174:175], 0, s[12:13]
	v_lshl_add_u64 v[212:213], v[162:163], 1, v[212:213]
	s_add_i32 s68, s45, s42
	s_mov_b32 m0, s68
	s_nop 0
	global_load_lds_dwordx4 v[212:213], off
	v_lshl_add_u64 v[212:213], v[174:175], 0, s[12:13]
	v_lshl_add_u64 v[212:213], v[164:165], 1, v[212:213]
	s_add_i32 s68, s45, s40
	s_mov_b32 m0, s68
	s_nop 0
	global_load_lds_dwordx4 v[212:213], off
	s_add_i32 s45, s41, s45
	v_lshl_add_u64 v[212:213], v[172:173], 0, s[12:13]
	s_mov_b32 m0, s45
	s_nop 0
	global_load_lds_dwordx4 v[212:213], off
	v_lshl_add_u64 v[212:213], v[170:171], 0, s[12:13]
	s_add_i32 s68, s45, 0x400
	s_mov_b32 m0, s68
	s_nop 0
	global_load_lds_dwordx4 v[212:213], off
	v_lshl_add_u64 v[212:213], v[168:169], 0, s[12:13]
	s_add_i32 s68, s45, 0x800
	s_mov_b32 m0, s68
	s_nop 0
	global_load_lds_dwordx4 v[212:213], off
	s_addk_i32 s45, 0xc00
	v_lshl_add_u64 v[212:213], v[166:167], 0, s[12:13]
	s_mov_b32 m0, s45
	s_nop 0
	global_load_lds_dwordx4 v[212:213], off
	s_setprio 0
	s_waitcnt lgkmcnt(7)
	v_mfma_f32_16x16x32_bf16 v[34:37], v[202:205], v[180:183], v[34:37]
	v_mfma_f32_16x16x32_bf16 v[38:41], v[202:205], v[184:187], v[38:41]
	v_mfma_f32_16x16x32_bf16 v[42:45], v[202:205], v[188:191], v[42:45]
	v_mfma_f32_16x16x32_bf16 v[46:49], v[202:205], v[198:201], v[46:49]
	s_waitcnt lgkmcnt(6)
	v_mfma_f32_16x16x32_bf16 v[50:53], v[234:237], v[180:183], v[50:53]
	v_mfma_f32_16x16x32_bf16 v[54:57], v[234:237], v[184:187], v[54:57]
	v_mfma_f32_16x16x32_bf16 v[58:61], v[234:237], v[188:191], v[58:61]
	v_mfma_f32_16x16x32_bf16 v[62:65], v[234:237], v[198:201], v[62:65]
	s_waitcnt lgkmcnt(5)
	v_mfma_f32_16x16x32_bf16 v[66:69], v[238:241], v[180:183], v[66:69]
	v_mfma_f32_16x16x32_bf16 v[70:73], v[238:241], v[184:187], v[70:73]
	v_mfma_f32_16x16x32_bf16 v[74:77], v[238:241], v[188:191], v[74:77]
	v_mfma_f32_16x16x32_bf16 v[78:81], v[238:241], v[198:201], v[78:81]
	s_waitcnt lgkmcnt(4)
	v_mfma_f32_16x16x32_bf16 v[82:85], v[242:245], v[180:183], v[82:85]
	v_mfma_f32_16x16x32_bf16 v[86:89], v[242:245], v[184:187], v[86:89]
	v_mfma_f32_16x16x32_bf16 v[90:93], v[242:245], v[188:191], v[90:93]
	v_mfma_f32_16x16x32_bf16 v[94:97], v[242:245], v[198:201], v[94:97]
	s_waitcnt lgkmcnt(3)
	v_mfma_f32_16x16x32_bf16 v[98:101], v[246:249], v[180:183], v[98:101]
	v_mfma_f32_16x16x32_bf16 v[102:105], v[246:249], v[184:187], v[102:105]
	v_mfma_f32_16x16x32_bf16 v[106:109], v[246:249], v[188:191], v[106:109]
	v_mfma_f32_16x16x32_bf16 v[110:113], v[246:249], v[198:201], v[110:113]
	s_waitcnt lgkmcnt(2)
	v_mfma_f32_16x16x32_bf16 v[114:117], v[226:229], v[180:183], v[114:117]
	v_mfma_f32_16x16x32_bf16 v[118:121], v[226:229], v[184:187], v[118:121]
	v_mfma_f32_16x16x32_bf16 v[122:125], v[226:229], v[188:191], v[122:125]
	v_mfma_f32_16x16x32_bf16 v[126:129], v[226:229], v[198:201], v[126:129]
	s_waitcnt lgkmcnt(1)
	v_mfma_f32_16x16x32_bf16 v[130:133], v[216:219], v[180:183], v[130:133]
	v_mfma_f32_16x16x32_bf16 v[134:137], v[216:219], v[184:187], v[134:137]
	v_mfma_f32_16x16x32_bf16 v[138:141], v[216:219], v[188:191], v[138:141]
	v_mfma_f32_16x16x32_bf16 v[142:145], v[216:219], v[198:201], v[142:145]
	s_waitcnt lgkmcnt(0)
	v_mfma_f32_16x16x32_bf16 v[146:149], v[230:233], v[180:183], v[146:149]
	v_mfma_f32_16x16x32_bf16 v[150:153], v[230:233], v[184:187], v[150:153]
	v_mfma_f32_16x16x32_bf16 v[154:157], v[230:233], v[188:191], v[154:157]
	v_mfma_f32_16x16x32_bf16 v[158:161], v[230:233], v[198:201], v[158:161]
	s_add_i32 s44, s43, 1
	s_cmp_lg_u32 s43, 2
	s_cselect_b32 s43, s44, 0
	s_add_u32 s12, s12, 64
	s_addc_u32 s13, s13, 0
	s_cmpk_eq_i32 s12, 0x780
	s_cbranch_scc0 .LBB0_643
	s_waitcnt vmcnt(6)
	v_mov_b32_e32 v162, v19
	v_mov_b32_e32 v163, v20
	v_mov_b32_e32 v19, v21
	v_mov_b32_e32 v164, v3
	v_mov_b32_e32 v165, v4
	v_pk_add_f32 v[18:19], v[162:163], v[18:19]
	v_mov_b32_e32 v3, v5
	v_pk_add_f32 v[2:3], v[164:165], v[2:3]
	v_add_f32_e32 v0, v18, v19
	v_add_f32_e32 v0, v0, v2
	v_add_f32_e32 v0, v0, v3
	v_fmamk_f32 v0, v0, 0x3a800000, v250
	s_waitcnt vmcnt(4)
	v_mov_b32_e32 v166, v23
	v_mov_b32_e32 v167, v24
	v_mul_f32_e32 v2, 0x4b800000, v0
	v_cmp_gt_f32_e32 vcc, s80, v0
	v_mov_b32_e32 v23, v25
	v_mov_b32_e32 v168, v7
	v_mov_b32_e32 v169, v8
	v_cndmask_b32_e32 v0, v0, v2, vcc
	v_pk_add_f32 v[2:3], v[166:167], v[22:23]
	v_mov_b32_e32 v7, v9
	v_pk_add_f32 v[4:5], v[168:169], v[6:7]
	v_add_f32_e32 v2, v2, v3
	v_add_f32_e32 v2, v2, v4
	v_add_f32_e32 v2, v2, v5
	v_fmamk_f32 v2, v2, 0x3a800000, v250
	v_mul_f32_e32 v3, 0x4b800000, v2
	v_cmp_gt_f32_e64 s[40:41], s80, v2
	s_waitcnt vmcnt(2)
	v_mov_b32_e32 v170, v27
	v_mov_b32_e32 v171, v28
	v_cndmask_b32_e64 v2, v2, v3, s[40:41]
	v_mov_b32_e32 v27, v29
	v_mov_b32_e32 v172, v11
	v_mov_b32_e32 v173, v12
	v_rsq_f32_e32 v179, v2
	v_pk_add_f32 v[2:3], v[170:171], v[26:27]
	v_mov_b32_e32 v11, v13
	v_pk_add_f32 v[4:5], v[172:173], v[10:11]
	v_add_f32_e32 v2, v2, v3
	v_add_f32_e32 v2, v2, v4
	v_add_f32_e32 v2, v2, v5
	v_fmamk_f32 v2, v2, 0x3a800000, v250
	v_mul_f32_e32 v3, 0x4b800000, v2
	v_cmp_gt_f32_e64 s[42:43], s80, v2
	s_waitcnt vmcnt(0)
	v_mov_b32_e32 v174, v31
	v_mov_b32_e32 v175, v32
	v_cndmask_b32_e64 v2, v2, v3, s[42:43]
	v_mov_b32_e32 v31, v33
	v_mov_b32_e32 v180, v15
	v_mov_b32_e32 v181, v16
	v_rsq_f32_e32 v182, v2
	v_pk_add_f32 v[2:3], v[174:175], v[30:31]
	v_mov_b32_e32 v15, v17
	v_pk_add_f32 v[4:5], v[180:181], v[14:15]
	v_add_f32_e32 v2, v2, v3
	v_add_f32_e32 v2, v2, v4
	v_add_f32_e32 v2, v2, v5
	v_fmamk_f32 v2, v2, 0x3a800000, v250
	v_mul_f32_e32 v3, 0x4b800000, v2
	v_cmp_gt_f32_e64 s[44:45], s80, v2
	s_waitcnt vmcnt(6)
	v_add_u32_e32 v183, v178, v176
	s_waitcnt lgkmcnt(0)
	s_barrier
	v_cndmask_b32_e64 v2, v2, v3, s[44:45]
	v_rsq_f32_e32 v180, v2
	ds_read_b128 v[2:5], v183 offset:15360
	ds_read_b128 v[6:9], v183 offset:14336
	ds_read_b128 v[10:13], v183 offset:13312
	ds_read_b128 v[14:17], v183 offset:12288
	ds_read_b128 v[18:21], v183 offset:11264
	ds_read_b128 v[22:25], v183 offset:10240
	ds_read_b128 v[26:29], v183 offset:9216
	ds_read_b128 v[30:33], v183 offset:8192
	v_add3_u32 v178, s55, v177, v176
	ds_read_b128 v[162:165], v178 offset:3072
	ds_read_b128 v[166:169], v178 offset:2048
	ds_read_b128 v[170:173], v178 offset:1024
	ds_read_b128 v[174:177], v178
	v_rsq_f32_e32 v0, v0
	v_mul_f32_e32 v184, 0x45800000, v179
	v_mul_f32_e32 v185, 0x45800000, v182
	v_mul_f32_e32 v186, 0x45800000, v180
	v_mul_f32_e32 v181, 0x45800000, v0
	s_waitcnt lgkmcnt(0)
	v_mfma_f32_16x16x32_bf16 v[34:37], v[30:33], v[174:177], v[34:37]
	v_mfma_f32_16x16x32_bf16 v[38:41], v[30:33], v[170:173], v[38:41]
	v_mfma_f32_16x16x32_bf16 v[42:45], v[30:33], v[166:169], v[42:45]
	v_mfma_f32_16x16x32_bf16 v[30:33], v[30:33], v[162:165], v[46:49]
	v_mfma_f32_16x16x32_bf16 v[46:49], v[26:29], v[174:177], v[50:53]
	v_mfma_f32_16x16x32_bf16 v[50:53], v[26:29], v[170:173], v[54:57]
	v_mfma_f32_16x16x32_bf16 v[54:57], v[26:29], v[166:169], v[58:61]
	v_mfma_f32_16x16x32_bf16 v[58:61], v[26:29], v[162:165], v[62:65]
	v_mfma_f32_16x16x32_bf16 v[62:65], v[22:25], v[174:177], v[66:69]
	v_mfma_f32_16x16x32_bf16 v[66:69], v[22:25], v[170:173], v[70:73]
	v_mfma_f32_16x16x32_bf16 v[70:73], v[22:25], v[166:169], v[74:77]
	v_mfma_f32_16x16x32_bf16 v[74:77], v[22:25], v[162:165], v[78:81]
	v_mfma_f32_16x16x32_bf16 v[78:81], v[18:21], v[174:177], v[82:85]
	v_mfma_f32_16x16x32_bf16 v[82:85], v[18:21], v[170:173], v[86:89]
	v_mfma_f32_16x16x32_bf16 v[86:89], v[18:21], v[166:169], v[90:93]
	v_mfma_f32_16x16x32_bf16 v[18:21], v[18:21], v[162:165], v[94:97]
	v_mfma_f32_16x16x32_bf16 v[90:93], v[14:17], v[174:177], v[98:101]
	v_mfma_f32_16x16x32_bf16 v[94:97], v[14:17], v[170:173], v[102:105]
	v_mfma_f32_16x16x32_bf16 v[98:101], v[14:17], v[166:169], v[106:109]
	v_mfma_f32_16x16x32_bf16 v[14:17], v[14:17], v[162:165], v[110:113]
	v_mfma_f32_16x16x32_bf16 v[102:105], v[10:13], v[174:177], v[114:117]
	v_mfma_f32_16x16x32_bf16 v[106:109], v[10:13], v[170:173], v[118:121]
	v_mfma_f32_16x16x32_bf16 v[110:113], v[10:13], v[166:169], v[122:125]
	v_mfma_f32_16x16x32_bf16 v[10:13], v[10:13], v[162:165], v[126:129]
	v_mfma_f32_16x16x32_bf16 v[114:117], v[6:9], v[174:177], v[130:133]
	v_mfma_f32_16x16x32_bf16 v[118:121], v[6:9], v[170:173], v[134:137]
	v_mfma_f32_16x16x32_bf16 v[122:125], v[6:9], v[166:169], v[138:141]
	v_mfma_f32_16x16x32_bf16 v[6:9], v[6:9], v[162:165], v[142:145]
	v_mfma_f32_16x16x32_bf16 v[126:129], v[2:5], v[174:177], v[146:149]
	v_mfma_f32_16x16x32_bf16 v[130:133], v[2:5], v[170:173], v[150:153]
	v_mfma_f32_16x16x32_bf16 v[134:137], v[2:5], v[166:169], v[154:157]
	v_mfma_f32_16x16x32_bf16 v[2:5], v[2:5], v[162:165], v[158:161]
	s_waitcnt vmcnt(0)
	v_cndmask_b32_e32 v26, v0, v181, vcc
	v_cndmask_b32_e64 v24, v179, v184, s[40:41]
	v_cndmask_b32_e64 v22, v182, v185, s[42:43]
	v_cndmask_b32_e64 v0, v180, v186, s[44:45]
	s_waitcnt lgkmcnt(0)
	s_barrier
	ds_read_b128 v[138:141], v178 offset:24576
	ds_read_b128 v[142:145], v178 offset:25600
	ds_read_b128 v[146:149], v178 offset:26624
	ds_read_b128 v[150:153], v178 offset:27648
	ds_read_b128 v[154:157], v183 offset:32768
	ds_read_b128 v[158:161], v183 offset:33792
	ds_read_b128 v[162:165], v183 offset:34816
	ds_read_b128 v[166:169], v183 offset:35840
	ds_read_b128 v[170:173], v183 offset:36864
	ds_read_b128 v[174:177], v183 offset:37888
	ds_read_b128 v[178:181], v183 offset:38912
	ds_read_b128 v[182:185], v183 offset:39936
	s_waitcnt lgkmcnt(7)
	v_mfma_f32_16x16x32_bf16 v[34:37], v[154:157], v[138:141], v[34:37]
	v_mfma_f32_16x16x32_bf16 v[38:41], v[154:157], v[142:145], v[38:41]
	v_mfma_f32_16x16x32_bf16 v[42:45], v[154:157], v[146:149], v[42:45]
	v_mfma_f32_16x16x32_bf16 v[28:31], v[154:157], v[150:153], v[30:33]
	s_waitcnt lgkmcnt(6)
	v_mfma_f32_16x16x32_bf16 v[46:49], v[158:161], v[138:141], v[46:49]
	v_mfma_f32_16x16x32_bf16 v[50:53], v[158:161], v[142:145], v[50:53]
	v_mfma_f32_16x16x32_bf16 v[54:57], v[158:161], v[146:149], v[54:57]
	v_mfma_f32_16x16x32_bf16 v[58:61], v[158:161], v[150:153], v[58:61]
	s_waitcnt lgkmcnt(5)
	v_mfma_f32_16x16x32_bf16 v[62:65], v[162:165], v[138:141], v[62:65]
	v_mfma_f32_16x16x32_bf16 v[66:69], v[162:165], v[142:145], v[66:69]
	v_mfma_f32_16x16x32_bf16 v[70:73], v[162:165], v[146:149], v[70:73]
	v_mfma_f32_16x16x32_bf16 v[74:77], v[162:165], v[150:153], v[74:77]
	s_waitcnt lgkmcnt(4)
	v_mfma_f32_16x16x32_bf16 v[78:81], v[166:169], v[138:141], v[78:81]
	v_mfma_f32_16x16x32_bf16 v[82:85], v[166:169], v[142:145], v[82:85]
	v_mfma_f32_16x16x32_bf16 v[86:89], v[166:169], v[146:149], v[86:89]
	v_mfma_f32_16x16x32_bf16 v[154:157], v[166:169], v[150:153], v[18:21]
	s_waitcnt lgkmcnt(3)
	v_mfma_f32_16x16x32_bf16 v[90:93], v[170:173], v[138:141], v[90:93]
	v_mfma_f32_16x16x32_bf16 v[94:97], v[170:173], v[142:145], v[94:97]
	v_mfma_f32_16x16x32_bf16 v[98:101], v[170:173], v[146:149], v[98:101]
	v_mfma_f32_16x16x32_bf16 v[158:161], v[170:173], v[150:153], v[14:17]
	s_waitcnt lgkmcnt(2)
	v_mfma_f32_16x16x32_bf16 v[102:105], v[174:177], v[138:141], v[102:105]
	v_mfma_f32_16x16x32_bf16 v[106:109], v[174:177], v[142:145], v[106:109]
	v_mfma_f32_16x16x32_bf16 v[110:113], v[174:177], v[146:149], v[110:113]
	v_mfma_f32_16x16x32_bf16 v[162:165], v[174:177], v[150:153], v[10:13]
	s_waitcnt lgkmcnt(1)
	v_mfma_f32_16x16x32_bf16 v[114:117], v[178:181], v[138:141], v[114:117]
	v_mfma_f32_16x16x32_bf16 v[118:121], v[178:181], v[142:145], v[118:121]
	v_mfma_f32_16x16x32_bf16 v[122:125], v[178:181], v[146:149], v[122:125]
	v_mfma_f32_16x16x32_bf16 v[18:21], v[178:181], v[150:153], v[6:9]
	s_waitcnt lgkmcnt(0)
	v_mfma_f32_16x16x32_bf16 v[14:17], v[182:185], v[138:141], v[126:129]
	v_mfma_f32_16x16x32_bf16 v[10:13], v[182:185], v[142:145], v[130:133]
	v_mfma_f32_16x16x32_bf16 v[6:9], v[182:185], v[146:149], v[134:137]
	v_mfma_f32_16x16x32_bf16 v[2:5], v[182:185], v[150:153], v[2:5]
	v_mov_b32_e32 v23, v224
	s_movk_i32 s12, 0x210
	v_lshrrev_b32_e32 v32, 1, v23
	v_and_b32_e32 v27, 0x7fffff80, v23
	v_and_b32_e32 v32, 24, v32
	v_and_b32_e32 v25, 0x4f, v23
	v_lshl_or_b32 v27, v27, 1, v32
	v_pk_mul_f32 v[32:33], v[26:27], v[34:35] op_sel_hi:[0,1]
	v_pk_mul_f32 v[34:35], v[26:27], v[36:37] op_sel_hi:[0,1]
	v_mad_u32_u24 v25, v25, s12, v27
	v_cvt_pk_bf16_f32 v32, v32, v33
	v_cvt_pk_bf16_f32 v33, v34, v35
	v_pk_mul_f32 v[34:35], v[24:25], v[38:39] op_sel_hi:[0,1]
	v_pk_mul_f32 v[36:37], v[24:25], v[40:41] op_sel_hi:[0,1]
	v_cvt_pk_bf16_f32 v34, v34, v35
	v_cvt_pk_bf16_f32 v35, v36, v37
	v_pk_mul_f32 v[36:37], v[22:23], v[42:43] op_sel_hi:[0,1]
	v_pk_mul_f32 v[38:39], v[22:23], v[44:45] op_sel_hi:[0,1]
	v_pk_mul_f32 v[28:29], v[0:1], v[28:29] op_sel_hi:[0,1]
	v_pk_mul_f32 v[30:31], v[0:1], v[30:31] op_sel_hi:[0,1]
	v_cvt_pk_bf16_f32 v36, v36, v37
	v_cvt_pk_bf16_f32 v37, v38, v39
	v_cvt_pk_bf16_f32 v28, v28, v29
	v_cvt_pk_bf16_f32 v29, v30, v31
	v_pk_mul_f32 v[30:31], v[26:27], v[46:47] op_sel_hi:[0,1]
	v_pk_mul_f32 v[38:39], v[26:27], v[48:49] op_sel_hi:[0,1]
	v_cvt_pk_bf16_f32 v30, v30, v31
	v_cvt_pk_bf16_f32 v31, v38, v39
	s_barrier
	ds_write2_b64 v25, v[32:33], v[30:31] offset1:4
	v_pk_mul_f32 v[30:31], v[24:25], v[50:51] op_sel_hi:[0,1]
	v_pk_mul_f32 v[32:33], v[24:25], v[52:53] op_sel_hi:[0,1]
	v_cvt_pk_bf16_f32 v30, v30, v31
	v_cvt_pk_bf16_f32 v31, v32, v33
	v_add_u32_e32 v27, 0x2000, v25
	ds_write2_b64 v27, v[34:35], v[30:31] offset0:32 offset1:36
	v_pk_mul_f32 v[30:31], v[22:23], v[54:55] op_sel_hi:[0,1]
	v_pk_mul_f32 v[32:33], v[22:23], v[56:57] op_sel_hi:[0,1]
	v_cvt_pk_bf16_f32 v30, v30, v31
	v_cvt_pk_bf16_f32 v31, v32, v33
	v_add_u32_e32 v40, 0x4000, v25
	ds_write2_b64 v40, v[36:37], v[30:31] offset0:64 offset1:68
	v_pk_mul_f32 v[30:31], v[0:1], v[58:59] op_sel_hi:[0,1]
	v_pk_mul_f32 v[32:33], v[0:1], v[60:61] op_sel_hi:[0,1]
	v_cvt_pk_bf16_f32 v30, v30, v31
	v_cvt_pk_bf16_f32 v31, v32, v33
	v_add_u32_e32 v41, 0x6000, v25
	ds_write2_b64 v41, v[28:29], v[30:31] offset0:96 offset1:100
	v_pk_mul_f32 v[28:29], v[26:27], v[62:63] op_sel_hi:[0,1]
	v_pk_mul_f32 v[30:31], v[26:27], v[64:65] op_sel_hi:[0,1]
	v_cvt_pk_bf16_f32 v28, v28, v29
	v_cvt_pk_bf16_f32 v29, v30, v31
	v_pk_mul_f32 v[30:31], v[24:25], v[66:67] op_sel_hi:[0,1]
	v_pk_mul_f32 v[32:33], v[24:25], v[68:69] op_sel_hi:[0,1]
	v_cvt_pk_bf16_f32 v30, v30, v31
	v_cvt_pk_bf16_f32 v31, v32, v33
	v_pk_mul_f32 v[32:33], v[22:23], v[70:71] op_sel_hi:[0,1]
	v_pk_mul_f32 v[34:35], v[22:23], v[72:73] op_sel_hi:[0,1]
	v_cvt_pk_bf16_f32 v32, v32, v33
	v_cvt_pk_bf16_f32 v33, v34, v35
	v_pk_mul_f32 v[34:35], v[0:1], v[74:75] op_sel_hi:[0,1]
	v_pk_mul_f32 v[36:37], v[0:1], v[76:77] op_sel_hi:[0,1]
	v_cvt_pk_bf16_f32 v34, v34, v35
	v_cvt_pk_bf16_f32 v35, v36, v37
	v_pk_mul_f32 v[36:37], v[26:27], v[78:79] op_sel_hi:[0,1]
	v_pk_mul_f32 v[38:39], v[26:27], v[80:81] op_sel_hi:[0,1]
	v_cvt_pk_bf16_f32 v36, v36, v37
	v_cvt_pk_bf16_f32 v37, v38, v39
	ds_write2_b64 v25, v[28:29], v[36:37] offset0:8 offset1:12
	v_pk_mul_f32 v[28:29], v[24:25], v[82:83] op_sel_hi:[0,1]
	v_pk_mul_f32 v[36:37], v[24:25], v[84:85] op_sel_hi:[0,1]
	v_cvt_pk_bf16_f32 v28, v28, v29
	v_cvt_pk_bf16_f32 v29, v36, v37
	ds_write2_b64 v27, v[30:31], v[28:29] offset0:40 offset1:44
	v_pk_mul_f32 v[28:29], v[22:23], v[86:87] op_sel_hi:[0,1]
	v_pk_mul_f32 v[30:31], v[22:23], v[88:89] op_sel_hi:[0,1]
	v_cvt_pk_bf16_f32 v28, v28, v29
	v_cvt_pk_bf16_f32 v29, v30, v31
	ds_write2_b64 v40, v[32:33], v[28:29] offset0:72 offset1:76
	v_pk_mul_f32 v[28:29], v[0:1], v[154:155] op_sel_hi:[0,1]
	v_pk_mul_f32 v[30:31], v[0:1], v[156:157] op_sel_hi:[0,1]
	v_cvt_pk_bf16_f32 v28, v28, v29
	v_cvt_pk_bf16_f32 v29, v30, v31
	ds_write2_b64 v41, v[34:35], v[28:29] offset0:104 offset1:108
	v_pk_mul_f32 v[28:29], v[26:27], v[90:91] op_sel_hi:[0,1]
	v_pk_mul_f32 v[30:31], v[26:27], v[92:93] op_sel_hi:[0,1]
	v_cvt_pk_bf16_f32 v28, v28, v29
	v_cvt_pk_bf16_f32 v29, v30, v31
	v_pk_mul_f32 v[30:31], v[24:25], v[94:95] op_sel_hi:[0,1]
	v_pk_mul_f32 v[32:33], v[24:25], v[96:97] op_sel_hi:[0,1]
	v_cvt_pk_bf16_f32 v30, v30, v31
	v_cvt_pk_bf16_f32 v31, v32, v33
	v_pk_mul_f32 v[32:33], v[22:23], v[98:99] op_sel_hi:[0,1]
	v_pk_mul_f32 v[34:35], v[22:23], v[100:101] op_sel_hi:[0,1]
	v_cvt_pk_bf16_f32 v32, v32, v33
	v_cvt_pk_bf16_f32 v33, v34, v35
	v_pk_mul_f32 v[34:35], v[0:1], v[158:159] op_sel_hi:[0,1]
	v_pk_mul_f32 v[36:37], v[0:1], v[160:161] op_sel_hi:[0,1]
	v_cvt_pk_bf16_f32 v34, v34, v35
	v_cvt_pk_bf16_f32 v35, v36, v37
	v_pk_mul_f32 v[36:37], v[26:27], v[102:103] op_sel_hi:[0,1]
	v_pk_mul_f32 v[38:39], v[26:27], v[104:105] op_sel_hi:[0,1]
	v_cvt_pk_bf16_f32 v36, v36, v37
	v_cvt_pk_bf16_f32 v37, v38, v39
	ds_write2_b64 v25, v[28:29], v[36:37] offset0:16 offset1:20
	v_pk_mul_f32 v[28:29], v[24:25], v[106:107] op_sel_hi:[0,1]
	v_pk_mul_f32 v[36:37], v[24:25], v[108:109] op_sel_hi:[0,1]
	v_cvt_pk_bf16_f32 v28, v28, v29
	v_cvt_pk_bf16_f32 v29, v36, v37
	ds_write2_b64 v27, v[30:31], v[28:29] offset0:48 offset1:52
	v_pk_mul_f32 v[28:29], v[22:23], v[110:111] op_sel_hi:[0,1]
	v_pk_mul_f32 v[30:31], v[22:23], v[112:113] op_sel_hi:[0,1]
	v_cvt_pk_bf16_f32 v28, v28, v29
	v_cvt_pk_bf16_f32 v29, v30, v31
	ds_write2_b64 v40, v[32:33], v[28:29] offset0:80 offset1:84
	v_pk_mul_f32 v[28:29], v[0:1], v[162:163] op_sel_hi:[0,1]
	v_pk_mul_f32 v[30:31], v[0:1], v[164:165] op_sel_hi:[0,1]
	v_cvt_pk_bf16_f32 v28, v28, v29
	v_cvt_pk_bf16_f32 v29, v30, v31
	ds_write2_b64 v41, v[34:35], v[28:29] offset0:112 offset1:116
	v_pk_mul_f32 v[28:29], v[26:27], v[114:115] op_sel_hi:[0,1]
	v_pk_mul_f32 v[30:31], v[26:27], v[116:117] op_sel_hi:[0,1]
	v_pk_mul_f32 v[18:19], v[0:1], v[18:19] op_sel_hi:[0,1]
	v_pk_mul_f32 v[20:21], v[0:1], v[20:21] op_sel_hi:[0,1]
	v_pk_mul_f32 v[2:3], v[0:1], v[2:3] op_sel_hi:[0,1]
	v_pk_mul_f32 v[4:5], v[0:1], v[4:5] op_sel_hi:[0,1]
	v_lshlrev_b32_e32 v0, 3, v23
	v_cvt_pk_bf16_f32 v28, v28, v29
	v_cvt_pk_bf16_f32 v29, v30, v31
	v_pk_mul_f32 v[30:31], v[24:25], v[118:119] op_sel_hi:[0,1]
	v_pk_mul_f32 v[32:33], v[24:25], v[120:121] op_sel_hi:[0,1]
	v_cvt_pk_bf16_f32 v18, v18, v19
	v_cvt_pk_bf16_f32 v19, v20, v21
	v_cvt_pk_bf16_f32 v2, v2, v3
	v_cvt_pk_bf16_f32 v3, v4, v5
	v_and_b32_e32 v0, 0xf8, v0
	v_cvt_pk_bf16_f32 v30, v30, v31
	v_cvt_pk_bf16_f32 v31, v32, v33
	v_pk_mul_f32 v[32:33], v[22:23], v[122:123] op_sel_hi:[0,1]
	v_pk_mul_f32 v[34:35], v[22:23], v[124:125] op_sel_hi:[0,1]
	v_pk_mul_f32 v[14:15], v[26:27], v[14:15] op_sel_hi:[0,1]
	v_pk_mul_f32 v[16:17], v[26:27], v[16:17] op_sel_hi:[0,1]
	v_pk_mul_f32 v[10:11], v[24:25], v[10:11] op_sel_hi:[0,1]
	v_pk_mul_f32 v[12:13], v[24:25], v[12:13] op_sel_hi:[0,1]
	v_pk_mul_f32 v[6:7], v[22:23], v[6:7] op_sel_hi:[0,1]
	v_pk_mul_f32 v[8:9], v[22:23], v[8:9] op_sel_hi:[0,1]
	ds_write2_b64 v41, v[18:19], v[2:3] offset0:120 offset1:124
	v_or_b32_e32 v2, s54, v0
	s_movk_i32 s12, 0xa30
	v_cvt_pk_bf16_f32 v32, v32, v33
	v_cvt_pk_bf16_f32 v33, v34, v35
	v_cvt_pk_bf16_f32 v14, v14, v15
	v_cvt_pk_bf16_f32 v15, v16, v17
	v_cvt_pk_bf16_f32 v10, v10, v11
	v_cvt_pk_bf16_f32 v11, v12, v13
	v_cvt_pk_bf16_f32 v6, v6, v7
	v_cvt_pk_bf16_f32 v7, v8, v9
	v_cmp_gt_i32_e32 vcc, s12, v2
	ds_write2_b64 v25, v[28:29], v[14:15] offset0:24 offset1:28
	ds_write2_b64 v27, v[30:31], v[10:11] offset0:56 offset1:60
	ds_write2_b64 v40, v[32:33], v[6:7] offset0:88 offset1:92
	s_waitcnt lgkmcnt(0)
	s_barrier
	s_and_saveexec_b64 s[12:13], vcc
	s_cbranch_execz .LBB0_641
	v_ashrrev_i32_e32 v8, 5, v23
	v_lshlrev_b32_e32 v0, 1, v0
	s_movk_i32 s40, 0x210
	v_mad_u64_u32 v[6:7], s[40:41], v8, s40, v[0:1]
	ds_read_b128 v[2:5], v6
	v_add_u32_e32 v7, s57, v8
	v_mov_b64_e32 v[8:9], s[4:5]
	s_ashr_i32 s55, s54, 31
	v_mad_i64_i32 v[10:11], s[40:41], v7, s16, v[8:9]
	s_lshl_b64 s[40:41], s[54:55], 1
	s_nop 0
	v_lshl_add_u64 v[10:11], v[10:11], 0, s[40:41]
	v_lshl_add_u64 v[10:11], v[10:11], 0, v[0:1]
	s_waitcnt lgkmcnt(0)
	global_store_dwordx4 v[10:11], v[2:5], off
	ds_read_b128 v[2:5], v6 offset:4224
	v_add_u32_e32 v10, 8, v7
	v_mad_i64_i32 v[10:11], s[42:43], v10, s16, v[8:9]
	v_lshl_add_u64 v[10:11], v[10:11], 0, s[40:41]
	v_lshl_add_u64 v[10:11], v[10:11], 0, v[0:1]
	s_waitcnt lgkmcnt(0)
	global_store_dwordx4 v[10:11], v[2:5], off
	ds_read_b128 v[2:5], v6 offset:8448
	v_add_u32_e32 v10, 16, v7
	v_mad_i64_i32 v[10:11], s[42:43], v10, s16, v[8:9]
	v_lshl_add_u64 v[10:11], v[10:11], 0, s[40:41]
	v_lshl_add_u64 v[10:11], v[10:11], 0, v[0:1]
	s_waitcnt lgkmcnt(0)
	global_store_dwordx4 v[10:11], v[2:5], off
	ds_read_b128 v[2:5], v6 offset:12672
	v_add_u32_e32 v10, 24, v7
	v_mad_i64_i32 v[10:11], s[42:43], v10, s16, v[8:9]
	v_lshl_add_u64 v[10:11], v[10:11], 0, s[40:41]
	v_lshl_add_u64 v[10:11], v[10:11], 0, v[0:1]
	s_waitcnt lgkmcnt(0)
	global_store_dwordx4 v[10:11], v[2:5], off
	ds_read_b128 v[2:5], v6 offset:16896
	v_add_u32_e32 v10, 32, v7
	v_mad_i64_i32 v[10:11], s[42:43], v10, s16, v[8:9]
	v_lshl_add_u64 v[10:11], v[10:11], 0, s[40:41]
	v_lshl_add_u64 v[10:11], v[10:11], 0, v[0:1]
	s_waitcnt lgkmcnt(0)
	global_store_dwordx4 v[10:11], v[2:5], off
	ds_read_b128 v[2:5], v6 offset:21120
	v_add_u32_e32 v10, 40, v7
	v_mad_i64_i32 v[10:11], s[42:43], v10, s16, v[8:9]
	v_lshl_add_u64 v[10:11], v[10:11], 0, s[40:41]
	v_lshl_add_u64 v[10:11], v[10:11], 0, v[0:1]
	s_waitcnt lgkmcnt(0)
	global_store_dwordx4 v[10:11], v[2:5], off
	ds_read_b128 v[2:5], v6 offset:25344
	v_add_u32_e32 v10, 48, v7
	v_mad_i64_i32 v[10:11], s[42:43], v10, s16, v[8:9]
	v_lshl_add_u64 v[10:11], v[10:11], 0, s[40:41]
	v_lshl_add_u64 v[10:11], v[10:11], 0, v[0:1]
	s_waitcnt lgkmcnt(0)
	global_store_dwordx4 v[10:11], v[2:5], off
	ds_read_b128 v[2:5], v6 offset:29568
	v_add_u32_e32 v10, 56, v7
	v_mad_i64_i32 v[10:11], s[42:43], v10, s16, v[8:9]
	v_lshl_add_u64 v[10:11], v[10:11], 0, s[40:41]
	v_lshl_add_u64 v[10:11], v[10:11], 0, v[0:1]
	s_waitcnt lgkmcnt(0)
	global_store_dwordx4 v[10:11], v[2:5], off
	ds_read_b128 v[2:5], v6 offset:33792
	v_add_u32_e32 v10, 64, v7
	v_mad_i64_i32 v[10:11], s[42:43], v10, s16, v[8:9]
	v_lshl_add_u64 v[10:11], v[10:11], 0, s[40:41]
	v_lshl_add_u64 v[10:11], v[10:11], 0, v[0:1]
	s_waitcnt lgkmcnt(0)
	global_store_dwordx4 v[10:11], v[2:5], off
	ds_read_b128 v[2:5], v6 offset:38016
	v_add_u32_e32 v10, 0x48, v7
	v_mad_i64_i32 v[10:11], s[42:43], v10, s16, v[8:9]
	v_lshl_add_u64 v[10:11], v[10:11], 0, s[40:41]
	v_lshl_add_u64 v[10:11], v[10:11], 0, v[0:1]
	s_waitcnt lgkmcnt(0)
	global_store_dwordx4 v[10:11], v[2:5], off
	ds_read_b128 v[2:5], v6 offset:42240
	v_add_u32_e32 v10, 0x50, v7
	v_mad_i64_i32 v[10:11], s[42:43], v10, s16, v[8:9]
	v_lshl_add_u64 v[10:11], v[10:11], 0, s[40:41]
	v_lshl_add_u64 v[10:11], v[10:11], 0, v[0:1]
	s_waitcnt lgkmcnt(0)
	global_store_dwordx4 v[10:11], v[2:5], off
	ds_read_b128 v[2:5], v6 offset:46464
	v_add_u32_e32 v10, 0x58, v7
	v_mad_i64_i32 v[10:11], s[42:43], v10, s16, v[8:9]
	v_lshl_add_u64 v[10:11], v[10:11], 0, s[40:41]
	v_lshl_add_u64 v[10:11], v[10:11], 0, v[0:1]
	s_waitcnt lgkmcnt(0)
	global_store_dwordx4 v[10:11], v[2:5], off
	ds_read_b128 v[2:5], v6 offset:50688
	v_add_u32_e32 v10, 0x60, v7
	v_mad_i64_i32 v[10:11], s[42:43], v10, s16, v[8:9]
	v_lshl_add_u64 v[10:11], v[10:11], 0, s[40:41]
	v_lshl_add_u64 v[10:11], v[10:11], 0, v[0:1]
	s_waitcnt lgkmcnt(0)
	global_store_dwordx4 v[10:11], v[2:5], off
	ds_read_b128 v[2:5], v6 offset:54912
	v_add_u32_e32 v10, 0x68, v7
	v_mad_i64_i32 v[10:11], s[42:43], v10, s16, v[8:9]
	v_lshl_add_u64 v[10:11], v[10:11], 0, s[40:41]
	v_lshl_add_u64 v[10:11], v[10:11], 0, v[0:1]
	s_waitcnt lgkmcnt(0)
	global_store_dwordx4 v[10:11], v[2:5], off
	ds_read_b128 v[2:5], v6 offset:59136
	v_add_u32_e32 v10, 0x70, v7
	v_mad_i64_i32 v[10:11], s[42:43], v10, s16, v[8:9]
	v_lshl_add_u64 v[10:11], v[10:11], 0, s[40:41]
	v_lshl_add_u64 v[10:11], v[10:11], 0, v[0:1]
	s_waitcnt lgkmcnt(0)
	global_store_dwordx4 v[10:11], v[2:5], off
	ds_read_b128 v[2:5], v6 offset:63360
	v_add_u32_e32 v6, 0x78, v7
	v_mad_i64_i32 v[6:7], s[42:43], v6, s16, v[8:9]
	v_lshl_add_u64 v[6:7], v[6:7], 0, s[40:41]
	v_lshl_add_u64 v[6:7], v[6:7], 0, v[0:1]
	s_waitcnt lgkmcnt(0)
	global_store_dwordx4 v[6:7], v[2:5], off
	s_branch .LBB0_641
